# pool block head: LDS ring prologue issued at block start (own base register), accumulators cleared with v_mov_b64
# baseline (speedup 1.0000x reference)
.LBB0_332:
	s_or_b64 exec, exec, s[6:7]
	s_waitcnt lgkmcnt(0)
	global_load_dwordx4 v[82:85], v[144:145], off offset:512
	global_load_dwordx4 v[86:89], v[146:147], off offset:512
	global_load_dwordx4 v[90:93], v[148:149], off offset:512
	global_load_dwordx4 v[94:97], v[150:151], off offset:512
	global_load_dwordx4 v[112:115], v[144:145], off offset:1024
	global_load_dwordx4 v[116:119], v[146:147], off offset:1024
	global_load_dwordx4 v[122:125], v[148:149], off offset:1024
	global_load_dwordx4 v[126:129], v[150:151], off offset:1024
	v_lshl_add_u32 v246, v197, 1, v214
	ds_read_b128 v[222:225], v246 offset:4080
	ds_read_b128 v[226:229], v246 offset:3808
	ds_read_b128 v[230:233], v246 offset:3536
	ds_read_b128 v[234:237], v246 offset:3264
	ds_read_b128 v[238:241], v246 offset:2992
	ds_read_b128 v[242:245], v246 offset:2720
	ds_read_b128 v[248:251], v246 offset:2448
	ds_read_b128 v[252:255], v246 offset:2176
	v_or_b32_e32 v2, s28, v1
	v_min_u32_e32 v3, 15, v2
	v_add_u32_e32 v3, 1, v3
	v_cvt_f32_ubyte0_e32 v3, v3
	v_div_scale_f32 v4, s[6:7], v3, v3, 1.0
	v_rcp_f32_e32 v5, v4
	s_ashr_i32 s8, s30, 6
	s_mul_i32 s10, s8, 15
	v_cmp_lt_u32_e64 s[6:7], s41, v2
	v_fma_f32 v6, -v4, v5, 1.0
	v_fmac_f32_e32 v5, v6, v5
	v_div_scale_f32 v6, vcc, 1.0, v3, 1.0
	v_mul_f32_e32 v7, v6, v5
	v_fma_f32 v8, -v4, v7, v6
	v_fmac_f32_e32 v7, v8, v5
	v_fma_f32 v4, -v4, v7, v6
	v_div_fmas_f32 v4, v4, v5, v7
	v_div_fixup_f32 v159, v4, v3, 1.0
	s_ashr_i32 s11, s10, 31
	v_add_u32_e32 v2, 0xfffff80f, v2
	v_mov_b32_e32 v3, v155
	v_lshl_add_u64 v[2:3], v[2:3], 0, s[10:11]
	v_lshlrev_b64 v[2:3], 11, v[2:3]
	v_lshl_add_u64 v[2:3], s[70:71], 0, v[2:3]
	v_mov_b32_e32 v163, v155
	v_lshl_add_u64 v[2:3], v[2:3], 0, v[162:163]
	v_lshl_add_u64 v[192:193], v[2:3], 0, s[16:17]
	v_mov_b64_e32 v[2:3], 0
	v_mov_b64_e32 v[4:5], 0
	v_mov_b64_e32 v[6:7], 0
	v_mov_b64_e32 v[8:9], 0
	v_mov_b64_e32 v[10:11], 0
	v_mov_b64_e32 v[12:13], 0
	v_mov_b64_e32 v[14:15], 0
	v_mov_b64_e32 v[16:17], 0
	v_mov_b64_e32 v[18:19], 0
	v_mov_b64_e32 v[20:21], 0
	v_mov_b64_e32 v[22:23], 0
	v_mov_b64_e32 v[24:25], 0
	v_mov_b64_e32 v[26:27], 0
	v_mov_b64_e32 v[28:29], 0
	v_mov_b64_e32 v[30:31], 0
	v_mov_b64_e32 v[32:33], 0
	v_mov_b64_e32 v[34:35], 0
	v_mov_b64_e32 v[36:37], 0
	v_mov_b64_e32 v[38:39], 0
	v_mov_b64_e32 v[40:41], 0
	v_mov_b64_e32 v[42:43], 0
	v_mov_b64_e32 v[44:45], 0
	v_mov_b64_e32 v[46:47], 0
	v_mov_b64_e32 v[48:49], 0
	v_mov_b64_e32 v[50:51], 0
	v_mov_b64_e32 v[52:53], 0
	v_mov_b64_e32 v[54:55], 0
	v_mov_b64_e32 v[56:57], 0
	v_mov_b64_e32 v[58:59], 0
	v_mov_b64_e32 v[60:61], 0
	v_mov_b64_e32 v[62:63], 0
	v_mov_b64_e32 v[64:65], 0
	s_mov_b32 s49, 0
	s_mov_b64 s[10:11], 0
	s_waitcnt lgkmcnt(7)
	v_lshlrev_b32_e32 v98, 16, v222
	v_and_b32_e32 v99, 0xffff0000, v222
	v_lshlrev_b32_e32 v100, 16, v223
	v_and_b32_e32 v101, 0xffff0000, v223
	v_lshlrev_b32_e32 v102, 16, v224
	v_and_b32_e32 v103, 0xffff0000, v224
	v_lshlrev_b32_e32 v104, 16, v225
	v_and_b32_e32 v105, 0xffff0000, v225
	ds_read_b128 v[222:225], v246 offset:1904
	s_waitcnt lgkmcnt(7)
	v_lshlrev_b32_e32 v216, 16, v226
	v_and_b32_e32 v217, 0xffff0000, v226
	v_lshlrev_b32_e32 v226, 16, v227
	v_and_b32_e32 v227, 0xffff0000, v227
	v_pk_add_f32 v[106:107], v[98:99], v[216:217]
	v_pk_add_f32 v[108:109], v[100:101], v[226:227]
	v_lshlrev_b32_e32 v216, 16, v228
	v_and_b32_e32 v217, 0xffff0000, v228
	v_lshlrev_b32_e32 v228, 16, v229
	v_and_b32_e32 v229, 0xffff0000, v229
	v_pk_add_f32 v[218:219], v[102:103], v[216:217]
	v_pk_add_f32 v[220:221], v[104:105], v[228:229]
	ds_read_b128 v[226:229], v246 offset:1632
	s_waitcnt lgkmcnt(7)
	v_lshlrev_b32_e32 v216, 16, v230
	v_and_b32_e32 v217, 0xffff0000, v230
	v_lshlrev_b32_e32 v230, 16, v231
	v_and_b32_e32 v231, 0xffff0000, v231
	v_pk_add_f32 v[106:107], v[106:107], v[216:217]
	v_pk_add_f32 v[108:109], v[108:109], v[230:231]
	v_lshlrev_b32_e32 v216, 16, v232
	v_and_b32_e32 v217, 0xffff0000, v232
	v_lshlrev_b32_e32 v232, 16, v233
	v_and_b32_e32 v233, 0xffff0000, v233
	v_pk_add_f32 v[218:219], v[218:219], v[216:217]
	v_pk_add_f32 v[220:221], v[220:221], v[232:233]
	ds_read_b128 v[230:233], v246 offset:1360
	s_waitcnt lgkmcnt(7)
	v_lshlrev_b32_e32 v216, 16, v234
	v_and_b32_e32 v217, 0xffff0000, v234
	v_lshlrev_b32_e32 v234, 16, v235
	v_and_b32_e32 v235, 0xffff0000, v235
	v_pk_add_f32 v[106:107], v[106:107], v[216:217]
	v_pk_add_f32 v[108:109], v[108:109], v[234:235]
	v_lshlrev_b32_e32 v216, 16, v236
	v_and_b32_e32 v217, 0xffff0000, v236
	v_lshlrev_b32_e32 v236, 16, v237
	v_and_b32_e32 v237, 0xffff0000, v237
	v_pk_add_f32 v[218:219], v[218:219], v[216:217]
	v_pk_add_f32 v[220:221], v[220:221], v[236:237]
	ds_read_b128 v[234:237], v246 offset:1088
	s_waitcnt lgkmcnt(7)
	v_lshlrev_b32_e32 v216, 16, v238
	v_and_b32_e32 v217, 0xffff0000, v238
	v_lshlrev_b32_e32 v238, 16, v239
	v_and_b32_e32 v239, 0xffff0000, v239
	v_pk_add_f32 v[106:107], v[106:107], v[216:217]
	v_pk_add_f32 v[108:109], v[108:109], v[238:239]
	v_lshlrev_b32_e32 v216, 16, v240
	v_and_b32_e32 v217, 0xffff0000, v240
	v_lshlrev_b32_e32 v240, 16, v241
	v_and_b32_e32 v241, 0xffff0000, v241
	v_pk_add_f32 v[218:219], v[218:219], v[216:217]
	v_pk_add_f32 v[220:221], v[220:221], v[240:241]
	ds_read_b128 v[238:241], v246 offset:816
	s_waitcnt lgkmcnt(7)
	v_lshlrev_b32_e32 v216, 16, v242
	v_and_b32_e32 v217, 0xffff0000, v242
	v_lshlrev_b32_e32 v242, 16, v243
	v_and_b32_e32 v243, 0xffff0000, v243
	v_pk_add_f32 v[106:107], v[106:107], v[216:217]
	v_pk_add_f32 v[108:109], v[108:109], v[242:243]
	v_lshlrev_b32_e32 v216, 16, v244
	v_and_b32_e32 v217, 0xffff0000, v244
	v_lshlrev_b32_e32 v244, 16, v245
	v_and_b32_e32 v245, 0xffff0000, v245
	v_pk_add_f32 v[218:219], v[218:219], v[216:217]
	v_pk_add_f32 v[220:221], v[220:221], v[244:245]
	ds_read_b128 v[242:245], v246 offset:544
	s_waitcnt lgkmcnt(7)
	v_lshlrev_b32_e32 v216, 16, v248
	v_and_b32_e32 v217, 0xffff0000, v248
	v_lshlrev_b32_e32 v248, 16, v249
	v_and_b32_e32 v249, 0xffff0000, v249
	v_pk_add_f32 v[106:107], v[106:107], v[216:217]
	v_pk_add_f32 v[108:109], v[108:109], v[248:249]
	v_lshlrev_b32_e32 v216, 16, v250
	v_and_b32_e32 v217, 0xffff0000, v250
	v_lshlrev_b32_e32 v250, 16, v251
	v_and_b32_e32 v251, 0xffff0000, v251
	v_pk_add_f32 v[218:219], v[218:219], v[216:217]
	v_pk_add_f32 v[220:221], v[220:221], v[250:251]
	ds_read_b128 v[248:251], v246 offset:272
	s_waitcnt lgkmcnt(7)
	v_lshlrev_b32_e32 v216, 16, v252
	v_and_b32_e32 v217, 0xffff0000, v252
	v_lshlrev_b32_e32 v252, 16, v253
	v_and_b32_e32 v253, 0xffff0000, v253
	v_pk_add_f32 v[106:107], v[106:107], v[216:217]
	v_pk_add_f32 v[108:109], v[108:109], v[252:253]
	v_lshlrev_b32_e32 v216, 16, v254
	v_and_b32_e32 v217, 0xffff0000, v254
	v_lshlrev_b32_e32 v254, 16, v255
	v_and_b32_e32 v255, 0xffff0000, v255
	v_pk_add_f32 v[218:219], v[218:219], v[216:217]
	v_pk_add_f32 v[220:221], v[220:221], v[254:255]
	ds_read_b128 v[252:255], v246 offset:0
	s_waitcnt lgkmcnt(7)
	v_lshlrev_b32_e32 v216, 16, v222
	v_and_b32_e32 v217, 0xffff0000, v222
	v_lshlrev_b32_e32 v222, 16, v223
	v_and_b32_e32 v223, 0xffff0000, v223
	v_pk_add_f32 v[106:107], v[106:107], v[216:217]
	v_pk_add_f32 v[108:109], v[108:109], v[222:223]
	v_lshlrev_b32_e32 v216, 16, v224
	v_and_b32_e32 v217, 0xffff0000, v224
	v_lshlrev_b32_e32 v224, 16, v225
	v_and_b32_e32 v225, 0xffff0000, v225
	v_pk_add_f32 v[218:219], v[218:219], v[216:217]
	v_pk_add_f32 v[220:221], v[220:221], v[224:225]
	ds_read_b128 v[222:225], v246 offset:4112
	s_waitcnt lgkmcnt(7)
	v_lshlrev_b32_e32 v216, 16, v226
	v_and_b32_e32 v217, 0xffff0000, v226
	v_lshlrev_b32_e32 v226, 16, v227
	v_and_b32_e32 v227, 0xffff0000, v227
	v_pk_add_f32 v[106:107], v[106:107], v[216:217]
	v_pk_add_f32 v[108:109], v[108:109], v[226:227]
	v_lshlrev_b32_e32 v216, 16, v228
	v_and_b32_e32 v217, 0xffff0000, v228
	v_lshlrev_b32_e32 v228, 16, v229
	v_and_b32_e32 v229, 0xffff0000, v229
	v_pk_add_f32 v[218:219], v[218:219], v[216:217]
	v_pk_add_f32 v[220:221], v[220:221], v[228:229]
	ds_read_b128 v[226:229], v246 offset:3840
	s_waitcnt lgkmcnt(7)
	v_lshlrev_b32_e32 v216, 16, v230
	v_and_b32_e32 v217, 0xffff0000, v230
	v_lshlrev_b32_e32 v230, 16, v231
	v_and_b32_e32 v231, 0xffff0000, v231
	v_pk_add_f32 v[106:107], v[106:107], v[216:217]
	v_pk_add_f32 v[108:109], v[108:109], v[230:231]
	v_lshlrev_b32_e32 v216, 16, v232
	v_and_b32_e32 v217, 0xffff0000, v232
	v_lshlrev_b32_e32 v232, 16, v233
	v_and_b32_e32 v233, 0xffff0000, v233
	v_pk_add_f32 v[218:219], v[218:219], v[216:217]
	v_pk_add_f32 v[220:221], v[220:221], v[232:233]
	ds_read_b128 v[230:233], v246 offset:3568
	s_waitcnt lgkmcnt(7)
	v_lshlrev_b32_e32 v216, 16, v234
	v_and_b32_e32 v217, 0xffff0000, v234
	v_lshlrev_b32_e32 v234, 16, v235
	v_and_b32_e32 v235, 0xffff0000, v235
	v_pk_add_f32 v[106:107], v[106:107], v[216:217]
	v_pk_add_f32 v[108:109], v[108:109], v[234:235]
	v_lshlrev_b32_e32 v216, 16, v236
	v_and_b32_e32 v217, 0xffff0000, v236
	v_lshlrev_b32_e32 v236, 16, v237
	v_and_b32_e32 v237, 0xffff0000, v237
	v_pk_add_f32 v[218:219], v[218:219], v[216:217]
	v_pk_add_f32 v[220:221], v[220:221], v[236:237]
	ds_read_b128 v[234:237], v246 offset:3296
	s_waitcnt lgkmcnt(7)
	v_lshlrev_b32_e32 v216, 16, v238
	v_and_b32_e32 v217, 0xffff0000, v238
	v_lshlrev_b32_e32 v238, 16, v239
	v_and_b32_e32 v239, 0xffff0000, v239
	v_pk_add_f32 v[106:107], v[106:107], v[216:217]
	v_pk_add_f32 v[108:109], v[108:109], v[238:239]
	v_lshlrev_b32_e32 v216, 16, v240
	v_and_b32_e32 v217, 0xffff0000, v240
	v_lshlrev_b32_e32 v240, 16, v241
	v_and_b32_e32 v241, 0xffff0000, v241
	v_pk_add_f32 v[218:219], v[218:219], v[216:217]
	v_pk_add_f32 v[220:221], v[220:221], v[240:241]
	ds_read_b128 v[238:241], v246 offset:3024
	s_waitcnt lgkmcnt(7)
	v_lshlrev_b32_e32 v216, 16, v242
	v_and_b32_e32 v217, 0xffff0000, v242
	v_lshlrev_b32_e32 v242, 16, v243
	v_and_b32_e32 v243, 0xffff0000, v243
	v_pk_add_f32 v[106:107], v[106:107], v[216:217]
	v_pk_add_f32 v[108:109], v[108:109], v[242:243]
	v_lshlrev_b32_e32 v216, 16, v244
	v_and_b32_e32 v217, 0xffff0000, v244
	v_lshlrev_b32_e32 v244, 16, v245
	v_and_b32_e32 v245, 0xffff0000, v245
	v_pk_add_f32 v[218:219], v[218:219], v[216:217]
	v_pk_add_f32 v[220:221], v[220:221], v[244:245]
	ds_read_b128 v[242:245], v246 offset:2752
	s_waitcnt lgkmcnt(7)
	v_lshlrev_b32_e32 v216, 16, v248
	v_and_b32_e32 v217, 0xffff0000, v248
	v_lshlrev_b32_e32 v248, 16, v249
	v_and_b32_e32 v249, 0xffff0000, v249
	v_pk_add_f32 v[106:107], v[106:107], v[216:217]
	v_pk_add_f32 v[108:109], v[108:109], v[248:249]
	v_lshlrev_b32_e32 v216, 16, v250
	v_and_b32_e32 v217, 0xffff0000, v250
	v_lshlrev_b32_e32 v250, 16, v251
	v_and_b32_e32 v251, 0xffff0000, v251
	v_pk_add_f32 v[218:219], v[218:219], v[216:217]
	v_pk_add_f32 v[220:221], v[220:221], v[250:251]
	ds_read_b128 v[248:251], v246 offset:2480
	s_waitcnt lgkmcnt(7)
	v_lshlrev_b32_e32 v216, 16, v252
	v_and_b32_e32 v217, 0xffff0000, v252
	v_lshlrev_b32_e32 v252, 16, v253
	v_and_b32_e32 v253, 0xffff0000, v253
	v_pk_add_f32 v[106:107], v[106:107], v[216:217]
	v_pk_add_f32 v[108:109], v[108:109], v[252:253]
	v_lshlrev_b32_e32 v216, 16, v254
	v_and_b32_e32 v217, 0xffff0000, v254
	v_lshlrev_b32_e32 v254, 16, v255
	v_and_b32_e32 v255, 0xffff0000, v255
	v_pk_add_f32 v[218:219], v[218:219], v[216:217]
	v_pk_add_f32 v[220:221], v[220:221], v[254:255]
	ds_read_b128 v[252:255], v246 offset:2208
	v_fma_f32 v106, v159, v106, -v98
	v_fma_f32 v107, v159, v107, -v99
	v_fma_f32 v108, v159, v108, -v100
	v_fma_f32 v109, v159, v109, -v101
	v_fma_f32 v218, v159, v218, -v102
	v_fma_f32 v219, v159, v219, -v103
	v_fma_f32 v220, v159, v220, -v104
	v_fma_f32 v221, v159, v221, -v105
	v_cvt_pk_bf16_f32 v106, v106, v107
	v_cvt_pk_bf16_f32 v107, v108, v109
	v_cvt_pk_bf16_f32 v108, v218, v219
	v_cvt_pk_bf16_f32 v109, v220, v221
	s_and_saveexec_b64 s[28:29], s[6:7]
	s_cbranch_execz .Lpu0_0
	global_store_dwordx4 v[192:193], v[98:101], off offset:0
	global_store_dwordx4 v[192:193], v[102:105], off offset:16
.Lpu0_0:
	s_or_b64 exec, exec, s[28:29]
	s_waitcnt vmcnt(8)
	v_mfma_f32_32x32x16_bf16 v[2:17], v[106:109], v[70:73], v[2:17]
	v_mfma_f32_32x32x16_bf16 v[18:33], v[106:109], v[74:77], v[18:33]
	v_mfma_f32_32x32x16_bf16 v[34:49], v[106:109], v[78:81], v[34:49]
	v_mfma_f32_32x32x16_bf16 v[50:65], v[106:109], v[66:69], v[50:65]
	global_load_dwordx4 v[70:73], v[144:145], off offset:1536
	global_load_dwordx4 v[74:77], v[146:147], off offset:1536
	global_load_dwordx4 v[78:81], v[148:149], off offset:1536
	global_load_dwordx4 v[66:69], v[150:151], off offset:1536
	s_waitcnt lgkmcnt(7)
	v_lshlrev_b32_e32 v98, 16, v222
	v_and_b32_e32 v99, 0xffff0000, v222
	v_lshlrev_b32_e32 v100, 16, v223
	v_and_b32_e32 v101, 0xffff0000, v223
	v_lshlrev_b32_e32 v102, 16, v224
	v_and_b32_e32 v103, 0xffff0000, v224
	v_lshlrev_b32_e32 v104, 16, v225
	v_and_b32_e32 v105, 0xffff0000, v225
	ds_read_b128 v[222:225], v246 offset:1936
	s_waitcnt lgkmcnt(7)
	v_lshlrev_b32_e32 v216, 16, v226
	v_and_b32_e32 v217, 0xffff0000, v226
	v_lshlrev_b32_e32 v226, 16, v227
	v_and_b32_e32 v227, 0xffff0000, v227
	v_pk_add_f32 v[106:107], v[98:99], v[216:217]
	v_pk_add_f32 v[108:109], v[100:101], v[226:227]
	v_lshlrev_b32_e32 v216, 16, v228
	v_and_b32_e32 v217, 0xffff0000, v228
	v_lshlrev_b32_e32 v228, 16, v229
	v_and_b32_e32 v229, 0xffff0000, v229
	v_pk_add_f32 v[218:219], v[102:103], v[216:217]
	v_pk_add_f32 v[220:221], v[104:105], v[228:229]
	ds_read_b128 v[226:229], v246 offset:1664
	s_waitcnt lgkmcnt(7)
	v_lshlrev_b32_e32 v216, 16, v230
	v_and_b32_e32 v217, 0xffff0000, v230
	v_lshlrev_b32_e32 v230, 16, v231
	v_and_b32_e32 v231, 0xffff0000, v231
	v_pk_add_f32 v[106:107], v[106:107], v[216:217]
	v_pk_add_f32 v[108:109], v[108:109], v[230:231]
	v_lshlrev_b32_e32 v216, 16, v232
	v_and_b32_e32 v217, 0xffff0000, v232
	v_lshlrev_b32_e32 v232, 16, v233
	v_and_b32_e32 v233, 0xffff0000, v233
	v_pk_add_f32 v[218:219], v[218:219], v[216:217]
	v_pk_add_f32 v[220:221], v[220:221], v[232:233]
	ds_read_b128 v[230:233], v246 offset:1392
	s_waitcnt lgkmcnt(7)
	v_lshlrev_b32_e32 v216, 16, v234
	v_and_b32_e32 v217, 0xffff0000, v234
	v_lshlrev_b32_e32 v234, 16, v235
	v_and_b32_e32 v235, 0xffff0000, v235
	v_pk_add_f32 v[106:107], v[106:107], v[216:217]
	v_pk_add_f32 v[108:109], v[108:109], v[234:235]
	v_lshlrev_b32_e32 v216, 16, v236
	v_and_b32_e32 v217, 0xffff0000, v236
	v_lshlrev_b32_e32 v236, 16, v237
	v_and_b32_e32 v237, 0xffff0000, v237
	v_pk_add_f32 v[218:219], v[218:219], v[216:217]
	v_pk_add_f32 v[220:221], v[220:221], v[236:237]
	ds_read_b128 v[234:237], v246 offset:1120
	s_waitcnt lgkmcnt(7)
	v_lshlrev_b32_e32 v216, 16, v238
	v_and_b32_e32 v217, 0xffff0000, v238
	v_lshlrev_b32_e32 v238, 16, v239
	v_and_b32_e32 v239, 0xffff0000, v239
	v_pk_add_f32 v[106:107], v[106:107], v[216:217]
	v_pk_add_f32 v[108:109], v[108:109], v[238:239]
	v_lshlrev_b32_e32 v216, 16, v240
	v_and_b32_e32 v217, 0xffff0000, v240
	v_lshlrev_b32_e32 v240, 16, v241
	v_and_b32_e32 v241, 0xffff0000, v241
	v_pk_add_f32 v[218:219], v[218:219], v[216:217]
	v_pk_add_f32 v[220:221], v[220:221], v[240:241]
	ds_read_b128 v[238:241], v246 offset:848
	s_waitcnt lgkmcnt(7)
	v_lshlrev_b32_e32 v216, 16, v242
	v_and_b32_e32 v217, 0xffff0000, v242
	v_lshlrev_b32_e32 v242, 16, v243
	v_and_b32_e32 v243, 0xffff0000, v243
	v_pk_add_f32 v[106:107], v[106:107], v[216:217]
	v_pk_add_f32 v[108:109], v[108:109], v[242:243]
	v_lshlrev_b32_e32 v216, 16, v244
	v_and_b32_e32 v217, 0xffff0000, v244
	v_lshlrev_b32_e32 v244, 16, v245
	v_and_b32_e32 v245, 0xffff0000, v245
	v_pk_add_f32 v[218:219], v[218:219], v[216:217]
	v_pk_add_f32 v[220:221], v[220:221], v[244:245]
	ds_read_b128 v[242:245], v246 offset:576
	s_waitcnt lgkmcnt(7)
	v_lshlrev_b32_e32 v216, 16, v248
	v_and_b32_e32 v217, 0xffff0000, v248
	v_lshlrev_b32_e32 v248, 16, v249
	v_and_b32_e32 v249, 0xffff0000, v249
	v_pk_add_f32 v[106:107], v[106:107], v[216:217]
	v_pk_add_f32 v[108:109], v[108:109], v[248:249]
	v_lshlrev_b32_e32 v216, 16, v250
	v_and_b32_e32 v217, 0xffff0000, v250
	v_lshlrev_b32_e32 v250, 16, v251
	v_and_b32_e32 v251, 0xffff0000, v251
	v_pk_add_f32 v[218:219], v[218:219], v[216:217]
	v_pk_add_f32 v[220:221], v[220:221], v[250:251]
	ds_read_b128 v[248:251], v246 offset:304
	s_waitcnt lgkmcnt(7)
	v_lshlrev_b32_e32 v216, 16, v252
	v_and_b32_e32 v217, 0xffff0000, v252
	v_lshlrev_b32_e32 v252, 16, v253
	v_and_b32_e32 v253, 0xffff0000, v253
	v_pk_add_f32 v[106:107], v[106:107], v[216:217]
	v_pk_add_f32 v[108:109], v[108:109], v[252:253]
	v_lshlrev_b32_e32 v216, 16, v254
	v_and_b32_e32 v217, 0xffff0000, v254
	v_lshlrev_b32_e32 v254, 16, v255
	v_and_b32_e32 v255, 0xffff0000, v255
	v_pk_add_f32 v[218:219], v[218:219], v[216:217]
	v_pk_add_f32 v[220:221], v[220:221], v[254:255]
	ds_read_b128 v[252:255], v246 offset:32
	s_waitcnt lgkmcnt(7)
	v_lshlrev_b32_e32 v216, 16, v222
	v_and_b32_e32 v217, 0xffff0000, v222
	v_lshlrev_b32_e32 v222, 16, v223
	v_and_b32_e32 v223, 0xffff0000, v223
	v_pk_add_f32 v[106:107], v[106:107], v[216:217]
	v_pk_add_f32 v[108:109], v[108:109], v[222:223]
	v_lshlrev_b32_e32 v216, 16, v224
	v_and_b32_e32 v217, 0xffff0000, v224
	v_lshlrev_b32_e32 v224, 16, v225
	v_and_b32_e32 v225, 0xffff0000, v225
	v_pk_add_f32 v[218:219], v[218:219], v[216:217]
	v_pk_add_f32 v[220:221], v[220:221], v[224:225]
	ds_read_b128 v[222:225], v246 offset:4144
	s_waitcnt lgkmcnt(7)
	v_lshlrev_b32_e32 v216, 16, v226
	v_and_b32_e32 v217, 0xffff0000, v226
	v_lshlrev_b32_e32 v226, 16, v227
	v_and_b32_e32 v227, 0xffff0000, v227
	v_pk_add_f32 v[106:107], v[106:107], v[216:217]
	v_pk_add_f32 v[108:109], v[108:109], v[226:227]
	v_lshlrev_b32_e32 v216, 16, v228
	v_and_b32_e32 v217, 0xffff0000, v228
	v_lshlrev_b32_e32 v228, 16, v229
	v_and_b32_e32 v229, 0xffff0000, v229
	v_pk_add_f32 v[218:219], v[218:219], v[216:217]
	v_pk_add_f32 v[220:221], v[220:221], v[228:229]
	ds_read_b128 v[226:229], v246 offset:3872
	s_waitcnt lgkmcnt(7)
	v_lshlrev_b32_e32 v216, 16, v230
	v_and_b32_e32 v217, 0xffff0000, v230
	v_lshlrev_b32_e32 v230, 16, v231
	v_and_b32_e32 v231, 0xffff0000, v231
	v_pk_add_f32 v[106:107], v[106:107], v[216:217]
	v_pk_add_f32 v[108:109], v[108:109], v[230:231]
	v_lshlrev_b32_e32 v216, 16, v232
	v_and_b32_e32 v217, 0xffff0000, v232
	v_lshlrev_b32_e32 v232, 16, v233
	v_and_b32_e32 v233, 0xffff0000, v233
	v_pk_add_f32 v[218:219], v[218:219], v[216:217]
	v_pk_add_f32 v[220:221], v[220:221], v[232:233]
	ds_read_b128 v[230:233], v246 offset:3600
	s_waitcnt lgkmcnt(7)
	v_lshlrev_b32_e32 v216, 16, v234
	v_and_b32_e32 v217, 0xffff0000, v234
	v_lshlrev_b32_e32 v234, 16, v235
	v_and_b32_e32 v235, 0xffff0000, v235
	v_pk_add_f32 v[106:107], v[106:107], v[216:217]
	v_pk_add_f32 v[108:109], v[108:109], v[234:235]
	v_lshlrev_b32_e32 v216, 16, v236
	v_and_b32_e32 v217, 0xffff0000, v236
	v_lshlrev_b32_e32 v236, 16, v237
	v_and_b32_e32 v237, 0xffff0000, v237
	v_pk_add_f32 v[218:219], v[218:219], v[216:217]
	v_pk_add_f32 v[220:221], v[220:221], v[236:237]
	ds_read_b128 v[234:237], v246 offset:3328
	s_waitcnt lgkmcnt(7)
	v_lshlrev_b32_e32 v216, 16, v238
	v_and_b32_e32 v217, 0xffff0000, v238
	v_lshlrev_b32_e32 v238, 16, v239
	v_and_b32_e32 v239, 0xffff0000, v239
	v_pk_add_f32 v[106:107], v[106:107], v[216:217]
	v_pk_add_f32 v[108:109], v[108:109], v[238:239]
	v_lshlrev_b32_e32 v216, 16, v240
	v_and_b32_e32 v217, 0xffff0000, v240
	v_lshlrev_b32_e32 v240, 16, v241
	v_and_b32_e32 v241, 0xffff0000, v241
	v_pk_add_f32 v[218:219], v[218:219], v[216:217]
	v_pk_add_f32 v[220:221], v[220:221], v[240:241]
	ds_read_b128 v[238:241], v246 offset:3056
	s_waitcnt lgkmcnt(7)
	v_lshlrev_b32_e32 v216, 16, v242
	v_and_b32_e32 v217, 0xffff0000, v242
	v_lshlrev_b32_e32 v242, 16, v243
	v_and_b32_e32 v243, 0xffff0000, v243
	v_pk_add_f32 v[106:107], v[106:107], v[216:217]
	v_pk_add_f32 v[108:109], v[108:109], v[242:243]
	v_lshlrev_b32_e32 v216, 16, v244
	v_and_b32_e32 v217, 0xffff0000, v244
	v_lshlrev_b32_e32 v244, 16, v245
	v_and_b32_e32 v245, 0xffff0000, v245
	v_pk_add_f32 v[218:219], v[218:219], v[216:217]
	v_pk_add_f32 v[220:221], v[220:221], v[244:245]
	ds_read_b128 v[242:245], v246 offset:2784
	s_waitcnt lgkmcnt(7)
	v_lshlrev_b32_e32 v216, 16, v248
	v_and_b32_e32 v217, 0xffff0000, v248
	v_lshlrev_b32_e32 v248, 16, v249
	v_and_b32_e32 v249, 0xffff0000, v249
	v_pk_add_f32 v[106:107], v[106:107], v[216:217]
	v_pk_add_f32 v[108:109], v[108:109], v[248:249]
	v_lshlrev_b32_e32 v216, 16, v250
	v_and_b32_e32 v217, 0xffff0000, v250
	v_lshlrev_b32_e32 v250, 16, v251
	v_and_b32_e32 v251, 0xffff0000, v251
	v_pk_add_f32 v[218:219], v[218:219], v[216:217]
	v_pk_add_f32 v[220:221], v[220:221], v[250:251]
	ds_read_b128 v[248:251], v246 offset:2512
	s_waitcnt lgkmcnt(7)
	v_lshlrev_b32_e32 v216, 16, v252
	v_and_b32_e32 v217, 0xffff0000, v252
	v_lshlrev_b32_e32 v252, 16, v253
	v_and_b32_e32 v253, 0xffff0000, v253
	v_pk_add_f32 v[106:107], v[106:107], v[216:217]
	v_pk_add_f32 v[108:109], v[108:109], v[252:253]
	v_lshlrev_b32_e32 v216, 16, v254
	v_and_b32_e32 v217, 0xffff0000, v254
	v_lshlrev_b32_e32 v254, 16, v255
	v_and_b32_e32 v255, 0xffff0000, v255
	v_pk_add_f32 v[218:219], v[218:219], v[216:217]
	v_pk_add_f32 v[220:221], v[220:221], v[254:255]
	ds_read_b128 v[252:255], v246 offset:2240
	v_fma_f32 v106, v159, v106, -v98
	v_fma_f32 v107, v159, v107, -v99
	v_fma_f32 v108, v159, v108, -v100
	v_fma_f32 v109, v159, v109, -v101
	v_fma_f32 v218, v159, v218, -v102
	v_fma_f32 v219, v159, v219, -v103
	v_fma_f32 v220, v159, v220, -v104
	v_fma_f32 v221, v159, v221, -v105
	v_cvt_pk_bf16_f32 v106, v106, v107
	v_cvt_pk_bf16_f32 v107, v108, v109
	v_cvt_pk_bf16_f32 v108, v218, v219
	v_cvt_pk_bf16_f32 v109, v220, v221
	s_and_saveexec_b64 s[28:29], s[6:7]
	s_cbranch_execz .Lpu0_1
	global_store_dwordx4 v[192:193], v[98:101], off offset:64
	global_store_dwordx4 v[192:193], v[102:105], off offset:80
.Lpu0_1:
	s_or_b64 exec, exec, s[28:29]
	s_waitcnt vmcnt(8)
	v_mfma_f32_32x32x16_bf16 v[2:17], v[106:109], v[82:85], v[2:17]
	v_mfma_f32_32x32x16_bf16 v[18:33], v[106:109], v[86:89], v[18:33]
	v_mfma_f32_32x32x16_bf16 v[34:49], v[106:109], v[90:93], v[34:49]
	v_mfma_f32_32x32x16_bf16 v[50:65], v[106:109], v[94:97], v[50:65]
	global_load_dwordx4 v[82:85], v[144:145], off offset:2048
	global_load_dwordx4 v[86:89], v[146:147], off offset:2048
	global_load_dwordx4 v[90:93], v[148:149], off offset:2048
	global_load_dwordx4 v[94:97], v[150:151], off offset:2048
	s_waitcnt lgkmcnt(7)
	v_lshlrev_b32_e32 v98, 16, v222
	v_and_b32_e32 v99, 0xffff0000, v222
	v_lshlrev_b32_e32 v100, 16, v223
	v_and_b32_e32 v101, 0xffff0000, v223
	v_lshlrev_b32_e32 v102, 16, v224
	v_and_b32_e32 v103, 0xffff0000, v224
	v_lshlrev_b32_e32 v104, 16, v225
	v_and_b32_e32 v105, 0xffff0000, v225
	ds_read_b128 v[222:225], v246 offset:1968
	s_waitcnt lgkmcnt(7)
	v_lshlrev_b32_e32 v216, 16, v226
	v_and_b32_e32 v217, 0xffff0000, v226
	v_lshlrev_b32_e32 v226, 16, v227
	v_and_b32_e32 v227, 0xffff0000, v227
	v_pk_add_f32 v[106:107], v[98:99], v[216:217]
	v_pk_add_f32 v[108:109], v[100:101], v[226:227]
	v_lshlrev_b32_e32 v216, 16, v228
	v_and_b32_e32 v217, 0xffff0000, v228
	v_lshlrev_b32_e32 v228, 16, v229
	v_and_b32_e32 v229, 0xffff0000, v229
	v_pk_add_f32 v[218:219], v[102:103], v[216:217]
	v_pk_add_f32 v[220:221], v[104:105], v[228:229]
	ds_read_b128 v[226:229], v246 offset:1696
	s_waitcnt lgkmcnt(7)
	v_lshlrev_b32_e32 v216, 16, v230
	v_and_b32_e32 v217, 0xffff0000, v230
	v_lshlrev_b32_e32 v230, 16, v231
	v_and_b32_e32 v231, 0xffff0000, v231
	v_pk_add_f32 v[106:107], v[106:107], v[216:217]
	v_pk_add_f32 v[108:109], v[108:109], v[230:231]
	v_lshlrev_b32_e32 v216, 16, v232
	v_and_b32_e32 v217, 0xffff0000, v232
	v_lshlrev_b32_e32 v232, 16, v233
	v_and_b32_e32 v233, 0xffff0000, v233
	v_pk_add_f32 v[218:219], v[218:219], v[216:217]
	v_pk_add_f32 v[220:221], v[220:221], v[232:233]
	ds_read_b128 v[230:233], v246 offset:1424
	s_waitcnt lgkmcnt(7)
	v_lshlrev_b32_e32 v216, 16, v234
	v_and_b32_e32 v217, 0xffff0000, v234
	v_lshlrev_b32_e32 v234, 16, v235
	v_and_b32_e32 v235, 0xffff0000, v235
	v_pk_add_f32 v[106:107], v[106:107], v[216:217]
	v_pk_add_f32 v[108:109], v[108:109], v[234:235]
	v_lshlrev_b32_e32 v216, 16, v236
	v_and_b32_e32 v217, 0xffff0000, v236
	v_lshlrev_b32_e32 v236, 16, v237
	v_and_b32_e32 v237, 0xffff0000, v237
	v_pk_add_f32 v[218:219], v[218:219], v[216:217]
	v_pk_add_f32 v[220:221], v[220:221], v[236:237]
	ds_read_b128 v[234:237], v246 offset:1152
	s_waitcnt lgkmcnt(7)
	v_lshlrev_b32_e32 v216, 16, v238
	v_and_b32_e32 v217, 0xffff0000, v238
	v_lshlrev_b32_e32 v238, 16, v239
	v_and_b32_e32 v239, 0xffff0000, v239
	v_pk_add_f32 v[106:107], v[106:107], v[216:217]
	v_pk_add_f32 v[108:109], v[108:109], v[238:239]
	v_lshlrev_b32_e32 v216, 16, v240
	v_and_b32_e32 v217, 0xffff0000, v240
	v_lshlrev_b32_e32 v240, 16, v241
	v_and_b32_e32 v241, 0xffff0000, v241
	v_pk_add_f32 v[218:219], v[218:219], v[216:217]
	v_pk_add_f32 v[220:221], v[220:221], v[240:241]
	ds_read_b128 v[238:241], v246 offset:880
	s_waitcnt lgkmcnt(7)
	v_lshlrev_b32_e32 v216, 16, v242
	v_and_b32_e32 v217, 0xffff0000, v242
	v_lshlrev_b32_e32 v242, 16, v243
	v_and_b32_e32 v243, 0xffff0000, v243
	v_pk_add_f32 v[106:107], v[106:107], v[216:217]
	v_pk_add_f32 v[108:109], v[108:109], v[242:243]
	v_lshlrev_b32_e32 v216, 16, v244
	v_and_b32_e32 v217, 0xffff0000, v244
	v_lshlrev_b32_e32 v244, 16, v245
	v_and_b32_e32 v245, 0xffff0000, v245
	v_pk_add_f32 v[218:219], v[218:219], v[216:217]
	v_pk_add_f32 v[220:221], v[220:221], v[244:245]
	ds_read_b128 v[242:245], v246 offset:608
	s_waitcnt lgkmcnt(7)
	v_lshlrev_b32_e32 v216, 16, v248
	v_and_b32_e32 v217, 0xffff0000, v248
	v_lshlrev_b32_e32 v248, 16, v249
	v_and_b32_e32 v249, 0xffff0000, v249
	v_pk_add_f32 v[106:107], v[106:107], v[216:217]
	v_pk_add_f32 v[108:109], v[108:109], v[248:249]
	v_lshlrev_b32_e32 v216, 16, v250
	v_and_b32_e32 v217, 0xffff0000, v250
	v_lshlrev_b32_e32 v250, 16, v251
	v_and_b32_e32 v251, 0xffff0000, v251
	v_pk_add_f32 v[218:219], v[218:219], v[216:217]
	v_pk_add_f32 v[220:221], v[220:221], v[250:251]
	ds_read_b128 v[248:251], v246 offset:336
	s_waitcnt lgkmcnt(7)
	v_lshlrev_b32_e32 v216, 16, v252
	v_and_b32_e32 v217, 0xffff0000, v252
	v_lshlrev_b32_e32 v252, 16, v253
	v_and_b32_e32 v253, 0xffff0000, v253
	v_pk_add_f32 v[106:107], v[106:107], v[216:217]
	v_pk_add_f32 v[108:109], v[108:109], v[252:253]
	v_lshlrev_b32_e32 v216, 16, v254
	v_and_b32_e32 v217, 0xffff0000, v254
	v_lshlrev_b32_e32 v254, 16, v255
	v_and_b32_e32 v255, 0xffff0000, v255
	v_pk_add_f32 v[218:219], v[218:219], v[216:217]
	v_pk_add_f32 v[220:221], v[220:221], v[254:255]
	ds_read_b128 v[252:255], v246 offset:64
	s_waitcnt lgkmcnt(7)
	v_lshlrev_b32_e32 v216, 16, v222
	v_and_b32_e32 v217, 0xffff0000, v222
	v_lshlrev_b32_e32 v222, 16, v223
	v_and_b32_e32 v223, 0xffff0000, v223
	v_pk_add_f32 v[106:107], v[106:107], v[216:217]
	v_pk_add_f32 v[108:109], v[108:109], v[222:223]
	v_lshlrev_b32_e32 v216, 16, v224
	v_and_b32_e32 v217, 0xffff0000, v224
	v_lshlrev_b32_e32 v224, 16, v225
	v_and_b32_e32 v225, 0xffff0000, v225
	v_pk_add_f32 v[218:219], v[218:219], v[216:217]
	v_pk_add_f32 v[220:221], v[220:221], v[224:225]
	ds_read_b128 v[222:225], v246 offset:4176
	s_waitcnt lgkmcnt(7)
	v_lshlrev_b32_e32 v216, 16, v226
	v_and_b32_e32 v217, 0xffff0000, v226
	v_lshlrev_b32_e32 v226, 16, v227
	v_and_b32_e32 v227, 0xffff0000, v227
	v_pk_add_f32 v[106:107], v[106:107], v[216:217]
	v_pk_add_f32 v[108:109], v[108:109], v[226:227]
	v_lshlrev_b32_e32 v216, 16, v228
	v_and_b32_e32 v217, 0xffff0000, v228
	v_lshlrev_b32_e32 v228, 16, v229
	v_and_b32_e32 v229, 0xffff0000, v229
	v_pk_add_f32 v[218:219], v[218:219], v[216:217]
	v_pk_add_f32 v[220:221], v[220:221], v[228:229]
	ds_read_b128 v[226:229], v246 offset:3904
	s_waitcnt lgkmcnt(7)
	v_lshlrev_b32_e32 v216, 16, v230
	v_and_b32_e32 v217, 0xffff0000, v230
	v_lshlrev_b32_e32 v230, 16, v231
	v_and_b32_e32 v231, 0xffff0000, v231
	v_pk_add_f32 v[106:107], v[106:107], v[216:217]
	v_pk_add_f32 v[108:109], v[108:109], v[230:231]
	v_lshlrev_b32_e32 v216, 16, v232
	v_and_b32_e32 v217, 0xffff0000, v232
	v_lshlrev_b32_e32 v232, 16, v233
	v_and_b32_e32 v233, 0xffff0000, v233
	v_pk_add_f32 v[218:219], v[218:219], v[216:217]
	v_pk_add_f32 v[220:221], v[220:221], v[232:233]
	ds_read_b128 v[230:233], v246 offset:3632
	s_waitcnt lgkmcnt(7)
	v_lshlrev_b32_e32 v216, 16, v234
	v_and_b32_e32 v217, 0xffff0000, v234
	v_lshlrev_b32_e32 v234, 16, v235
	v_and_b32_e32 v235, 0xffff0000, v235
	v_pk_add_f32 v[106:107], v[106:107], v[216:217]
	v_pk_add_f32 v[108:109], v[108:109], v[234:235]
	v_lshlrev_b32_e32 v216, 16, v236
	v_and_b32_e32 v217, 0xffff0000, v236
	v_lshlrev_b32_e32 v236, 16, v237
	v_and_b32_e32 v237, 0xffff0000, v237
	v_pk_add_f32 v[218:219], v[218:219], v[216:217]
	v_pk_add_f32 v[220:221], v[220:221], v[236:237]
	ds_read_b128 v[234:237], v246 offset:3360
	s_waitcnt lgkmcnt(7)
	v_lshlrev_b32_e32 v216, 16, v238
	v_and_b32_e32 v217, 0xffff0000, v238
	v_lshlrev_b32_e32 v238, 16, v239
	v_and_b32_e32 v239, 0xffff0000, v239
	v_pk_add_f32 v[106:107], v[106:107], v[216:217]
	v_pk_add_f32 v[108:109], v[108:109], v[238:239]
	v_lshlrev_b32_e32 v216, 16, v240
	v_and_b32_e32 v217, 0xffff0000, v240
	v_lshlrev_b32_e32 v240, 16, v241
	v_and_b32_e32 v241, 0xffff0000, v241
	v_pk_add_f32 v[218:219], v[218:219], v[216:217]
	v_pk_add_f32 v[220:221], v[220:221], v[240:241]
	ds_read_b128 v[238:241], v246 offset:3088
	s_waitcnt lgkmcnt(7)
	v_lshlrev_b32_e32 v216, 16, v242
	v_and_b32_e32 v217, 0xffff0000, v242
	v_lshlrev_b32_e32 v242, 16, v243
	v_and_b32_e32 v243, 0xffff0000, v243
	v_pk_add_f32 v[106:107], v[106:107], v[216:217]
	v_pk_add_f32 v[108:109], v[108:109], v[242:243]
	v_lshlrev_b32_e32 v216, 16, v244
	v_and_b32_e32 v217, 0xffff0000, v244
	v_lshlrev_b32_e32 v244, 16, v245
	v_and_b32_e32 v245, 0xffff0000, v245
	v_pk_add_f32 v[218:219], v[218:219], v[216:217]
	v_pk_add_f32 v[220:221], v[220:221], v[244:245]
	ds_read_b128 v[242:245], v246 offset:2816
	s_waitcnt lgkmcnt(7)
	v_lshlrev_b32_e32 v216, 16, v248
	v_and_b32_e32 v217, 0xffff0000, v248
	v_lshlrev_b32_e32 v248, 16, v249
	v_and_b32_e32 v249, 0xffff0000, v249
	v_pk_add_f32 v[106:107], v[106:107], v[216:217]
	v_pk_add_f32 v[108:109], v[108:109], v[248:249]
	v_lshlrev_b32_e32 v216, 16, v250
	v_and_b32_e32 v217, 0xffff0000, v250
	v_lshlrev_b32_e32 v250, 16, v251
	v_and_b32_e32 v251, 0xffff0000, v251
	v_pk_add_f32 v[218:219], v[218:219], v[216:217]
	v_pk_add_f32 v[220:221], v[220:221], v[250:251]
	ds_read_b128 v[248:251], v246 offset:2544
	s_waitcnt lgkmcnt(7)
	v_lshlrev_b32_e32 v216, 16, v252
	v_and_b32_e32 v217, 0xffff0000, v252
	v_lshlrev_b32_e32 v252, 16, v253
	v_and_b32_e32 v253, 0xffff0000, v253
	v_pk_add_f32 v[106:107], v[106:107], v[216:217]
	v_pk_add_f32 v[108:109], v[108:109], v[252:253]
	v_lshlrev_b32_e32 v216, 16, v254
	v_and_b32_e32 v217, 0xffff0000, v254
	v_lshlrev_b32_e32 v254, 16, v255
	v_and_b32_e32 v255, 0xffff0000, v255
	v_pk_add_f32 v[218:219], v[218:219], v[216:217]
	v_pk_add_f32 v[220:221], v[220:221], v[254:255]
	ds_read_b128 v[252:255], v246 offset:2272
	v_fma_f32 v106, v159, v106, -v98
	v_fma_f32 v107, v159, v107, -v99
	v_fma_f32 v108, v159, v108, -v100
	v_fma_f32 v109, v159, v109, -v101
	v_fma_f32 v218, v159, v218, -v102
	v_fma_f32 v219, v159, v219, -v103
	v_fma_f32 v220, v159, v220, -v104
	v_fma_f32 v221, v159, v221, -v105
	v_cvt_pk_bf16_f32 v106, v106, v107
	v_cvt_pk_bf16_f32 v107, v108, v109
	v_cvt_pk_bf16_f32 v108, v218, v219
	v_cvt_pk_bf16_f32 v109, v220, v221
	s_and_saveexec_b64 s[28:29], s[6:7]
	s_cbranch_execz .Lpu0_2
	global_store_dwordx4 v[192:193], v[98:101], off offset:128
	global_store_dwordx4 v[192:193], v[102:105], off offset:144
.Lpu0_2:
	s_or_b64 exec, exec, s[28:29]
	s_waitcnt vmcnt(8)
	v_mfma_f32_32x32x16_bf16 v[2:17], v[106:109], v[112:115], v[2:17]
	v_mfma_f32_32x32x16_bf16 v[18:33], v[106:109], v[116:119], v[18:33]
	v_mfma_f32_32x32x16_bf16 v[34:49], v[106:109], v[122:125], v[34:49]
	v_mfma_f32_32x32x16_bf16 v[50:65], v[106:109], v[126:129], v[50:65]
	global_load_dwordx4 v[112:115], v[144:145], off offset:2560
	global_load_dwordx4 v[116:119], v[146:147], off offset:2560
	global_load_dwordx4 v[122:125], v[148:149], off offset:2560
	global_load_dwordx4 v[126:129], v[150:151], off offset:2560
	s_waitcnt lgkmcnt(7)
	v_lshlrev_b32_e32 v98, 16, v222
	v_and_b32_e32 v99, 0xffff0000, v222
	v_lshlrev_b32_e32 v100, 16, v223
	v_and_b32_e32 v101, 0xffff0000, v223
	v_lshlrev_b32_e32 v102, 16, v224
	v_and_b32_e32 v103, 0xffff0000, v224
	v_lshlrev_b32_e32 v104, 16, v225
	v_and_b32_e32 v105, 0xffff0000, v225
	ds_read_b128 v[222:225], v246 offset:2000
	s_waitcnt lgkmcnt(7)
	v_lshlrev_b32_e32 v216, 16, v226
	v_and_b32_e32 v217, 0xffff0000, v226
	v_lshlrev_b32_e32 v226, 16, v227
	v_and_b32_e32 v227, 0xffff0000, v227
	v_pk_add_f32 v[106:107], v[98:99], v[216:217]
	v_pk_add_f32 v[108:109], v[100:101], v[226:227]
	v_lshlrev_b32_e32 v216, 16, v228
	v_and_b32_e32 v217, 0xffff0000, v228
	v_lshlrev_b32_e32 v228, 16, v229
	v_and_b32_e32 v229, 0xffff0000, v229
	v_pk_add_f32 v[218:219], v[102:103], v[216:217]
	v_pk_add_f32 v[220:221], v[104:105], v[228:229]
	ds_read_b128 v[226:229], v246 offset:1728
	s_waitcnt lgkmcnt(7)
	v_lshlrev_b32_e32 v216, 16, v230
	v_and_b32_e32 v217, 0xffff0000, v230
	v_lshlrev_b32_e32 v230, 16, v231
	v_and_b32_e32 v231, 0xffff0000, v231
	v_pk_add_f32 v[106:107], v[106:107], v[216:217]
	v_pk_add_f32 v[108:109], v[108:109], v[230:231]
	v_lshlrev_b32_e32 v216, 16, v232
	v_and_b32_e32 v217, 0xffff0000, v232
	v_lshlrev_b32_e32 v232, 16, v233
	v_and_b32_e32 v233, 0xffff0000, v233
	v_pk_add_f32 v[218:219], v[218:219], v[216:217]
	v_pk_add_f32 v[220:221], v[220:221], v[232:233]
	ds_read_b128 v[230:233], v246 offset:1456
	s_waitcnt lgkmcnt(7)
	v_lshlrev_b32_e32 v216, 16, v234
	v_and_b32_e32 v217, 0xffff0000, v234
	v_lshlrev_b32_e32 v234, 16, v235
	v_and_b32_e32 v235, 0xffff0000, v235
	v_pk_add_f32 v[106:107], v[106:107], v[216:217]
	v_pk_add_f32 v[108:109], v[108:109], v[234:235]
	v_lshlrev_b32_e32 v216, 16, v236
	v_and_b32_e32 v217, 0xffff0000, v236
	v_lshlrev_b32_e32 v236, 16, v237
	v_and_b32_e32 v237, 0xffff0000, v237
	v_pk_add_f32 v[218:219], v[218:219], v[216:217]
	v_pk_add_f32 v[220:221], v[220:221], v[236:237]
	ds_read_b128 v[234:237], v246 offset:1184
	s_waitcnt lgkmcnt(7)
	v_lshlrev_b32_e32 v216, 16, v238
	v_and_b32_e32 v217, 0xffff0000, v238
	v_lshlrev_b32_e32 v238, 16, v239
	v_and_b32_e32 v239, 0xffff0000, v239
	v_pk_add_f32 v[106:107], v[106:107], v[216:217]
	v_pk_add_f32 v[108:109], v[108:109], v[238:239]
	v_lshlrev_b32_e32 v216, 16, v240
	v_and_b32_e32 v217, 0xffff0000, v240
	v_lshlrev_b32_e32 v240, 16, v241
	v_and_b32_e32 v241, 0xffff0000, v241
	v_pk_add_f32 v[218:219], v[218:219], v[216:217]
	v_pk_add_f32 v[220:221], v[220:221], v[240:241]
	ds_read_b128 v[238:241], v246 offset:912
	s_waitcnt lgkmcnt(7)
	v_lshlrev_b32_e32 v216, 16, v242
	v_and_b32_e32 v217, 0xffff0000, v242
	v_lshlrev_b32_e32 v242, 16, v243
	v_and_b32_e32 v243, 0xffff0000, v243
	v_pk_add_f32 v[106:107], v[106:107], v[216:217]
	v_pk_add_f32 v[108:109], v[108:109], v[242:243]
	v_lshlrev_b32_e32 v216, 16, v244
	v_and_b32_e32 v217, 0xffff0000, v244
	v_lshlrev_b32_e32 v244, 16, v245
	v_and_b32_e32 v245, 0xffff0000, v245
	v_pk_add_f32 v[218:219], v[218:219], v[216:217]
	v_pk_add_f32 v[220:221], v[220:221], v[244:245]
	ds_read_b128 v[242:245], v246 offset:640
	s_waitcnt lgkmcnt(7)
	v_lshlrev_b32_e32 v216, 16, v248
	v_and_b32_e32 v217, 0xffff0000, v248
	v_lshlrev_b32_e32 v248, 16, v249
	v_and_b32_e32 v249, 0xffff0000, v249
	v_pk_add_f32 v[106:107], v[106:107], v[216:217]
	v_pk_add_f32 v[108:109], v[108:109], v[248:249]
	v_lshlrev_b32_e32 v216, 16, v250
	v_and_b32_e32 v217, 0xffff0000, v250
	v_lshlrev_b32_e32 v250, 16, v251
	v_and_b32_e32 v251, 0xffff0000, v251
	v_pk_add_f32 v[218:219], v[218:219], v[216:217]
	v_pk_add_f32 v[220:221], v[220:221], v[250:251]
	ds_read_b128 v[248:251], v246 offset:368
	s_waitcnt lgkmcnt(7)
	v_lshlrev_b32_e32 v216, 16, v252
	v_and_b32_e32 v217, 0xffff0000, v252
	v_lshlrev_b32_e32 v252, 16, v253
	v_and_b32_e32 v253, 0xffff0000, v253
	v_pk_add_f32 v[106:107], v[106:107], v[216:217]
	v_pk_add_f32 v[108:109], v[108:109], v[252:253]
	v_lshlrev_b32_e32 v216, 16, v254
	v_and_b32_e32 v217, 0xffff0000, v254
	v_lshlrev_b32_e32 v254, 16, v255
	v_and_b32_e32 v255, 0xffff0000, v255
	v_pk_add_f32 v[218:219], v[218:219], v[216:217]
	v_pk_add_f32 v[220:221], v[220:221], v[254:255]
	ds_read_b128 v[252:255], v246 offset:96
	s_waitcnt lgkmcnt(7)
	v_lshlrev_b32_e32 v216, 16, v222
	v_and_b32_e32 v217, 0xffff0000, v222
	v_lshlrev_b32_e32 v222, 16, v223
	v_and_b32_e32 v223, 0xffff0000, v223
	v_pk_add_f32 v[106:107], v[106:107], v[216:217]
	v_pk_add_f32 v[108:109], v[108:109], v[222:223]
	v_lshlrev_b32_e32 v216, 16, v224
	v_and_b32_e32 v217, 0xffff0000, v224
	v_lshlrev_b32_e32 v224, 16, v225
	v_and_b32_e32 v225, 0xffff0000, v225
	v_pk_add_f32 v[218:219], v[218:219], v[216:217]
	v_pk_add_f32 v[220:221], v[220:221], v[224:225]
	ds_read_b128 v[222:225], v246 offset:4208
	s_waitcnt lgkmcnt(7)
	v_lshlrev_b32_e32 v216, 16, v226
	v_and_b32_e32 v217, 0xffff0000, v226
	v_lshlrev_b32_e32 v226, 16, v227
	v_and_b32_e32 v227, 0xffff0000, v227
	v_pk_add_f32 v[106:107], v[106:107], v[216:217]
	v_pk_add_f32 v[108:109], v[108:109], v[226:227]
	v_lshlrev_b32_e32 v216, 16, v228
	v_and_b32_e32 v217, 0xffff0000, v228
	v_lshlrev_b32_e32 v228, 16, v229
	v_and_b32_e32 v229, 0xffff0000, v229
	v_pk_add_f32 v[218:219], v[218:219], v[216:217]
	v_pk_add_f32 v[220:221], v[220:221], v[228:229]
	ds_read_b128 v[226:229], v246 offset:3936
	s_waitcnt lgkmcnt(7)
	v_lshlrev_b32_e32 v216, 16, v230
	v_and_b32_e32 v217, 0xffff0000, v230
	v_lshlrev_b32_e32 v230, 16, v231
	v_and_b32_e32 v231, 0xffff0000, v231
	v_pk_add_f32 v[106:107], v[106:107], v[216:217]
	v_pk_add_f32 v[108:109], v[108:109], v[230:231]
	v_lshlrev_b32_e32 v216, 16, v232
	v_and_b32_e32 v217, 0xffff0000, v232
	v_lshlrev_b32_e32 v232, 16, v233
	v_and_b32_e32 v233, 0xffff0000, v233
	v_pk_add_f32 v[218:219], v[218:219], v[216:217]
	v_pk_add_f32 v[220:221], v[220:221], v[232:233]
	ds_read_b128 v[230:233], v246 offset:3664
	s_waitcnt lgkmcnt(7)
	v_lshlrev_b32_e32 v216, 16, v234
	v_and_b32_e32 v217, 0xffff0000, v234
	v_lshlrev_b32_e32 v234, 16, v235
	v_and_b32_e32 v235, 0xffff0000, v235
	v_pk_add_f32 v[106:107], v[106:107], v[216:217]
	v_pk_add_f32 v[108:109], v[108:109], v[234:235]
	v_lshlrev_b32_e32 v216, 16, v236
	v_and_b32_e32 v217, 0xffff0000, v236
	v_lshlrev_b32_e32 v236, 16, v237
	v_and_b32_e32 v237, 0xffff0000, v237
	v_pk_add_f32 v[218:219], v[218:219], v[216:217]
	v_pk_add_f32 v[220:221], v[220:221], v[236:237]
	ds_read_b128 v[234:237], v246 offset:3392
	s_waitcnt lgkmcnt(7)
	v_lshlrev_b32_e32 v216, 16, v238
	v_and_b32_e32 v217, 0xffff0000, v238
	v_lshlrev_b32_e32 v238, 16, v239
	v_and_b32_e32 v239, 0xffff0000, v239
	v_pk_add_f32 v[106:107], v[106:107], v[216:217]
	v_pk_add_f32 v[108:109], v[108:109], v[238:239]
	v_lshlrev_b32_e32 v216, 16, v240
	v_and_b32_e32 v217, 0xffff0000, v240
	v_lshlrev_b32_e32 v240, 16, v241
	v_and_b32_e32 v241, 0xffff0000, v241
	v_pk_add_f32 v[218:219], v[218:219], v[216:217]
	v_pk_add_f32 v[220:221], v[220:221], v[240:241]
	ds_read_b128 v[238:241], v246 offset:3120
	s_waitcnt lgkmcnt(7)
	v_lshlrev_b32_e32 v216, 16, v242
	v_and_b32_e32 v217, 0xffff0000, v242
	v_lshlrev_b32_e32 v242, 16, v243
	v_and_b32_e32 v243, 0xffff0000, v243
	v_pk_add_f32 v[106:107], v[106:107], v[216:217]
	v_pk_add_f32 v[108:109], v[108:109], v[242:243]
	v_lshlrev_b32_e32 v216, 16, v244
	v_and_b32_e32 v217, 0xffff0000, v244
	v_lshlrev_b32_e32 v244, 16, v245
	v_and_b32_e32 v245, 0xffff0000, v245
	v_pk_add_f32 v[218:219], v[218:219], v[216:217]
	v_pk_add_f32 v[220:221], v[220:221], v[244:245]
	ds_read_b128 v[242:245], v246 offset:2848
	s_waitcnt lgkmcnt(7)
	v_lshlrev_b32_e32 v216, 16, v248
	v_and_b32_e32 v217, 0xffff0000, v248
	v_lshlrev_b32_e32 v248, 16, v249
	v_and_b32_e32 v249, 0xffff0000, v249
	v_pk_add_f32 v[106:107], v[106:107], v[216:217]
	v_pk_add_f32 v[108:109], v[108:109], v[248:249]
	v_lshlrev_b32_e32 v216, 16, v250
	v_and_b32_e32 v217, 0xffff0000, v250
	v_lshlrev_b32_e32 v250, 16, v251
	v_and_b32_e32 v251, 0xffff0000, v251
	v_pk_add_f32 v[218:219], v[218:219], v[216:217]
	v_pk_add_f32 v[220:221], v[220:221], v[250:251]
	ds_read_b128 v[248:251], v246 offset:2576
	s_waitcnt lgkmcnt(7)
	v_lshlrev_b32_e32 v216, 16, v252
	v_and_b32_e32 v217, 0xffff0000, v252
	v_lshlrev_b32_e32 v252, 16, v253
	v_and_b32_e32 v253, 0xffff0000, v253
	v_pk_add_f32 v[106:107], v[106:107], v[216:217]
	v_pk_add_f32 v[108:109], v[108:109], v[252:253]
	v_lshlrev_b32_e32 v216, 16, v254
	v_and_b32_e32 v217, 0xffff0000, v254
	v_lshlrev_b32_e32 v254, 16, v255
	v_and_b32_e32 v255, 0xffff0000, v255
	v_pk_add_f32 v[218:219], v[218:219], v[216:217]
	v_pk_add_f32 v[220:221], v[220:221], v[254:255]
	ds_read_b128 v[252:255], v246 offset:2304
	v_fma_f32 v106, v159, v106, -v98
	v_fma_f32 v107, v159, v107, -v99
	v_fma_f32 v108, v159, v108, -v100
	v_fma_f32 v109, v159, v109, -v101
	v_fma_f32 v218, v159, v218, -v102
	v_fma_f32 v219, v159, v219, -v103
	v_fma_f32 v220, v159, v220, -v104
	v_fma_f32 v221, v159, v221, -v105
	v_cvt_pk_bf16_f32 v106, v106, v107
	v_cvt_pk_bf16_f32 v107, v108, v109
	v_cvt_pk_bf16_f32 v108, v218, v219
	v_cvt_pk_bf16_f32 v109, v220, v221
	s_and_saveexec_b64 s[28:29], s[6:7]
	s_cbranch_execz .Lpu0_3
	global_store_dwordx4 v[192:193], v[98:101], off offset:192
	global_store_dwordx4 v[192:193], v[102:105], off offset:208
.Lpu0_3:
	s_or_b64 exec, exec, s[28:29]
	s_waitcnt vmcnt(8)
	v_mfma_f32_32x32x16_bf16 v[2:17], v[106:109], v[70:73], v[2:17]
	v_mfma_f32_32x32x16_bf16 v[18:33], v[106:109], v[74:77], v[18:33]
	v_mfma_f32_32x32x16_bf16 v[34:49], v[106:109], v[78:81], v[34:49]
	v_mfma_f32_32x32x16_bf16 v[50:65], v[106:109], v[66:69], v[50:65]
	global_load_dwordx4 v[70:73], v[144:145], off offset:3072
	global_load_dwordx4 v[74:77], v[146:147], off offset:3072
	global_load_dwordx4 v[78:81], v[148:149], off offset:3072
	global_load_dwordx4 v[66:69], v[150:151], off offset:3072
	s_waitcnt lgkmcnt(7)
	v_lshlrev_b32_e32 v98, 16, v222
	v_and_b32_e32 v99, 0xffff0000, v222
	v_lshlrev_b32_e32 v100, 16, v223
	v_and_b32_e32 v101, 0xffff0000, v223
	v_lshlrev_b32_e32 v102, 16, v224
	v_and_b32_e32 v103, 0xffff0000, v224
	v_lshlrev_b32_e32 v104, 16, v225
	v_and_b32_e32 v105, 0xffff0000, v225
	ds_read_b128 v[222:225], v246 offset:2032
	s_waitcnt lgkmcnt(7)
	v_lshlrev_b32_e32 v216, 16, v226
	v_and_b32_e32 v217, 0xffff0000, v226
	v_lshlrev_b32_e32 v226, 16, v227
	v_and_b32_e32 v227, 0xffff0000, v227
	v_pk_add_f32 v[106:107], v[98:99], v[216:217]
	v_pk_add_f32 v[108:109], v[100:101], v[226:227]
	v_lshlrev_b32_e32 v216, 16, v228
	v_and_b32_e32 v217, 0xffff0000, v228
	v_lshlrev_b32_e32 v228, 16, v229
	v_and_b32_e32 v229, 0xffff0000, v229
	v_pk_add_f32 v[218:219], v[102:103], v[216:217]
	v_pk_add_f32 v[220:221], v[104:105], v[228:229]
	ds_read_b128 v[226:229], v246 offset:1760
	s_waitcnt lgkmcnt(7)
	v_lshlrev_b32_e32 v216, 16, v230
	v_and_b32_e32 v217, 0xffff0000, v230
	v_lshlrev_b32_e32 v230, 16, v231
	v_and_b32_e32 v231, 0xffff0000, v231
	v_pk_add_f32 v[106:107], v[106:107], v[216:217]
	v_pk_add_f32 v[108:109], v[108:109], v[230:231]
	v_lshlrev_b32_e32 v216, 16, v232
	v_and_b32_e32 v217, 0xffff0000, v232
	v_lshlrev_b32_e32 v232, 16, v233
	v_and_b32_e32 v233, 0xffff0000, v233
	v_pk_add_f32 v[218:219], v[218:219], v[216:217]
	v_pk_add_f32 v[220:221], v[220:221], v[232:233]
	ds_read_b128 v[230:233], v246 offset:1488
	s_waitcnt lgkmcnt(7)
	v_lshlrev_b32_e32 v216, 16, v234
	v_and_b32_e32 v217, 0xffff0000, v234
	v_lshlrev_b32_e32 v234, 16, v235
	v_and_b32_e32 v235, 0xffff0000, v235
	v_pk_add_f32 v[106:107], v[106:107], v[216:217]
	v_pk_add_f32 v[108:109], v[108:109], v[234:235]
	v_lshlrev_b32_e32 v216, 16, v236
	v_and_b32_e32 v217, 0xffff0000, v236
	v_lshlrev_b32_e32 v236, 16, v237
	v_and_b32_e32 v237, 0xffff0000, v237
	v_pk_add_f32 v[218:219], v[218:219], v[216:217]
	v_pk_add_f32 v[220:221], v[220:221], v[236:237]
	ds_read_b128 v[234:237], v246 offset:1216
	s_waitcnt lgkmcnt(7)
	v_lshlrev_b32_e32 v216, 16, v238
	v_and_b32_e32 v217, 0xffff0000, v238
	v_lshlrev_b32_e32 v238, 16, v239
	v_and_b32_e32 v239, 0xffff0000, v239
	v_pk_add_f32 v[106:107], v[106:107], v[216:217]
	v_pk_add_f32 v[108:109], v[108:109], v[238:239]
	v_lshlrev_b32_e32 v216, 16, v240
	v_and_b32_e32 v217, 0xffff0000, v240
	v_lshlrev_b32_e32 v240, 16, v241
	v_and_b32_e32 v241, 0xffff0000, v241
	v_pk_add_f32 v[218:219], v[218:219], v[216:217]
	v_pk_add_f32 v[220:221], v[220:221], v[240:241]
	ds_read_b128 v[238:241], v246 offset:944
	s_waitcnt lgkmcnt(7)
	v_lshlrev_b32_e32 v216, 16, v242
	v_and_b32_e32 v217, 0xffff0000, v242
	v_lshlrev_b32_e32 v242, 16, v243
	v_and_b32_e32 v243, 0xffff0000, v243
	v_pk_add_f32 v[106:107], v[106:107], v[216:217]
	v_pk_add_f32 v[108:109], v[108:109], v[242:243]
	v_lshlrev_b32_e32 v216, 16, v244
	v_and_b32_e32 v217, 0xffff0000, v244
	v_lshlrev_b32_e32 v244, 16, v245
	v_and_b32_e32 v245, 0xffff0000, v245
	v_pk_add_f32 v[218:219], v[218:219], v[216:217]
	v_pk_add_f32 v[220:221], v[220:221], v[244:245]
	ds_read_b128 v[242:245], v246 offset:672
	s_waitcnt lgkmcnt(7)
	v_lshlrev_b32_e32 v216, 16, v248
	v_and_b32_e32 v217, 0xffff0000, v248
	v_lshlrev_b32_e32 v248, 16, v249
	v_and_b32_e32 v249, 0xffff0000, v249
	v_pk_add_f32 v[106:107], v[106:107], v[216:217]
	v_pk_add_f32 v[108:109], v[108:109], v[248:249]
	v_lshlrev_b32_e32 v216, 16, v250
	v_and_b32_e32 v217, 0xffff0000, v250
	v_lshlrev_b32_e32 v250, 16, v251
	v_and_b32_e32 v251, 0xffff0000, v251
	v_pk_add_f32 v[218:219], v[218:219], v[216:217]
	v_pk_add_f32 v[220:221], v[220:221], v[250:251]
	ds_read_b128 v[248:251], v246 offset:400
	s_waitcnt lgkmcnt(7)
	v_lshlrev_b32_e32 v216, 16, v252
	v_and_b32_e32 v217, 0xffff0000, v252
	v_lshlrev_b32_e32 v252, 16, v253
	v_and_b32_e32 v253, 0xffff0000, v253
	v_pk_add_f32 v[106:107], v[106:107], v[216:217]
	v_pk_add_f32 v[108:109], v[108:109], v[252:253]
	v_lshlrev_b32_e32 v216, 16, v254
	v_and_b32_e32 v217, 0xffff0000, v254
	v_lshlrev_b32_e32 v254, 16, v255
	v_and_b32_e32 v255, 0xffff0000, v255
	v_pk_add_f32 v[218:219], v[218:219], v[216:217]
	v_pk_add_f32 v[220:221], v[220:221], v[254:255]
	ds_read_b128 v[252:255], v246 offset:128
	s_waitcnt lgkmcnt(7)
	v_lshlrev_b32_e32 v216, 16, v222
	v_and_b32_e32 v217, 0xffff0000, v222
	v_lshlrev_b32_e32 v222, 16, v223
	v_and_b32_e32 v223, 0xffff0000, v223
	v_pk_add_f32 v[106:107], v[106:107], v[216:217]
	v_pk_add_f32 v[108:109], v[108:109], v[222:223]
	v_lshlrev_b32_e32 v216, 16, v224
	v_and_b32_e32 v217, 0xffff0000, v224
	v_lshlrev_b32_e32 v224, 16, v225
	v_and_b32_e32 v225, 0xffff0000, v225
	v_pk_add_f32 v[218:219], v[218:219], v[216:217]
	v_pk_add_f32 v[220:221], v[220:221], v[224:225]
	ds_read_b128 v[222:225], v246 offset:4240
	s_waitcnt lgkmcnt(7)
	v_lshlrev_b32_e32 v216, 16, v226
	v_and_b32_e32 v217, 0xffff0000, v226
	v_lshlrev_b32_e32 v226, 16, v227
	v_and_b32_e32 v227, 0xffff0000, v227
	v_pk_add_f32 v[106:107], v[106:107], v[216:217]
	v_pk_add_f32 v[108:109], v[108:109], v[226:227]
	v_lshlrev_b32_e32 v216, 16, v228
	v_and_b32_e32 v217, 0xffff0000, v228
	v_lshlrev_b32_e32 v228, 16, v229
	v_and_b32_e32 v229, 0xffff0000, v229
	v_pk_add_f32 v[218:219], v[218:219], v[216:217]
	v_pk_add_f32 v[220:221], v[220:221], v[228:229]
	ds_read_b128 v[226:229], v246 offset:3968
	s_waitcnt lgkmcnt(7)
	v_lshlrev_b32_e32 v216, 16, v230
	v_and_b32_e32 v217, 0xffff0000, v230
	v_lshlrev_b32_e32 v230, 16, v231
	v_and_b32_e32 v231, 0xffff0000, v231
	v_pk_add_f32 v[106:107], v[106:107], v[216:217]
	v_pk_add_f32 v[108:109], v[108:109], v[230:231]
	v_lshlrev_b32_e32 v216, 16, v232
	v_and_b32_e32 v217, 0xffff0000, v232
	v_lshlrev_b32_e32 v232, 16, v233
	v_and_b32_e32 v233, 0xffff0000, v233
	v_pk_add_f32 v[218:219], v[218:219], v[216:217]
	v_pk_add_f32 v[220:221], v[220:221], v[232:233]
	ds_read_b128 v[230:233], v246 offset:3696
	s_waitcnt lgkmcnt(7)
	v_lshlrev_b32_e32 v216, 16, v234
	v_and_b32_e32 v217, 0xffff0000, v234
	v_lshlrev_b32_e32 v234, 16, v235
	v_and_b32_e32 v235, 0xffff0000, v235
	v_pk_add_f32 v[106:107], v[106:107], v[216:217]
	v_pk_add_f32 v[108:109], v[108:109], v[234:235]
	v_lshlrev_b32_e32 v216, 16, v236
	v_and_b32_e32 v217, 0xffff0000, v236
	v_lshlrev_b32_e32 v236, 16, v237
	v_and_b32_e32 v237, 0xffff0000, v237
	v_pk_add_f32 v[218:219], v[218:219], v[216:217]
	v_pk_add_f32 v[220:221], v[220:221], v[236:237]
	ds_read_b128 v[234:237], v246 offset:3424
	s_waitcnt lgkmcnt(7)
	v_lshlrev_b32_e32 v216, 16, v238
	v_and_b32_e32 v217, 0xffff0000, v238
	v_lshlrev_b32_e32 v238, 16, v239
	v_and_b32_e32 v239, 0xffff0000, v239
	v_pk_add_f32 v[106:107], v[106:107], v[216:217]
	v_pk_add_f32 v[108:109], v[108:109], v[238:239]
	v_lshlrev_b32_e32 v216, 16, v240
	v_and_b32_e32 v217, 0xffff0000, v240
	v_lshlrev_b32_e32 v240, 16, v241
	v_and_b32_e32 v241, 0xffff0000, v241
	v_pk_add_f32 v[218:219], v[218:219], v[216:217]
	v_pk_add_f32 v[220:221], v[220:221], v[240:241]
	ds_read_b128 v[238:241], v246 offset:3152
	s_waitcnt lgkmcnt(7)
	v_lshlrev_b32_e32 v216, 16, v242
	v_and_b32_e32 v217, 0xffff0000, v242
	v_lshlrev_b32_e32 v242, 16, v243
	v_and_b32_e32 v243, 0xffff0000, v243
	v_pk_add_f32 v[106:107], v[106:107], v[216:217]
	v_pk_add_f32 v[108:109], v[108:109], v[242:243]
	v_lshlrev_b32_e32 v216, 16, v244
	v_and_b32_e32 v217, 0xffff0000, v244
	v_lshlrev_b32_e32 v244, 16, v245
	v_and_b32_e32 v245, 0xffff0000, v245
	v_pk_add_f32 v[218:219], v[218:219], v[216:217]
	v_pk_add_f32 v[220:221], v[220:221], v[244:245]
	ds_read_b128 v[242:245], v246 offset:2880
	s_waitcnt lgkmcnt(7)
	v_lshlrev_b32_e32 v216, 16, v248
	v_and_b32_e32 v217, 0xffff0000, v248
	v_lshlrev_b32_e32 v248, 16, v249
	v_and_b32_e32 v249, 0xffff0000, v249
	v_pk_add_f32 v[106:107], v[106:107], v[216:217]
	v_pk_add_f32 v[108:109], v[108:109], v[248:249]
	v_lshlrev_b32_e32 v216, 16, v250
	v_and_b32_e32 v217, 0xffff0000, v250
	v_lshlrev_b32_e32 v250, 16, v251
	v_and_b32_e32 v251, 0xffff0000, v251
	v_pk_add_f32 v[218:219], v[218:219], v[216:217]
	v_pk_add_f32 v[220:221], v[220:221], v[250:251]
	ds_read_b128 v[248:251], v246 offset:2608
	s_waitcnt lgkmcnt(7)
	v_lshlrev_b32_e32 v216, 16, v252
	v_and_b32_e32 v217, 0xffff0000, v252
	v_lshlrev_b32_e32 v252, 16, v253
	v_and_b32_e32 v253, 0xffff0000, v253
	v_pk_add_f32 v[106:107], v[106:107], v[216:217]
	v_pk_add_f32 v[108:109], v[108:109], v[252:253]
	v_lshlrev_b32_e32 v216, 16, v254
	v_and_b32_e32 v217, 0xffff0000, v254
	v_lshlrev_b32_e32 v254, 16, v255
	v_and_b32_e32 v255, 0xffff0000, v255
	v_pk_add_f32 v[218:219], v[218:219], v[216:217]
	v_pk_add_f32 v[220:221], v[220:221], v[254:255]
	ds_read_b128 v[252:255], v246 offset:2336
	v_fma_f32 v106, v159, v106, -v98
	v_fma_f32 v107, v159, v107, -v99
	v_fma_f32 v108, v159, v108, -v100
	v_fma_f32 v109, v159, v109, -v101
	v_fma_f32 v218, v159, v218, -v102
	v_fma_f32 v219, v159, v219, -v103
	v_fma_f32 v220, v159, v220, -v104
	v_fma_f32 v221, v159, v221, -v105
	v_cvt_pk_bf16_f32 v106, v106, v107
	v_cvt_pk_bf16_f32 v107, v108, v109
	v_cvt_pk_bf16_f32 v108, v218, v219
	v_cvt_pk_bf16_f32 v109, v220, v221
	s_and_saveexec_b64 s[28:29], s[6:7]
	s_cbranch_execz .Lpu0_4
	global_store_dwordx4 v[192:193], v[98:101], off offset:256
	global_store_dwordx4 v[192:193], v[102:105], off offset:272
.Lpu0_4:
	s_or_b64 exec, exec, s[28:29]
	s_waitcnt vmcnt(8)
	v_mfma_f32_32x32x16_bf16 v[2:17], v[106:109], v[82:85], v[2:17]
	v_mfma_f32_32x32x16_bf16 v[18:33], v[106:109], v[86:89], v[18:33]
	v_mfma_f32_32x32x16_bf16 v[34:49], v[106:109], v[90:93], v[34:49]
	v_mfma_f32_32x32x16_bf16 v[50:65], v[106:109], v[94:97], v[50:65]
	global_load_dwordx4 v[82:85], v[144:145], off offset:3584
	global_load_dwordx4 v[86:89], v[146:147], off offset:3584
	global_load_dwordx4 v[90:93], v[148:149], off offset:3584
	global_load_dwordx4 v[94:97], v[150:151], off offset:3584
	s_waitcnt lgkmcnt(7)
	v_lshlrev_b32_e32 v98, 16, v222
	v_and_b32_e32 v99, 0xffff0000, v222
	v_lshlrev_b32_e32 v100, 16, v223
	v_and_b32_e32 v101, 0xffff0000, v223
	v_lshlrev_b32_e32 v102, 16, v224
	v_and_b32_e32 v103, 0xffff0000, v224
	v_lshlrev_b32_e32 v104, 16, v225
	v_and_b32_e32 v105, 0xffff0000, v225
	ds_read_b128 v[222:225], v246 offset:2064
	s_waitcnt lgkmcnt(7)
	v_lshlrev_b32_e32 v216, 16, v226
	v_and_b32_e32 v217, 0xffff0000, v226
	v_lshlrev_b32_e32 v226, 16, v227
	v_and_b32_e32 v227, 0xffff0000, v227
	v_pk_add_f32 v[106:107], v[98:99], v[216:217]
	v_pk_add_f32 v[108:109], v[100:101], v[226:227]
	v_lshlrev_b32_e32 v216, 16, v228
	v_and_b32_e32 v217, 0xffff0000, v228
	v_lshlrev_b32_e32 v228, 16, v229
	v_and_b32_e32 v229, 0xffff0000, v229
	v_pk_add_f32 v[218:219], v[102:103], v[216:217]
	v_pk_add_f32 v[220:221], v[104:105], v[228:229]
	ds_read_b128 v[226:229], v246 offset:1792
	s_waitcnt lgkmcnt(7)
	v_lshlrev_b32_e32 v216, 16, v230
	v_and_b32_e32 v217, 0xffff0000, v230
	v_lshlrev_b32_e32 v230, 16, v231
	v_and_b32_e32 v231, 0xffff0000, v231
	v_pk_add_f32 v[106:107], v[106:107], v[216:217]
	v_pk_add_f32 v[108:109], v[108:109], v[230:231]
	v_lshlrev_b32_e32 v216, 16, v232
	v_and_b32_e32 v217, 0xffff0000, v232
	v_lshlrev_b32_e32 v232, 16, v233
	v_and_b32_e32 v233, 0xffff0000, v233
	v_pk_add_f32 v[218:219], v[218:219], v[216:217]
	v_pk_add_f32 v[220:221], v[220:221], v[232:233]
	ds_read_b128 v[230:233], v246 offset:1520
	s_waitcnt lgkmcnt(7)
	v_lshlrev_b32_e32 v216, 16, v234
	v_and_b32_e32 v217, 0xffff0000, v234
	v_lshlrev_b32_e32 v234, 16, v235
	v_and_b32_e32 v235, 0xffff0000, v235
	v_pk_add_f32 v[106:107], v[106:107], v[216:217]
	v_pk_add_f32 v[108:109], v[108:109], v[234:235]
	v_lshlrev_b32_e32 v216, 16, v236
	v_and_b32_e32 v217, 0xffff0000, v236
	v_lshlrev_b32_e32 v236, 16, v237
	v_and_b32_e32 v237, 0xffff0000, v237
	v_pk_add_f32 v[218:219], v[218:219], v[216:217]
	v_pk_add_f32 v[220:221], v[220:221], v[236:237]
	ds_read_b128 v[234:237], v246 offset:1248
	s_waitcnt lgkmcnt(7)
	v_lshlrev_b32_e32 v216, 16, v238
	v_and_b32_e32 v217, 0xffff0000, v238
	v_lshlrev_b32_e32 v238, 16, v239
	v_and_b32_e32 v239, 0xffff0000, v239
	v_pk_add_f32 v[106:107], v[106:107], v[216:217]
	v_pk_add_f32 v[108:109], v[108:109], v[238:239]
	v_lshlrev_b32_e32 v216, 16, v240
	v_and_b32_e32 v217, 0xffff0000, v240
	v_lshlrev_b32_e32 v240, 16, v241
	v_and_b32_e32 v241, 0xffff0000, v241
	v_pk_add_f32 v[218:219], v[218:219], v[216:217]
	v_pk_add_f32 v[220:221], v[220:221], v[240:241]
	ds_read_b128 v[238:241], v246 offset:976
	s_waitcnt lgkmcnt(7)
	v_lshlrev_b32_e32 v216, 16, v242
	v_and_b32_e32 v217, 0xffff0000, v242
	v_lshlrev_b32_e32 v242, 16, v243
	v_and_b32_e32 v243, 0xffff0000, v243
	v_pk_add_f32 v[106:107], v[106:107], v[216:217]
	v_pk_add_f32 v[108:109], v[108:109], v[242:243]
	v_lshlrev_b32_e32 v216, 16, v244
	v_and_b32_e32 v217, 0xffff0000, v244
	v_lshlrev_b32_e32 v244, 16, v245
	v_and_b32_e32 v245, 0xffff0000, v245
	v_pk_add_f32 v[218:219], v[218:219], v[216:217]
	v_pk_add_f32 v[220:221], v[220:221], v[244:245]
	ds_read_b128 v[242:245], v246 offset:704
	s_waitcnt lgkmcnt(7)
	v_lshlrev_b32_e32 v216, 16, v248
	v_and_b32_e32 v217, 0xffff0000, v248
	v_lshlrev_b32_e32 v248, 16, v249
	v_and_b32_e32 v249, 0xffff0000, v249
	v_pk_add_f32 v[106:107], v[106:107], v[216:217]
	v_pk_add_f32 v[108:109], v[108:109], v[248:249]
	v_lshlrev_b32_e32 v216, 16, v250
	v_and_b32_e32 v217, 0xffff0000, v250
	v_lshlrev_b32_e32 v250, 16, v251
	v_and_b32_e32 v251, 0xffff0000, v251
	v_pk_add_f32 v[218:219], v[218:219], v[216:217]
	v_pk_add_f32 v[220:221], v[220:221], v[250:251]
	ds_read_b128 v[248:251], v246 offset:432
	s_waitcnt lgkmcnt(7)
	v_lshlrev_b32_e32 v216, 16, v252
	v_and_b32_e32 v217, 0xffff0000, v252
	v_lshlrev_b32_e32 v252, 16, v253
	v_and_b32_e32 v253, 0xffff0000, v253
	v_pk_add_f32 v[106:107], v[106:107], v[216:217]
	v_pk_add_f32 v[108:109], v[108:109], v[252:253]
	v_lshlrev_b32_e32 v216, 16, v254
	v_and_b32_e32 v217, 0xffff0000, v254
	v_lshlrev_b32_e32 v254, 16, v255
	v_and_b32_e32 v255, 0xffff0000, v255
	v_pk_add_f32 v[218:219], v[218:219], v[216:217]
	v_pk_add_f32 v[220:221], v[220:221], v[254:255]
	ds_read_b128 v[252:255], v246 offset:160
	s_waitcnt lgkmcnt(7)
	v_lshlrev_b32_e32 v216, 16, v222
	v_and_b32_e32 v217, 0xffff0000, v222
	v_lshlrev_b32_e32 v222, 16, v223
	v_and_b32_e32 v223, 0xffff0000, v223
	v_pk_add_f32 v[106:107], v[106:107], v[216:217]
	v_pk_add_f32 v[108:109], v[108:109], v[222:223]
	v_lshlrev_b32_e32 v216, 16, v224
	v_and_b32_e32 v217, 0xffff0000, v224
	v_lshlrev_b32_e32 v224, 16, v225
	v_and_b32_e32 v225, 0xffff0000, v225
	v_pk_add_f32 v[218:219], v[218:219], v[216:217]
	v_pk_add_f32 v[220:221], v[220:221], v[224:225]
	ds_read_b128 v[222:225], v246 offset:4272
	s_waitcnt lgkmcnt(7)
	v_lshlrev_b32_e32 v216, 16, v226
	v_and_b32_e32 v217, 0xffff0000, v226
	v_lshlrev_b32_e32 v226, 16, v227
	v_and_b32_e32 v227, 0xffff0000, v227
	v_pk_add_f32 v[106:107], v[106:107], v[216:217]
	v_pk_add_f32 v[108:109], v[108:109], v[226:227]
	v_lshlrev_b32_e32 v216, 16, v228
	v_and_b32_e32 v217, 0xffff0000, v228
	v_lshlrev_b32_e32 v228, 16, v229
	v_and_b32_e32 v229, 0xffff0000, v229
	v_pk_add_f32 v[218:219], v[218:219], v[216:217]
	v_pk_add_f32 v[220:221], v[220:221], v[228:229]
	ds_read_b128 v[226:229], v246 offset:4000
	s_waitcnt lgkmcnt(7)
	v_lshlrev_b32_e32 v216, 16, v230
	v_and_b32_e32 v217, 0xffff0000, v230
	v_lshlrev_b32_e32 v230, 16, v231
	v_and_b32_e32 v231, 0xffff0000, v231
	v_pk_add_f32 v[106:107], v[106:107], v[216:217]
	v_pk_add_f32 v[108:109], v[108:109], v[230:231]
	v_lshlrev_b32_e32 v216, 16, v232
	v_and_b32_e32 v217, 0xffff0000, v232
	v_lshlrev_b32_e32 v232, 16, v233
	v_and_b32_e32 v233, 0xffff0000, v233
	v_pk_add_f32 v[218:219], v[218:219], v[216:217]
	v_pk_add_f32 v[220:221], v[220:221], v[232:233]
	ds_read_b128 v[230:233], v246 offset:3728
	s_waitcnt lgkmcnt(7)
	v_lshlrev_b32_e32 v216, 16, v234
	v_and_b32_e32 v217, 0xffff0000, v234
	v_lshlrev_b32_e32 v234, 16, v235
	v_and_b32_e32 v235, 0xffff0000, v235
	v_pk_add_f32 v[106:107], v[106:107], v[216:217]
	v_pk_add_f32 v[108:109], v[108:109], v[234:235]
	v_lshlrev_b32_e32 v216, 16, v236
	v_and_b32_e32 v217, 0xffff0000, v236
	v_lshlrev_b32_e32 v236, 16, v237
	v_and_b32_e32 v237, 0xffff0000, v237
	v_pk_add_f32 v[218:219], v[218:219], v[216:217]
	v_pk_add_f32 v[220:221], v[220:221], v[236:237]
	ds_read_b128 v[234:237], v246 offset:3456
	s_waitcnt lgkmcnt(7)
	v_lshlrev_b32_e32 v216, 16, v238
	v_and_b32_e32 v217, 0xffff0000, v238
	v_lshlrev_b32_e32 v238, 16, v239
	v_and_b32_e32 v239, 0xffff0000, v239
	v_pk_add_f32 v[106:107], v[106:107], v[216:217]
	v_pk_add_f32 v[108:109], v[108:109], v[238:239]
	v_lshlrev_b32_e32 v216, 16, v240
	v_and_b32_e32 v217, 0xffff0000, v240
	v_lshlrev_b32_e32 v240, 16, v241
	v_and_b32_e32 v241, 0xffff0000, v241
	v_pk_add_f32 v[218:219], v[218:219], v[216:217]
	v_pk_add_f32 v[220:221], v[220:221], v[240:241]
	ds_read_b128 v[238:241], v246 offset:3184
	s_waitcnt lgkmcnt(7)
	v_lshlrev_b32_e32 v216, 16, v242
	v_and_b32_e32 v217, 0xffff0000, v242
	v_lshlrev_b32_e32 v242, 16, v243
	v_and_b32_e32 v243, 0xffff0000, v243
	v_pk_add_f32 v[106:107], v[106:107], v[216:217]
	v_pk_add_f32 v[108:109], v[108:109], v[242:243]
	v_lshlrev_b32_e32 v216, 16, v244
	v_and_b32_e32 v217, 0xffff0000, v244
	v_lshlrev_b32_e32 v244, 16, v245
	v_and_b32_e32 v245, 0xffff0000, v245
	v_pk_add_f32 v[218:219], v[218:219], v[216:217]
	v_pk_add_f32 v[220:221], v[220:221], v[244:245]
	ds_read_b128 v[242:245], v246 offset:2912
	s_waitcnt lgkmcnt(7)
	v_lshlrev_b32_e32 v216, 16, v248
	v_and_b32_e32 v217, 0xffff0000, v248
	v_lshlrev_b32_e32 v248, 16, v249
	v_and_b32_e32 v249, 0xffff0000, v249
	v_pk_add_f32 v[106:107], v[106:107], v[216:217]
	v_pk_add_f32 v[108:109], v[108:109], v[248:249]
	v_lshlrev_b32_e32 v216, 16, v250
	v_and_b32_e32 v217, 0xffff0000, v250
	v_lshlrev_b32_e32 v250, 16, v251
	v_and_b32_e32 v251, 0xffff0000, v251
	v_pk_add_f32 v[218:219], v[218:219], v[216:217]
	v_pk_add_f32 v[220:221], v[220:221], v[250:251]
	ds_read_b128 v[248:251], v246 offset:2640
	s_waitcnt lgkmcnt(7)
	v_lshlrev_b32_e32 v216, 16, v252
	v_and_b32_e32 v217, 0xffff0000, v252
	v_lshlrev_b32_e32 v252, 16, v253
	v_and_b32_e32 v253, 0xffff0000, v253
	v_pk_add_f32 v[106:107], v[106:107], v[216:217]
	v_pk_add_f32 v[108:109], v[108:109], v[252:253]
	v_lshlrev_b32_e32 v216, 16, v254
	v_and_b32_e32 v217, 0xffff0000, v254
	v_lshlrev_b32_e32 v254, 16, v255
	v_and_b32_e32 v255, 0xffff0000, v255
	v_pk_add_f32 v[218:219], v[218:219], v[216:217]
	v_pk_add_f32 v[220:221], v[220:221], v[254:255]
	ds_read_b128 v[252:255], v246 offset:2368
	v_fma_f32 v106, v159, v106, -v98
	v_fma_f32 v107, v159, v107, -v99
	v_fma_f32 v108, v159, v108, -v100
	v_fma_f32 v109, v159, v109, -v101
	v_fma_f32 v218, v159, v218, -v102
	v_fma_f32 v219, v159, v219, -v103
	v_fma_f32 v220, v159, v220, -v104
	v_fma_f32 v221, v159, v221, -v105
	v_cvt_pk_bf16_f32 v106, v106, v107
	v_cvt_pk_bf16_f32 v107, v108, v109
	v_cvt_pk_bf16_f32 v108, v218, v219
	v_cvt_pk_bf16_f32 v109, v220, v221
	s_and_saveexec_b64 s[28:29], s[6:7]
	s_cbranch_execz .Lpu0_5
	global_store_dwordx4 v[192:193], v[98:101], off offset:320
	global_store_dwordx4 v[192:193], v[102:105], off offset:336
.Lpu0_5:
	s_or_b64 exec, exec, s[28:29]
	s_waitcnt vmcnt(8)
	v_mfma_f32_32x32x16_bf16 v[2:17], v[106:109], v[112:115], v[2:17]
	v_mfma_f32_32x32x16_bf16 v[18:33], v[106:109], v[116:119], v[18:33]
	v_mfma_f32_32x32x16_bf16 v[34:49], v[106:109], v[122:125], v[34:49]
	v_mfma_f32_32x32x16_bf16 v[50:65], v[106:109], v[126:129], v[50:65]
	s_waitcnt lgkmcnt(7)
	v_lshlrev_b32_e32 v98, 16, v222
	v_and_b32_e32 v99, 0xffff0000, v222
	v_lshlrev_b32_e32 v100, 16, v223
	v_and_b32_e32 v101, 0xffff0000, v223
	v_lshlrev_b32_e32 v102, 16, v224
	v_and_b32_e32 v103, 0xffff0000, v224
	v_lshlrev_b32_e32 v104, 16, v225
	v_and_b32_e32 v105, 0xffff0000, v225
	ds_read_b128 v[222:225], v246 offset:2096
	s_waitcnt lgkmcnt(7)
	v_lshlrev_b32_e32 v216, 16, v226
	v_and_b32_e32 v217, 0xffff0000, v226
	v_lshlrev_b32_e32 v226, 16, v227
	v_and_b32_e32 v227, 0xffff0000, v227
	v_pk_add_f32 v[106:107], v[98:99], v[216:217]
	v_pk_add_f32 v[108:109], v[100:101], v[226:227]
	v_lshlrev_b32_e32 v216, 16, v228
	v_and_b32_e32 v217, 0xffff0000, v228
	v_lshlrev_b32_e32 v228, 16, v229
	v_and_b32_e32 v229, 0xffff0000, v229
	v_pk_add_f32 v[218:219], v[102:103], v[216:217]
	v_pk_add_f32 v[220:221], v[104:105], v[228:229]
	ds_read_b128 v[226:229], v246 offset:1824
	s_waitcnt lgkmcnt(7)
	v_lshlrev_b32_e32 v216, 16, v230
	v_and_b32_e32 v217, 0xffff0000, v230
	v_lshlrev_b32_e32 v230, 16, v231
	v_and_b32_e32 v231, 0xffff0000, v231
	v_pk_add_f32 v[106:107], v[106:107], v[216:217]
	v_pk_add_f32 v[108:109], v[108:109], v[230:231]
	v_lshlrev_b32_e32 v216, 16, v232
	v_and_b32_e32 v217, 0xffff0000, v232
	v_lshlrev_b32_e32 v232, 16, v233
	v_and_b32_e32 v233, 0xffff0000, v233
	v_pk_add_f32 v[218:219], v[218:219], v[216:217]
	v_pk_add_f32 v[220:221], v[220:221], v[232:233]
	ds_read_b128 v[230:233], v246 offset:1552
	s_waitcnt lgkmcnt(7)
	v_lshlrev_b32_e32 v216, 16, v234
	v_and_b32_e32 v217, 0xffff0000, v234
	v_lshlrev_b32_e32 v234, 16, v235
	v_and_b32_e32 v235, 0xffff0000, v235
	v_pk_add_f32 v[106:107], v[106:107], v[216:217]
	v_pk_add_f32 v[108:109], v[108:109], v[234:235]
	v_lshlrev_b32_e32 v216, 16, v236
	v_and_b32_e32 v217, 0xffff0000, v236
	v_lshlrev_b32_e32 v236, 16, v237
	v_and_b32_e32 v237, 0xffff0000, v237
	v_pk_add_f32 v[218:219], v[218:219], v[216:217]
	v_pk_add_f32 v[220:221], v[220:221], v[236:237]
	ds_read_b128 v[234:237], v246 offset:1280
	s_waitcnt lgkmcnt(7)
	v_lshlrev_b32_e32 v216, 16, v238
	v_and_b32_e32 v217, 0xffff0000, v238
	v_lshlrev_b32_e32 v238, 16, v239
	v_and_b32_e32 v239, 0xffff0000, v239
	v_pk_add_f32 v[106:107], v[106:107], v[216:217]
	v_pk_add_f32 v[108:109], v[108:109], v[238:239]
	v_lshlrev_b32_e32 v216, 16, v240
	v_and_b32_e32 v217, 0xffff0000, v240
	v_lshlrev_b32_e32 v240, 16, v241
	v_and_b32_e32 v241, 0xffff0000, v241
	v_pk_add_f32 v[218:219], v[218:219], v[216:217]
	v_pk_add_f32 v[220:221], v[220:221], v[240:241]
	ds_read_b128 v[238:241], v246 offset:1008
	s_waitcnt lgkmcnt(7)
	v_lshlrev_b32_e32 v216, 16, v242
	v_and_b32_e32 v217, 0xffff0000, v242
	v_lshlrev_b32_e32 v242, 16, v243
	v_and_b32_e32 v243, 0xffff0000, v243
	v_pk_add_f32 v[106:107], v[106:107], v[216:217]
	v_pk_add_f32 v[108:109], v[108:109], v[242:243]
	v_lshlrev_b32_e32 v216, 16, v244
	v_and_b32_e32 v217, 0xffff0000, v244
	v_lshlrev_b32_e32 v244, 16, v245
	v_and_b32_e32 v245, 0xffff0000, v245
	v_pk_add_f32 v[218:219], v[218:219], v[216:217]
	v_pk_add_f32 v[220:221], v[220:221], v[244:245]
	ds_read_b128 v[242:245], v246 offset:736
	s_waitcnt lgkmcnt(7)
	v_lshlrev_b32_e32 v216, 16, v248
	v_and_b32_e32 v217, 0xffff0000, v248
	v_lshlrev_b32_e32 v248, 16, v249
	v_and_b32_e32 v249, 0xffff0000, v249
	v_pk_add_f32 v[106:107], v[106:107], v[216:217]
	v_pk_add_f32 v[108:109], v[108:109], v[248:249]
	v_lshlrev_b32_e32 v216, 16, v250
	v_and_b32_e32 v217, 0xffff0000, v250
	v_lshlrev_b32_e32 v250, 16, v251
	v_and_b32_e32 v251, 0xffff0000, v251
	v_pk_add_f32 v[218:219], v[218:219], v[216:217]
	v_pk_add_f32 v[220:221], v[220:221], v[250:251]
	ds_read_b128 v[248:251], v246 offset:464
	s_waitcnt lgkmcnt(7)
	v_lshlrev_b32_e32 v216, 16, v252
	v_and_b32_e32 v217, 0xffff0000, v252
	v_lshlrev_b32_e32 v252, 16, v253
	v_and_b32_e32 v253, 0xffff0000, v253
	v_pk_add_f32 v[106:107], v[106:107], v[216:217]
	v_pk_add_f32 v[108:109], v[108:109], v[252:253]
	v_lshlrev_b32_e32 v216, 16, v254
	v_and_b32_e32 v217, 0xffff0000, v254
	v_lshlrev_b32_e32 v254, 16, v255
	v_and_b32_e32 v255, 0xffff0000, v255
	v_pk_add_f32 v[218:219], v[218:219], v[216:217]
	v_pk_add_f32 v[220:221], v[220:221], v[254:255]
	ds_read_b128 v[252:255], v246 offset:192
	s_waitcnt lgkmcnt(7)
	v_lshlrev_b32_e32 v216, 16, v222
	v_and_b32_e32 v217, 0xffff0000, v222
	v_lshlrev_b32_e32 v222, 16, v223
	v_and_b32_e32 v223, 0xffff0000, v223
	v_pk_add_f32 v[106:107], v[106:107], v[216:217]
	v_pk_add_f32 v[108:109], v[108:109], v[222:223]
	v_lshlrev_b32_e32 v216, 16, v224
	v_and_b32_e32 v217, 0xffff0000, v224
	v_lshlrev_b32_e32 v224, 16, v225
	v_and_b32_e32 v225, 0xffff0000, v225
	v_pk_add_f32 v[218:219], v[218:219], v[216:217]
	v_pk_add_f32 v[220:221], v[220:221], v[224:225]
	ds_read_b128 v[222:225], v246 offset:4304
	s_waitcnt lgkmcnt(7)
	v_lshlrev_b32_e32 v216, 16, v226
	v_and_b32_e32 v217, 0xffff0000, v226
	v_lshlrev_b32_e32 v226, 16, v227
	v_and_b32_e32 v227, 0xffff0000, v227
	v_pk_add_f32 v[106:107], v[106:107], v[216:217]
	v_pk_add_f32 v[108:109], v[108:109], v[226:227]
	v_lshlrev_b32_e32 v216, 16, v228
	v_and_b32_e32 v217, 0xffff0000, v228
	v_lshlrev_b32_e32 v228, 16, v229
	v_and_b32_e32 v229, 0xffff0000, v229
	v_pk_add_f32 v[218:219], v[218:219], v[216:217]
	v_pk_add_f32 v[220:221], v[220:221], v[228:229]
	ds_read_b128 v[226:229], v246 offset:4032
	s_waitcnt lgkmcnt(7)
	v_lshlrev_b32_e32 v216, 16, v230
	v_and_b32_e32 v217, 0xffff0000, v230
	v_lshlrev_b32_e32 v230, 16, v231
	v_and_b32_e32 v231, 0xffff0000, v231
	v_pk_add_f32 v[106:107], v[106:107], v[216:217]
	v_pk_add_f32 v[108:109], v[108:109], v[230:231]
	v_lshlrev_b32_e32 v216, 16, v232
	v_and_b32_e32 v217, 0xffff0000, v232
	v_lshlrev_b32_e32 v232, 16, v233
	v_and_b32_e32 v233, 0xffff0000, v233
	v_pk_add_f32 v[218:219], v[218:219], v[216:217]
	v_pk_add_f32 v[220:221], v[220:221], v[232:233]
	ds_read_b128 v[230:233], v246 offset:3760
	s_waitcnt lgkmcnt(7)
	v_lshlrev_b32_e32 v216, 16, v234
	v_and_b32_e32 v217, 0xffff0000, v234
	v_lshlrev_b32_e32 v234, 16, v235
	v_and_b32_e32 v235, 0xffff0000, v235
	v_pk_add_f32 v[106:107], v[106:107], v[216:217]
	v_pk_add_f32 v[108:109], v[108:109], v[234:235]
	v_lshlrev_b32_e32 v216, 16, v236
	v_and_b32_e32 v217, 0xffff0000, v236
	v_lshlrev_b32_e32 v236, 16, v237
	v_and_b32_e32 v237, 0xffff0000, v237
	v_pk_add_f32 v[218:219], v[218:219], v[216:217]
	v_pk_add_f32 v[220:221], v[220:221], v[236:237]
	ds_read_b128 v[234:237], v246 offset:3488
	s_waitcnt lgkmcnt(7)
	v_lshlrev_b32_e32 v216, 16, v238
	v_and_b32_e32 v217, 0xffff0000, v238
	v_lshlrev_b32_e32 v238, 16, v239
	v_and_b32_e32 v239, 0xffff0000, v239
	v_pk_add_f32 v[106:107], v[106:107], v[216:217]
	v_pk_add_f32 v[108:109], v[108:109], v[238:239]
	v_lshlrev_b32_e32 v216, 16, v240
	v_and_b32_e32 v217, 0xffff0000, v240
	v_lshlrev_b32_e32 v240, 16, v241
	v_and_b32_e32 v241, 0xffff0000, v241
	v_pk_add_f32 v[218:219], v[218:219], v[216:217]
	v_pk_add_f32 v[220:221], v[220:221], v[240:241]
	ds_read_b128 v[238:241], v246 offset:3216
	s_waitcnt lgkmcnt(7)
	v_lshlrev_b32_e32 v216, 16, v242
	v_and_b32_e32 v217, 0xffff0000, v242
	v_lshlrev_b32_e32 v242, 16, v243
	v_and_b32_e32 v243, 0xffff0000, v243
	v_pk_add_f32 v[106:107], v[106:107], v[216:217]
	v_pk_add_f32 v[108:109], v[108:109], v[242:243]
	v_lshlrev_b32_e32 v216, 16, v244
	v_and_b32_e32 v217, 0xffff0000, v244
	v_lshlrev_b32_e32 v244, 16, v245
	v_and_b32_e32 v245, 0xffff0000, v245
	v_pk_add_f32 v[218:219], v[218:219], v[216:217]
	v_pk_add_f32 v[220:221], v[220:221], v[244:245]
	ds_read_b128 v[242:245], v246 offset:2944
	s_waitcnt lgkmcnt(7)
	v_lshlrev_b32_e32 v216, 16, v248
	v_and_b32_e32 v217, 0xffff0000, v248
	v_lshlrev_b32_e32 v248, 16, v249
	v_and_b32_e32 v249, 0xffff0000, v249
	v_pk_add_f32 v[106:107], v[106:107], v[216:217]
	v_pk_add_f32 v[108:109], v[108:109], v[248:249]
	v_lshlrev_b32_e32 v216, 16, v250
	v_and_b32_e32 v217, 0xffff0000, v250
	v_lshlrev_b32_e32 v250, 16, v251
	v_and_b32_e32 v251, 0xffff0000, v251
	v_pk_add_f32 v[218:219], v[218:219], v[216:217]
	v_pk_add_f32 v[220:221], v[220:221], v[250:251]
	ds_read_b128 v[248:251], v246 offset:2672
	s_waitcnt lgkmcnt(7)
	v_lshlrev_b32_e32 v216, 16, v252
	v_and_b32_e32 v217, 0xffff0000, v252
	v_lshlrev_b32_e32 v252, 16, v253
	v_and_b32_e32 v253, 0xffff0000, v253
	v_pk_add_f32 v[106:107], v[106:107], v[216:217]
	v_pk_add_f32 v[108:109], v[108:109], v[252:253]
	v_lshlrev_b32_e32 v216, 16, v254
	v_and_b32_e32 v217, 0xffff0000, v254
	v_lshlrev_b32_e32 v254, 16, v255
	v_and_b32_e32 v255, 0xffff0000, v255
	v_pk_add_f32 v[218:219], v[218:219], v[216:217]
	v_pk_add_f32 v[220:221], v[220:221], v[254:255]
	ds_read_b128 v[252:255], v246 offset:2400
	v_fma_f32 v106, v159, v106, -v98
	v_fma_f32 v107, v159, v107, -v99
	v_fma_f32 v108, v159, v108, -v100
	v_fma_f32 v109, v159, v109, -v101
	v_fma_f32 v218, v159, v218, -v102
	v_fma_f32 v219, v159, v219, -v103
	v_fma_f32 v220, v159, v220, -v104
	v_fma_f32 v221, v159, v221, -v105
	v_cvt_pk_bf16_f32 v106, v106, v107
	v_cvt_pk_bf16_f32 v107, v108, v109
	v_cvt_pk_bf16_f32 v108, v218, v219
	v_cvt_pk_bf16_f32 v109, v220, v221
	s_and_saveexec_b64 s[28:29], s[6:7]
	s_cbranch_execz .Lpu0_6
	global_store_dwordx4 v[192:193], v[98:101], off offset:384
	global_store_dwordx4 v[192:193], v[102:105], off offset:400
.Lpu0_6:
	s_or_b64 exec, exec, s[28:29]
	s_waitcnt vmcnt(4)
	v_mfma_f32_32x32x16_bf16 v[2:17], v[106:109], v[70:73], v[2:17]
	v_mfma_f32_32x32x16_bf16 v[18:33], v[106:109], v[74:77], v[18:33]
	v_mfma_f32_32x32x16_bf16 v[34:49], v[106:109], v[78:81], v[34:49]
	v_mfma_f32_32x32x16_bf16 v[50:65], v[106:109], v[66:69], v[50:65]
	s_waitcnt lgkmcnt(7)
	v_lshlrev_b32_e32 v98, 16, v222
	v_and_b32_e32 v99, 0xffff0000, v222
	v_lshlrev_b32_e32 v100, 16, v223
	v_and_b32_e32 v101, 0xffff0000, v223
	v_lshlrev_b32_e32 v102, 16, v224
	v_and_b32_e32 v103, 0xffff0000, v224
	v_lshlrev_b32_e32 v104, 16, v225
	v_and_b32_e32 v105, 0xffff0000, v225
	ds_read_b128 v[222:225], v246 offset:2128
	s_waitcnt lgkmcnt(7)
	v_lshlrev_b32_e32 v216, 16, v226
	v_and_b32_e32 v217, 0xffff0000, v226
	v_lshlrev_b32_e32 v226, 16, v227
	v_and_b32_e32 v227, 0xffff0000, v227
	v_pk_add_f32 v[106:107], v[98:99], v[216:217]
	v_pk_add_f32 v[108:109], v[100:101], v[226:227]
	v_lshlrev_b32_e32 v216, 16, v228
	v_and_b32_e32 v217, 0xffff0000, v228
	v_lshlrev_b32_e32 v228, 16, v229
	v_and_b32_e32 v229, 0xffff0000, v229
	v_pk_add_f32 v[218:219], v[102:103], v[216:217]
	v_pk_add_f32 v[220:221], v[104:105], v[228:229]
	ds_read_b128 v[226:229], v246 offset:1856
	s_waitcnt lgkmcnt(7)
	v_lshlrev_b32_e32 v216, 16, v230
	v_and_b32_e32 v217, 0xffff0000, v230
	v_lshlrev_b32_e32 v230, 16, v231
	v_and_b32_e32 v231, 0xffff0000, v231
	v_pk_add_f32 v[106:107], v[106:107], v[216:217]
	v_pk_add_f32 v[108:109], v[108:109], v[230:231]
	v_lshlrev_b32_e32 v216, 16, v232
	v_and_b32_e32 v217, 0xffff0000, v232
	v_lshlrev_b32_e32 v232, 16, v233
	v_and_b32_e32 v233, 0xffff0000, v233
	v_pk_add_f32 v[218:219], v[218:219], v[216:217]
	v_pk_add_f32 v[220:221], v[220:221], v[232:233]
	ds_read_b128 v[230:233], v246 offset:1584
	s_waitcnt lgkmcnt(7)
	v_lshlrev_b32_e32 v216, 16, v234
	v_and_b32_e32 v217, 0xffff0000, v234
	v_lshlrev_b32_e32 v234, 16, v235
	v_and_b32_e32 v235, 0xffff0000, v235
	v_pk_add_f32 v[106:107], v[106:107], v[216:217]
	v_pk_add_f32 v[108:109], v[108:109], v[234:235]
	v_lshlrev_b32_e32 v216, 16, v236
	v_and_b32_e32 v217, 0xffff0000, v236
	v_lshlrev_b32_e32 v236, 16, v237
	v_and_b32_e32 v237, 0xffff0000, v237
	v_pk_add_f32 v[218:219], v[218:219], v[216:217]
	v_pk_add_f32 v[220:221], v[220:221], v[236:237]
	ds_read_b128 v[234:237], v246 offset:1312
	s_waitcnt lgkmcnt(7)
	v_lshlrev_b32_e32 v216, 16, v238
	v_and_b32_e32 v217, 0xffff0000, v238
	v_lshlrev_b32_e32 v238, 16, v239
	v_and_b32_e32 v239, 0xffff0000, v239
	v_pk_add_f32 v[106:107], v[106:107], v[216:217]
	v_pk_add_f32 v[108:109], v[108:109], v[238:239]
	v_lshlrev_b32_e32 v216, 16, v240
	v_and_b32_e32 v217, 0xffff0000, v240
	v_lshlrev_b32_e32 v240, 16, v241
	v_and_b32_e32 v241, 0xffff0000, v241
	v_pk_add_f32 v[218:219], v[218:219], v[216:217]
	v_pk_add_f32 v[220:221], v[220:221], v[240:241]
	ds_read_b128 v[238:241], v246 offset:1040
	s_waitcnt lgkmcnt(7)
	v_lshlrev_b32_e32 v216, 16, v242
	v_and_b32_e32 v217, 0xffff0000, v242
	v_lshlrev_b32_e32 v242, 16, v243
	v_and_b32_e32 v243, 0xffff0000, v243
	v_pk_add_f32 v[106:107], v[106:107], v[216:217]
	v_pk_add_f32 v[108:109], v[108:109], v[242:243]
	v_lshlrev_b32_e32 v216, 16, v244
	v_and_b32_e32 v217, 0xffff0000, v244
	v_lshlrev_b32_e32 v244, 16, v245
	v_and_b32_e32 v245, 0xffff0000, v245
	v_pk_add_f32 v[218:219], v[218:219], v[216:217]
	v_pk_add_f32 v[220:221], v[220:221], v[244:245]
	ds_read_b128 v[242:245], v246 offset:768
	s_waitcnt lgkmcnt(7)
	v_lshlrev_b32_e32 v216, 16, v248
	v_and_b32_e32 v217, 0xffff0000, v248
	v_lshlrev_b32_e32 v248, 16, v249
	v_and_b32_e32 v249, 0xffff0000, v249
	v_pk_add_f32 v[106:107], v[106:107], v[216:217]
	v_pk_add_f32 v[108:109], v[108:109], v[248:249]
	v_lshlrev_b32_e32 v216, 16, v250
	v_and_b32_e32 v217, 0xffff0000, v250
	v_lshlrev_b32_e32 v250, 16, v251
	v_and_b32_e32 v251, 0xffff0000, v251
	v_pk_add_f32 v[218:219], v[218:219], v[216:217]
	v_pk_add_f32 v[220:221], v[220:221], v[250:251]
	ds_read_b128 v[248:251], v246 offset:496
	s_waitcnt lgkmcnt(7)
	v_lshlrev_b32_e32 v216, 16, v252
	v_and_b32_e32 v217, 0xffff0000, v252
	v_lshlrev_b32_e32 v252, 16, v253
	v_and_b32_e32 v253, 0xffff0000, v253
	v_pk_add_f32 v[106:107], v[106:107], v[216:217]
	v_pk_add_f32 v[108:109], v[108:109], v[252:253]
	v_lshlrev_b32_e32 v216, 16, v254
	v_and_b32_e32 v217, 0xffff0000, v254
	v_lshlrev_b32_e32 v254, 16, v255
	v_and_b32_e32 v255, 0xffff0000, v255
	v_pk_add_f32 v[218:219], v[218:219], v[216:217]
	v_pk_add_f32 v[220:221], v[220:221], v[254:255]
	ds_read_b128 v[252:255], v246 offset:224
	s_waitcnt lgkmcnt(7)
	v_lshlrev_b32_e32 v216, 16, v222
	v_and_b32_e32 v217, 0xffff0000, v222
	v_lshlrev_b32_e32 v222, 16, v223
	v_and_b32_e32 v223, 0xffff0000, v223
	v_pk_add_f32 v[106:107], v[106:107], v[216:217]
	v_pk_add_f32 v[108:109], v[108:109], v[222:223]
	v_lshlrev_b32_e32 v216, 16, v224
	v_and_b32_e32 v217, 0xffff0000, v224
	v_lshlrev_b32_e32 v224, 16, v225
	v_and_b32_e32 v225, 0xffff0000, v225
	v_pk_add_f32 v[218:219], v[218:219], v[216:217]
	v_pk_add_f32 v[220:221], v[220:221], v[224:225]
	s_waitcnt lgkmcnt(6)
	v_lshlrev_b32_e32 v216, 16, v226
	v_and_b32_e32 v217, 0xffff0000, v226
	v_lshlrev_b32_e32 v226, 16, v227
	v_and_b32_e32 v227, 0xffff0000, v227
	v_pk_add_f32 v[106:107], v[106:107], v[216:217]
	v_pk_add_f32 v[108:109], v[108:109], v[226:227]
	v_lshlrev_b32_e32 v216, 16, v228
	v_and_b32_e32 v217, 0xffff0000, v228
	v_lshlrev_b32_e32 v228, 16, v229
	v_and_b32_e32 v229, 0xffff0000, v229
	v_pk_add_f32 v[218:219], v[218:219], v[216:217]
	v_pk_add_f32 v[220:221], v[220:221], v[228:229]
	s_waitcnt lgkmcnt(5)
	v_lshlrev_b32_e32 v216, 16, v230
	v_and_b32_e32 v217, 0xffff0000, v230
	v_lshlrev_b32_e32 v230, 16, v231
	v_and_b32_e32 v231, 0xffff0000, v231
	v_pk_add_f32 v[106:107], v[106:107], v[216:217]
	v_pk_add_f32 v[108:109], v[108:109], v[230:231]
	v_lshlrev_b32_e32 v216, 16, v232
	v_and_b32_e32 v217, 0xffff0000, v232
	v_lshlrev_b32_e32 v232, 16, v233
	v_and_b32_e32 v233, 0xffff0000, v233
	v_pk_add_f32 v[218:219], v[218:219], v[216:217]
	v_pk_add_f32 v[220:221], v[220:221], v[232:233]
	s_waitcnt lgkmcnt(4)
	v_lshlrev_b32_e32 v216, 16, v234
	v_and_b32_e32 v217, 0xffff0000, v234
	v_lshlrev_b32_e32 v234, 16, v235
	v_and_b32_e32 v235, 0xffff0000, v235
	v_pk_add_f32 v[106:107], v[106:107], v[216:217]
	v_pk_add_f32 v[108:109], v[108:109], v[234:235]
	v_lshlrev_b32_e32 v216, 16, v236
	v_and_b32_e32 v217, 0xffff0000, v236
	v_lshlrev_b32_e32 v236, 16, v237
	v_and_b32_e32 v237, 0xffff0000, v237
	v_pk_add_f32 v[218:219], v[218:219], v[216:217]
	v_pk_add_f32 v[220:221], v[220:221], v[236:237]
	s_waitcnt lgkmcnt(3)
	v_lshlrev_b32_e32 v216, 16, v238
	v_and_b32_e32 v217, 0xffff0000, v238
	v_lshlrev_b32_e32 v238, 16, v239
	v_and_b32_e32 v239, 0xffff0000, v239
	v_pk_add_f32 v[106:107], v[106:107], v[216:217]
	v_pk_add_f32 v[108:109], v[108:109], v[238:239]
	v_lshlrev_b32_e32 v216, 16, v240
	v_and_b32_e32 v217, 0xffff0000, v240
	v_lshlrev_b32_e32 v240, 16, v241
	v_and_b32_e32 v241, 0xffff0000, v241
	v_pk_add_f32 v[218:219], v[218:219], v[216:217]
	v_pk_add_f32 v[220:221], v[220:221], v[240:241]
	s_waitcnt lgkmcnt(2)
	v_lshlrev_b32_e32 v216, 16, v242
	v_and_b32_e32 v217, 0xffff0000, v242
	v_lshlrev_b32_e32 v242, 16, v243
	v_and_b32_e32 v243, 0xffff0000, v243
	v_pk_add_f32 v[106:107], v[106:107], v[216:217]
	v_pk_add_f32 v[108:109], v[108:109], v[242:243]
	v_lshlrev_b32_e32 v216, 16, v244
	v_and_b32_e32 v217, 0xffff0000, v244
	v_lshlrev_b32_e32 v244, 16, v245
	v_and_b32_e32 v245, 0xffff0000, v245
	v_pk_add_f32 v[218:219], v[218:219], v[216:217]
	v_pk_add_f32 v[220:221], v[220:221], v[244:245]
	s_waitcnt lgkmcnt(1)
	v_lshlrev_b32_e32 v216, 16, v248
	v_and_b32_e32 v217, 0xffff0000, v248
	v_lshlrev_b32_e32 v248, 16, v249
	v_and_b32_e32 v249, 0xffff0000, v249
	v_pk_add_f32 v[106:107], v[106:107], v[216:217]
	v_pk_add_f32 v[108:109], v[108:109], v[248:249]
	v_lshlrev_b32_e32 v216, 16, v250
	v_and_b32_e32 v217, 0xffff0000, v250
	v_lshlrev_b32_e32 v250, 16, v251
	v_and_b32_e32 v251, 0xffff0000, v251
	v_pk_add_f32 v[218:219], v[218:219], v[216:217]
	v_pk_add_f32 v[220:221], v[220:221], v[250:251]
	s_waitcnt lgkmcnt(0)
	v_lshlrev_b32_e32 v216, 16, v252
	v_and_b32_e32 v217, 0xffff0000, v252
	v_lshlrev_b32_e32 v252, 16, v253
	v_and_b32_e32 v253, 0xffff0000, v253
	v_pk_add_f32 v[106:107], v[106:107], v[216:217]
	v_pk_add_f32 v[108:109], v[108:109], v[252:253]
	v_lshlrev_b32_e32 v216, 16, v254
	v_and_b32_e32 v217, 0xffff0000, v254
	v_lshlrev_b32_e32 v254, 16, v255
	v_and_b32_e32 v255, 0xffff0000, v255
	v_pk_add_f32 v[218:219], v[218:219], v[216:217]
	v_pk_add_f32 v[220:221], v[220:221], v[254:255]
	v_fma_f32 v106, v159, v106, -v98
	v_fma_f32 v107, v159, v107, -v99
	v_fma_f32 v108, v159, v108, -v100
	v_fma_f32 v109, v159, v109, -v101
	v_fma_f32 v218, v159, v218, -v102
	v_fma_f32 v219, v159, v219, -v103
	v_fma_f32 v220, v159, v220, -v104
	v_fma_f32 v221, v159, v221, -v105
	v_cvt_pk_bf16_f32 v106, v106, v107
	v_cvt_pk_bf16_f32 v107, v108, v109
	v_cvt_pk_bf16_f32 v108, v218, v219
	v_cvt_pk_bf16_f32 v109, v220, v221
	s_and_saveexec_b64 s[28:29], s[6:7]
	s_cbranch_execz .Lpu0_7
	global_store_dwordx4 v[192:193], v[98:101], off offset:448
	global_store_dwordx4 v[192:193], v[102:105], off offset:464

.LBB0_355:
	s_or_b64 exec, exec, s[6:7]
	s_waitcnt lgkmcnt(0)
	global_load_dwordx4 v[82:85], v[112:113], off offset:512
	global_load_dwordx4 v[86:89], v[114:115], off offset:512
	global_load_dwordx4 v[90:93], v[116:117], off offset:512
	global_load_dwordx4 v[94:97], v[118:119], off offset:512
	global_load_dwordx4 v[222:225], v[112:113], off offset:1024
	global_load_dwordx4 v[226:229], v[114:115], off offset:1024
	global_load_dwordx4 v[230:233], v[116:117], off offset:1024
	global_load_dwordx4 v[234:237], v[118:119], off offset:1024
	v_lshl_add_u32 v246, v197, 1, v214
	ds_read_b128 v[238:241], v246 offset:4080
	ds_read_b128 v[242:245], v246 offset:3808
	ds_read_b128 v[248:251], v246 offset:3536
	ds_read_b128 v[252:255], v246 offset:3264
	v_or_b32_e32 v2, s28, v1
	v_min_u32_e32 v3, 7, v2
	v_add_u32_e32 v3, 1, v3
	v_cvt_f32_ubyte0_e32 v3, v3
	v_div_scale_f32 v4, s[6:7], v3, v3, 1.0
	v_rcp_f32_e32 v5, v4
	s_ashr_i32 s8, s30, 6
	s_mul_i32 s10, s8, 15
	v_cmp_lt_u32_e64 s[6:7], s41, v2
	v_fma_f32 v6, -v4, v5, 1.0
	v_fmac_f32_e32 v5, v6, v5
	v_div_scale_f32 v6, vcc, 1.0, v3, 1.0
	v_mul_f32_e32 v7, v6, v5
	v_fma_f32 v8, -v4, v7, v6
	v_fmac_f32_e32 v7, v8, v5
	v_fma_f32 v4, -v4, v7, v6
	v_div_fmas_f32 v4, v4, v5, v7
	v_div_fixup_f32 v159, v4, v3, 1.0
	s_ashr_i32 s11, s10, 31
	v_add_u32_e32 v2, 0xfffff80f, v2
	v_mov_b32_e32 v3, v155
	v_lshl_add_u64 v[2:3], v[2:3], 0, s[10:11]
	v_lshlrev_b64 v[2:3], 11, v[2:3]
	v_lshl_add_u64 v[2:3], s[70:71], 0, v[2:3]
	v_mov_b32_e32 v163, v155
	v_lshl_add_u64 v[2:3], v[2:3], 0, v[162:163]
	v_lshl_add_u64 v[192:193], v[2:3], 0, s[20:21]
	v_mov_b64_e32 v[2:3], 0
	v_mov_b64_e32 v[4:5], 0
	v_mov_b64_e32 v[6:7], 0
	v_mov_b64_e32 v[8:9], 0
	v_mov_b64_e32 v[10:11], 0
	v_mov_b64_e32 v[12:13], 0
	v_mov_b64_e32 v[14:15], 0
	v_mov_b64_e32 v[16:17], 0
	v_mov_b64_e32 v[18:19], 0
	v_mov_b64_e32 v[20:21], 0
	v_mov_b64_e32 v[22:23], 0
	v_mov_b64_e32 v[24:25], 0
	v_mov_b64_e32 v[26:27], 0
	v_mov_b64_e32 v[28:29], 0
	v_mov_b64_e32 v[30:31], 0
	v_mov_b64_e32 v[32:33], 0
	v_mov_b64_e32 v[34:35], 0
	v_mov_b64_e32 v[36:37], 0
	v_mov_b64_e32 v[38:39], 0
	v_mov_b64_e32 v[40:41], 0
	v_mov_b64_e32 v[42:43], 0
	v_mov_b64_e32 v[44:45], 0
	v_mov_b64_e32 v[46:47], 0
	v_mov_b64_e32 v[48:49], 0
	v_mov_b64_e32 v[50:51], 0
	v_mov_b64_e32 v[52:53], 0
	v_mov_b64_e32 v[54:55], 0
	v_mov_b64_e32 v[56:57], 0
	v_mov_b64_e32 v[58:59], 0
	v_mov_b64_e32 v[60:61], 0
	v_mov_b64_e32 v[62:63], 0
	v_mov_b64_e32 v[64:65], 0
	s_mov_b32 s49, 0
	s_mov_b64 s[10:11], 0
	s_waitcnt lgkmcnt(3)
	v_lshlrev_b32_e32 v98, 16, v238
	v_and_b32_e32 v99, 0xffff0000, v238
	v_lshlrev_b32_e32 v100, 16, v239
	v_and_b32_e32 v101, 0xffff0000, v239
	v_lshlrev_b32_e32 v102, 16, v240
	v_and_b32_e32 v103, 0xffff0000, v240
	v_lshlrev_b32_e32 v104, 16, v241
	v_and_b32_e32 v105, 0xffff0000, v241
	ds_read_b128 v[238:241], v246 offset:2992
	s_waitcnt lgkmcnt(3)
	v_lshlrev_b32_e32 v216, 16, v242
	v_and_b32_e32 v217, 0xffff0000, v242
	v_lshlrev_b32_e32 v242, 16, v243
	v_and_b32_e32 v243, 0xffff0000, v243
	v_pk_add_f32 v[106:107], v[98:99], v[216:217]
	v_pk_add_f32 v[108:109], v[100:101], v[242:243]
	v_lshlrev_b32_e32 v216, 16, v244
	v_and_b32_e32 v217, 0xffff0000, v244
	v_lshlrev_b32_e32 v244, 16, v245
	v_and_b32_e32 v245, 0xffff0000, v245
	v_pk_add_f32 v[218:219], v[102:103], v[216:217]
	v_pk_add_f32 v[220:221], v[104:105], v[244:245]
	ds_read_b128 v[242:245], v246 offset:2720
	s_waitcnt lgkmcnt(3)
	v_lshlrev_b32_e32 v216, 16, v248
	v_and_b32_e32 v217, 0xffff0000, v248
	v_lshlrev_b32_e32 v248, 16, v249
	v_and_b32_e32 v249, 0xffff0000, v249
	v_pk_add_f32 v[106:107], v[106:107], v[216:217]
	v_pk_add_f32 v[108:109], v[108:109], v[248:249]
	v_lshlrev_b32_e32 v216, 16, v250
	v_and_b32_e32 v217, 0xffff0000, v250
	v_lshlrev_b32_e32 v250, 16, v251
	v_and_b32_e32 v251, 0xffff0000, v251
	v_pk_add_f32 v[218:219], v[218:219], v[216:217]
	v_pk_add_f32 v[220:221], v[220:221], v[250:251]
	ds_read_b128 v[248:251], v246 offset:2448
	s_waitcnt lgkmcnt(3)
	v_lshlrev_b32_e32 v216, 16, v252
	v_and_b32_e32 v217, 0xffff0000, v252
	v_lshlrev_b32_e32 v252, 16, v253
	v_and_b32_e32 v253, 0xffff0000, v253
	v_pk_add_f32 v[106:107], v[106:107], v[216:217]
	v_pk_add_f32 v[108:109], v[108:109], v[252:253]
	v_lshlrev_b32_e32 v216, 16, v254
	v_and_b32_e32 v217, 0xffff0000, v254
	v_lshlrev_b32_e32 v254, 16, v255
	v_and_b32_e32 v255, 0xffff0000, v255
	v_pk_add_f32 v[218:219], v[218:219], v[216:217]
	v_pk_add_f32 v[220:221], v[220:221], v[254:255]
	ds_read_b128 v[252:255], v246 offset:2176
	s_waitcnt lgkmcnt(3)
	v_lshlrev_b32_e32 v216, 16, v238
	v_and_b32_e32 v217, 0xffff0000, v238
	v_lshlrev_b32_e32 v238, 16, v239
	v_and_b32_e32 v239, 0xffff0000, v239
	v_pk_add_f32 v[106:107], v[106:107], v[216:217]
	v_pk_add_f32 v[108:109], v[108:109], v[238:239]
	v_lshlrev_b32_e32 v216, 16, v240
	v_and_b32_e32 v217, 0xffff0000, v240
	v_lshlrev_b32_e32 v240, 16, v241
	v_and_b32_e32 v241, 0xffff0000, v241
	v_pk_add_f32 v[218:219], v[218:219], v[216:217]
	v_pk_add_f32 v[220:221], v[220:221], v[240:241]
	ds_read_b128 v[238:241], v246 offset:4112
	s_waitcnt lgkmcnt(3)
	v_lshlrev_b32_e32 v216, 16, v242
	v_and_b32_e32 v217, 0xffff0000, v242
	v_lshlrev_b32_e32 v242, 16, v243
	v_and_b32_e32 v243, 0xffff0000, v243
	v_pk_add_f32 v[106:107], v[106:107], v[216:217]
	v_pk_add_f32 v[108:109], v[108:109], v[242:243]
	v_lshlrev_b32_e32 v216, 16, v244
	v_and_b32_e32 v217, 0xffff0000, v244
	v_lshlrev_b32_e32 v244, 16, v245
	v_and_b32_e32 v245, 0xffff0000, v245
	v_pk_add_f32 v[218:219], v[218:219], v[216:217]
	v_pk_add_f32 v[220:221], v[220:221], v[244:245]
	ds_read_b128 v[242:245], v246 offset:3840
	s_waitcnt lgkmcnt(3)
	v_lshlrev_b32_e32 v216, 16, v248
	v_and_b32_e32 v217, 0xffff0000, v248
	v_lshlrev_b32_e32 v248, 16, v249
	v_and_b32_e32 v249, 0xffff0000, v249
	v_pk_add_f32 v[106:107], v[106:107], v[216:217]
	v_pk_add_f32 v[108:109], v[108:109], v[248:249]
	v_lshlrev_b32_e32 v216, 16, v250
	v_and_b32_e32 v217, 0xffff0000, v250
	v_lshlrev_b32_e32 v250, 16, v251
	v_and_b32_e32 v251, 0xffff0000, v251
	v_pk_add_f32 v[218:219], v[218:219], v[216:217]
	v_pk_add_f32 v[220:221], v[220:221], v[250:251]
	ds_read_b128 v[248:251], v246 offset:3568
	s_waitcnt lgkmcnt(3)
	v_lshlrev_b32_e32 v216, 16, v252
	v_and_b32_e32 v217, 0xffff0000, v252
	v_lshlrev_b32_e32 v252, 16, v253
	v_and_b32_e32 v253, 0xffff0000, v253
	v_pk_add_f32 v[106:107], v[106:107], v[216:217]
	v_pk_add_f32 v[108:109], v[108:109], v[252:253]
	v_lshlrev_b32_e32 v216, 16, v254
	v_and_b32_e32 v217, 0xffff0000, v254
	v_lshlrev_b32_e32 v254, 16, v255
	v_and_b32_e32 v255, 0xffff0000, v255
	v_pk_add_f32 v[218:219], v[218:219], v[216:217]
	v_pk_add_f32 v[220:221], v[220:221], v[254:255]
	ds_read_b128 v[252:255], v246 offset:3296
	v_fma_f32 v106, v159, v106, -v98
	v_fma_f32 v107, v159, v107, -v99
	v_fma_f32 v108, v159, v108, -v100
	v_fma_f32 v109, v159, v109, -v101
	v_fma_f32 v218, v159, v218, -v102
	v_fma_f32 v219, v159, v219, -v103
	v_fma_f32 v220, v159, v220, -v104
	v_fma_f32 v221, v159, v221, -v105
	v_cvt_pk_bf16_f32 v106, v106, v107
	v_cvt_pk_bf16_f32 v107, v108, v109
	v_cvt_pk_bf16_f32 v108, v218, v219
	v_cvt_pk_bf16_f32 v109, v220, v221
	s_and_saveexec_b64 s[28:29], s[6:7]
	s_cbranch_execz .Lpu1_0
	global_store_dwordx4 v[192:193], v[98:101], off offset:0
	global_store_dwordx4 v[192:193], v[102:105], off offset:16
.Lpu1_0:
	s_or_b64 exec, exec, s[28:29]
	s_waitcnt vmcnt(8)
	v_mfma_f32_32x32x16_bf16 v[2:17], v[106:109], v[70:73], v[2:17]
	v_mfma_f32_32x32x16_bf16 v[18:33], v[106:109], v[74:77], v[18:33]
	v_mfma_f32_32x32x16_bf16 v[34:49], v[106:109], v[78:81], v[34:49]
	v_mfma_f32_32x32x16_bf16 v[50:65], v[106:109], v[66:69], v[50:65]
	global_load_dwordx4 v[70:73], v[112:113], off offset:1536
	global_load_dwordx4 v[74:77], v[114:115], off offset:1536
	global_load_dwordx4 v[78:81], v[116:117], off offset:1536
	global_load_dwordx4 v[66:69], v[118:119], off offset:1536
	s_waitcnt lgkmcnt(3)
	v_lshlrev_b32_e32 v98, 16, v238
	v_and_b32_e32 v99, 0xffff0000, v238
	v_lshlrev_b32_e32 v100, 16, v239
	v_and_b32_e32 v101, 0xffff0000, v239
	v_lshlrev_b32_e32 v102, 16, v240
	v_and_b32_e32 v103, 0xffff0000, v240
	v_lshlrev_b32_e32 v104, 16, v241
	v_and_b32_e32 v105, 0xffff0000, v241
	ds_read_b128 v[238:241], v246 offset:3024
	s_waitcnt lgkmcnt(3)
	v_lshlrev_b32_e32 v216, 16, v242
	v_and_b32_e32 v217, 0xffff0000, v242
	v_lshlrev_b32_e32 v242, 16, v243
	v_and_b32_e32 v243, 0xffff0000, v243
	v_pk_add_f32 v[106:107], v[98:99], v[216:217]
	v_pk_add_f32 v[108:109], v[100:101], v[242:243]
	v_lshlrev_b32_e32 v216, 16, v244
	v_and_b32_e32 v217, 0xffff0000, v244
	v_lshlrev_b32_e32 v244, 16, v245
	v_and_b32_e32 v245, 0xffff0000, v245
	v_pk_add_f32 v[218:219], v[102:103], v[216:217]
	v_pk_add_f32 v[220:221], v[104:105], v[244:245]
	ds_read_b128 v[242:245], v246 offset:2752
	s_waitcnt lgkmcnt(3)
	v_lshlrev_b32_e32 v216, 16, v248
	v_and_b32_e32 v217, 0xffff0000, v248
	v_lshlrev_b32_e32 v248, 16, v249
	v_and_b32_e32 v249, 0xffff0000, v249
	v_pk_add_f32 v[106:107], v[106:107], v[216:217]
	v_pk_add_f32 v[108:109], v[108:109], v[248:249]
	v_lshlrev_b32_e32 v216, 16, v250
	v_and_b32_e32 v217, 0xffff0000, v250
	v_lshlrev_b32_e32 v250, 16, v251
	v_and_b32_e32 v251, 0xffff0000, v251
	v_pk_add_f32 v[218:219], v[218:219], v[216:217]
	v_pk_add_f32 v[220:221], v[220:221], v[250:251]
	ds_read_b128 v[248:251], v246 offset:2480
	s_waitcnt lgkmcnt(3)
	v_lshlrev_b32_e32 v216, 16, v252
	v_and_b32_e32 v217, 0xffff0000, v252
	v_lshlrev_b32_e32 v252, 16, v253
	v_and_b32_e32 v253, 0xffff0000, v253
	v_pk_add_f32 v[106:107], v[106:107], v[216:217]
	v_pk_add_f32 v[108:109], v[108:109], v[252:253]
	v_lshlrev_b32_e32 v216, 16, v254
	v_and_b32_e32 v217, 0xffff0000, v254
	v_lshlrev_b32_e32 v254, 16, v255
	v_and_b32_e32 v255, 0xffff0000, v255
	v_pk_add_f32 v[218:219], v[218:219], v[216:217]
	v_pk_add_f32 v[220:221], v[220:221], v[254:255]
	ds_read_b128 v[252:255], v246 offset:2208
	s_waitcnt lgkmcnt(3)
	v_lshlrev_b32_e32 v216, 16, v238
	v_and_b32_e32 v217, 0xffff0000, v238
	v_lshlrev_b32_e32 v238, 16, v239
	v_and_b32_e32 v239, 0xffff0000, v239
	v_pk_add_f32 v[106:107], v[106:107], v[216:217]
	v_pk_add_f32 v[108:109], v[108:109], v[238:239]
	v_lshlrev_b32_e32 v216, 16, v240
	v_and_b32_e32 v217, 0xffff0000, v240
	v_lshlrev_b32_e32 v240, 16, v241
	v_and_b32_e32 v241, 0xffff0000, v241
	v_pk_add_f32 v[218:219], v[218:219], v[216:217]
	v_pk_add_f32 v[220:221], v[220:221], v[240:241]
	ds_read_b128 v[238:241], v246 offset:4144
	s_waitcnt lgkmcnt(3)
	v_lshlrev_b32_e32 v216, 16, v242
	v_and_b32_e32 v217, 0xffff0000, v242
	v_lshlrev_b32_e32 v242, 16, v243
	v_and_b32_e32 v243, 0xffff0000, v243
	v_pk_add_f32 v[106:107], v[106:107], v[216:217]
	v_pk_add_f32 v[108:109], v[108:109], v[242:243]
	v_lshlrev_b32_e32 v216, 16, v244
	v_and_b32_e32 v217, 0xffff0000, v244
	v_lshlrev_b32_e32 v244, 16, v245
	v_and_b32_e32 v245, 0xffff0000, v245
	v_pk_add_f32 v[218:219], v[218:219], v[216:217]
	v_pk_add_f32 v[220:221], v[220:221], v[244:245]
	ds_read_b128 v[242:245], v246 offset:3872
	s_waitcnt lgkmcnt(3)
	v_lshlrev_b32_e32 v216, 16, v248
	v_and_b32_e32 v217, 0xffff0000, v248
	v_lshlrev_b32_e32 v248, 16, v249
	v_and_b32_e32 v249, 0xffff0000, v249
	v_pk_add_f32 v[106:107], v[106:107], v[216:217]
	v_pk_add_f32 v[108:109], v[108:109], v[248:249]
	v_lshlrev_b32_e32 v216, 16, v250
	v_and_b32_e32 v217, 0xffff0000, v250
	v_lshlrev_b32_e32 v250, 16, v251
	v_and_b32_e32 v251, 0xffff0000, v251
	v_pk_add_f32 v[218:219], v[218:219], v[216:217]
	v_pk_add_f32 v[220:221], v[220:221], v[250:251]
	ds_read_b128 v[248:251], v246 offset:3600
	s_waitcnt lgkmcnt(3)
	v_lshlrev_b32_e32 v216, 16, v252
	v_and_b32_e32 v217, 0xffff0000, v252
	v_lshlrev_b32_e32 v252, 16, v253
	v_and_b32_e32 v253, 0xffff0000, v253
	v_pk_add_f32 v[106:107], v[106:107], v[216:217]
	v_pk_add_f32 v[108:109], v[108:109], v[252:253]
	v_lshlrev_b32_e32 v216, 16, v254
	v_and_b32_e32 v217, 0xffff0000, v254
	v_lshlrev_b32_e32 v254, 16, v255
	v_and_b32_e32 v255, 0xffff0000, v255
	v_pk_add_f32 v[218:219], v[218:219], v[216:217]
	v_pk_add_f32 v[220:221], v[220:221], v[254:255]
	ds_read_b128 v[252:255], v246 offset:3328
	v_fma_f32 v106, v159, v106, -v98
	v_fma_f32 v107, v159, v107, -v99
	v_fma_f32 v108, v159, v108, -v100
	v_fma_f32 v109, v159, v109, -v101
	v_fma_f32 v218, v159, v218, -v102
	v_fma_f32 v219, v159, v219, -v103
	v_fma_f32 v220, v159, v220, -v104
	v_fma_f32 v221, v159, v221, -v105
	v_cvt_pk_bf16_f32 v106, v106, v107
	v_cvt_pk_bf16_f32 v107, v108, v109
	v_cvt_pk_bf16_f32 v108, v218, v219
	v_cvt_pk_bf16_f32 v109, v220, v221
	s_and_saveexec_b64 s[28:29], s[6:7]
	s_cbranch_execz .Lpu1_1
	global_store_dwordx4 v[192:193], v[98:101], off offset:64
	global_store_dwordx4 v[192:193], v[102:105], off offset:80
.Lpu1_1:
	s_or_b64 exec, exec, s[28:29]
	s_waitcnt vmcnt(8)
	v_mfma_f32_32x32x16_bf16 v[2:17], v[106:109], v[82:85], v[2:17]
	v_mfma_f32_32x32x16_bf16 v[18:33], v[106:109], v[86:89], v[18:33]
	v_mfma_f32_32x32x16_bf16 v[34:49], v[106:109], v[90:93], v[34:49]
	v_mfma_f32_32x32x16_bf16 v[50:65], v[106:109], v[94:97], v[50:65]
	global_load_dwordx4 v[82:85], v[112:113], off offset:2048
	global_load_dwordx4 v[86:89], v[114:115], off offset:2048
	global_load_dwordx4 v[90:93], v[116:117], off offset:2048
	global_load_dwordx4 v[94:97], v[118:119], off offset:2048
	s_waitcnt lgkmcnt(3)
	v_lshlrev_b32_e32 v98, 16, v238
	v_and_b32_e32 v99, 0xffff0000, v238
	v_lshlrev_b32_e32 v100, 16, v239
	v_and_b32_e32 v101, 0xffff0000, v239
	v_lshlrev_b32_e32 v102, 16, v240
	v_and_b32_e32 v103, 0xffff0000, v240
	v_lshlrev_b32_e32 v104, 16, v241
	v_and_b32_e32 v105, 0xffff0000, v241
	ds_read_b128 v[238:241], v246 offset:3056
	s_waitcnt lgkmcnt(3)
	v_lshlrev_b32_e32 v216, 16, v242
	v_and_b32_e32 v217, 0xffff0000, v242
	v_lshlrev_b32_e32 v242, 16, v243
	v_and_b32_e32 v243, 0xffff0000, v243
	v_pk_add_f32 v[106:107], v[98:99], v[216:217]
	v_pk_add_f32 v[108:109], v[100:101], v[242:243]
	v_lshlrev_b32_e32 v216, 16, v244
	v_and_b32_e32 v217, 0xffff0000, v244
	v_lshlrev_b32_e32 v244, 16, v245
	v_and_b32_e32 v245, 0xffff0000, v245
	v_pk_add_f32 v[218:219], v[102:103], v[216:217]
	v_pk_add_f32 v[220:221], v[104:105], v[244:245]
	ds_read_b128 v[242:245], v246 offset:2784
	s_waitcnt lgkmcnt(3)
	v_lshlrev_b32_e32 v216, 16, v248
	v_and_b32_e32 v217, 0xffff0000, v248
	v_lshlrev_b32_e32 v248, 16, v249
	v_and_b32_e32 v249, 0xffff0000, v249
	v_pk_add_f32 v[106:107], v[106:107], v[216:217]
	v_pk_add_f32 v[108:109], v[108:109], v[248:249]
	v_lshlrev_b32_e32 v216, 16, v250
	v_and_b32_e32 v217, 0xffff0000, v250
	v_lshlrev_b32_e32 v250, 16, v251
	v_and_b32_e32 v251, 0xffff0000, v251
	v_pk_add_f32 v[218:219], v[218:219], v[216:217]
	v_pk_add_f32 v[220:221], v[220:221], v[250:251]
	ds_read_b128 v[248:251], v246 offset:2512
	s_waitcnt lgkmcnt(3)
	v_lshlrev_b32_e32 v216, 16, v252
	v_and_b32_e32 v217, 0xffff0000, v252
	v_lshlrev_b32_e32 v252, 16, v253
	v_and_b32_e32 v253, 0xffff0000, v253
	v_pk_add_f32 v[106:107], v[106:107], v[216:217]
	v_pk_add_f32 v[108:109], v[108:109], v[252:253]
	v_lshlrev_b32_e32 v216, 16, v254
	v_and_b32_e32 v217, 0xffff0000, v254
	v_lshlrev_b32_e32 v254, 16, v255
	v_and_b32_e32 v255, 0xffff0000, v255
	v_pk_add_f32 v[218:219], v[218:219], v[216:217]
	v_pk_add_f32 v[220:221], v[220:221], v[254:255]
	ds_read_b128 v[252:255], v246 offset:2240
	s_waitcnt lgkmcnt(3)
	v_lshlrev_b32_e32 v216, 16, v238
	v_and_b32_e32 v217, 0xffff0000, v238
	v_lshlrev_b32_e32 v238, 16, v239
	v_and_b32_e32 v239, 0xffff0000, v239
	v_pk_add_f32 v[106:107], v[106:107], v[216:217]
	v_pk_add_f32 v[108:109], v[108:109], v[238:239]
	v_lshlrev_b32_e32 v216, 16, v240
	v_and_b32_e32 v217, 0xffff0000, v240
	v_lshlrev_b32_e32 v240, 16, v241
	v_and_b32_e32 v241, 0xffff0000, v241
	v_pk_add_f32 v[218:219], v[218:219], v[216:217]
	v_pk_add_f32 v[220:221], v[220:221], v[240:241]
	ds_read_b128 v[238:241], v246 offset:4176
	s_waitcnt lgkmcnt(3)
	v_lshlrev_b32_e32 v216, 16, v242
	v_and_b32_e32 v217, 0xffff0000, v242
	v_lshlrev_b32_e32 v242, 16, v243
	v_and_b32_e32 v243, 0xffff0000, v243
	v_pk_add_f32 v[106:107], v[106:107], v[216:217]
	v_pk_add_f32 v[108:109], v[108:109], v[242:243]
	v_lshlrev_b32_e32 v216, 16, v244
	v_and_b32_e32 v217, 0xffff0000, v244
	v_lshlrev_b32_e32 v244, 16, v245
	v_and_b32_e32 v245, 0xffff0000, v245
	v_pk_add_f32 v[218:219], v[218:219], v[216:217]
	v_pk_add_f32 v[220:221], v[220:221], v[244:245]
	ds_read_b128 v[242:245], v246 offset:3904
	s_waitcnt lgkmcnt(3)
	v_lshlrev_b32_e32 v216, 16, v248
	v_and_b32_e32 v217, 0xffff0000, v248
	v_lshlrev_b32_e32 v248, 16, v249
	v_and_b32_e32 v249, 0xffff0000, v249
	v_pk_add_f32 v[106:107], v[106:107], v[216:217]
	v_pk_add_f32 v[108:109], v[108:109], v[248:249]
	v_lshlrev_b32_e32 v216, 16, v250
	v_and_b32_e32 v217, 0xffff0000, v250
	v_lshlrev_b32_e32 v250, 16, v251
	v_and_b32_e32 v251, 0xffff0000, v251
	v_pk_add_f32 v[218:219], v[218:219], v[216:217]
	v_pk_add_f32 v[220:221], v[220:221], v[250:251]
	ds_read_b128 v[248:251], v246 offset:3632
	s_waitcnt lgkmcnt(3)
	v_lshlrev_b32_e32 v216, 16, v252
	v_and_b32_e32 v217, 0xffff0000, v252
	v_lshlrev_b32_e32 v252, 16, v253
	v_and_b32_e32 v253, 0xffff0000, v253
	v_pk_add_f32 v[106:107], v[106:107], v[216:217]
	v_pk_add_f32 v[108:109], v[108:109], v[252:253]
	v_lshlrev_b32_e32 v216, 16, v254
	v_and_b32_e32 v217, 0xffff0000, v254
	v_lshlrev_b32_e32 v254, 16, v255
	v_and_b32_e32 v255, 0xffff0000, v255
	v_pk_add_f32 v[218:219], v[218:219], v[216:217]
	v_pk_add_f32 v[220:221], v[220:221], v[254:255]
	ds_read_b128 v[252:255], v246 offset:3360
	v_fma_f32 v106, v159, v106, -v98
	v_fma_f32 v107, v159, v107, -v99
	v_fma_f32 v108, v159, v108, -v100
	v_fma_f32 v109, v159, v109, -v101
	v_fma_f32 v218, v159, v218, -v102
	v_fma_f32 v219, v159, v219, -v103
	v_fma_f32 v220, v159, v220, -v104
	v_fma_f32 v221, v159, v221, -v105
	v_cvt_pk_bf16_f32 v106, v106, v107
	v_cvt_pk_bf16_f32 v107, v108, v109
	v_cvt_pk_bf16_f32 v108, v218, v219
	v_cvt_pk_bf16_f32 v109, v220, v221
	s_and_saveexec_b64 s[28:29], s[6:7]
	s_cbranch_execz .Lpu1_2
	global_store_dwordx4 v[192:193], v[98:101], off offset:128
	global_store_dwordx4 v[192:193], v[102:105], off offset:144
.Lpu1_2:
	s_or_b64 exec, exec, s[28:29]
	s_waitcnt vmcnt(8)
	v_mfma_f32_32x32x16_bf16 v[2:17], v[106:109], v[222:225], v[2:17]
	v_mfma_f32_32x32x16_bf16 v[18:33], v[106:109], v[226:229], v[18:33]
	v_mfma_f32_32x32x16_bf16 v[34:49], v[106:109], v[230:233], v[34:49]
	v_mfma_f32_32x32x16_bf16 v[50:65], v[106:109], v[234:237], v[50:65]
	global_load_dwordx4 v[222:225], v[112:113], off offset:2560
	global_load_dwordx4 v[226:229], v[114:115], off offset:2560
	global_load_dwordx4 v[230:233], v[116:117], off offset:2560
	global_load_dwordx4 v[234:237], v[118:119], off offset:2560
	s_waitcnt lgkmcnt(3)
	v_lshlrev_b32_e32 v98, 16, v238
	v_and_b32_e32 v99, 0xffff0000, v238
	v_lshlrev_b32_e32 v100, 16, v239
	v_and_b32_e32 v101, 0xffff0000, v239
	v_lshlrev_b32_e32 v102, 16, v240
	v_and_b32_e32 v103, 0xffff0000, v240
	v_lshlrev_b32_e32 v104, 16, v241
	v_and_b32_e32 v105, 0xffff0000, v241
	ds_read_b128 v[238:241], v246 offset:3088
	s_waitcnt lgkmcnt(3)
	v_lshlrev_b32_e32 v216, 16, v242
	v_and_b32_e32 v217, 0xffff0000, v242
	v_lshlrev_b32_e32 v242, 16, v243
	v_and_b32_e32 v243, 0xffff0000, v243
	v_pk_add_f32 v[106:107], v[98:99], v[216:217]
	v_pk_add_f32 v[108:109], v[100:101], v[242:243]
	v_lshlrev_b32_e32 v216, 16, v244
	v_and_b32_e32 v217, 0xffff0000, v244
	v_lshlrev_b32_e32 v244, 16, v245
	v_and_b32_e32 v245, 0xffff0000, v245
	v_pk_add_f32 v[218:219], v[102:103], v[216:217]
	v_pk_add_f32 v[220:221], v[104:105], v[244:245]
	ds_read_b128 v[242:245], v246 offset:2816
	s_waitcnt lgkmcnt(3)
	v_lshlrev_b32_e32 v216, 16, v248
	v_and_b32_e32 v217, 0xffff0000, v248
	v_lshlrev_b32_e32 v248, 16, v249
	v_and_b32_e32 v249, 0xffff0000, v249
	v_pk_add_f32 v[106:107], v[106:107], v[216:217]
	v_pk_add_f32 v[108:109], v[108:109], v[248:249]
	v_lshlrev_b32_e32 v216, 16, v250
	v_and_b32_e32 v217, 0xffff0000, v250
	v_lshlrev_b32_e32 v250, 16, v251
	v_and_b32_e32 v251, 0xffff0000, v251
	v_pk_add_f32 v[218:219], v[218:219], v[216:217]
	v_pk_add_f32 v[220:221], v[220:221], v[250:251]
	ds_read_b128 v[248:251], v246 offset:2544
	s_waitcnt lgkmcnt(3)
	v_lshlrev_b32_e32 v216, 16, v252
	v_and_b32_e32 v217, 0xffff0000, v252
	v_lshlrev_b32_e32 v252, 16, v253
	v_and_b32_e32 v253, 0xffff0000, v253
	v_pk_add_f32 v[106:107], v[106:107], v[216:217]
	v_pk_add_f32 v[108:109], v[108:109], v[252:253]
	v_lshlrev_b32_e32 v216, 16, v254
	v_and_b32_e32 v217, 0xffff0000, v254
	v_lshlrev_b32_e32 v254, 16, v255
	v_and_b32_e32 v255, 0xffff0000, v255
	v_pk_add_f32 v[218:219], v[218:219], v[216:217]
	v_pk_add_f32 v[220:221], v[220:221], v[254:255]
	ds_read_b128 v[252:255], v246 offset:2272
	s_waitcnt lgkmcnt(3)
	v_lshlrev_b32_e32 v216, 16, v238
	v_and_b32_e32 v217, 0xffff0000, v238
	v_lshlrev_b32_e32 v238, 16, v239
	v_and_b32_e32 v239, 0xffff0000, v239
	v_pk_add_f32 v[106:107], v[106:107], v[216:217]
	v_pk_add_f32 v[108:109], v[108:109], v[238:239]
	v_lshlrev_b32_e32 v216, 16, v240
	v_and_b32_e32 v217, 0xffff0000, v240
	v_lshlrev_b32_e32 v240, 16, v241
	v_and_b32_e32 v241, 0xffff0000, v241
	v_pk_add_f32 v[218:219], v[218:219], v[216:217]
	v_pk_add_f32 v[220:221], v[220:221], v[240:241]
	ds_read_b128 v[238:241], v246 offset:4208
	s_waitcnt lgkmcnt(3)
	v_lshlrev_b32_e32 v216, 16, v242
	v_and_b32_e32 v217, 0xffff0000, v242
	v_lshlrev_b32_e32 v242, 16, v243
	v_and_b32_e32 v243, 0xffff0000, v243
	v_pk_add_f32 v[106:107], v[106:107], v[216:217]
	v_pk_add_f32 v[108:109], v[108:109], v[242:243]
	v_lshlrev_b32_e32 v216, 16, v244
	v_and_b32_e32 v217, 0xffff0000, v244
	v_lshlrev_b32_e32 v244, 16, v245
	v_and_b32_e32 v245, 0xffff0000, v245
	v_pk_add_f32 v[218:219], v[218:219], v[216:217]
	v_pk_add_f32 v[220:221], v[220:221], v[244:245]
	ds_read_b128 v[242:245], v246 offset:3936
	s_waitcnt lgkmcnt(3)
	v_lshlrev_b32_e32 v216, 16, v248
	v_and_b32_e32 v217, 0xffff0000, v248
	v_lshlrev_b32_e32 v248, 16, v249
	v_and_b32_e32 v249, 0xffff0000, v249
	v_pk_add_f32 v[106:107], v[106:107], v[216:217]
	v_pk_add_f32 v[108:109], v[108:109], v[248:249]
	v_lshlrev_b32_e32 v216, 16, v250
	v_and_b32_e32 v217, 0xffff0000, v250
	v_lshlrev_b32_e32 v250, 16, v251
	v_and_b32_e32 v251, 0xffff0000, v251
	v_pk_add_f32 v[218:219], v[218:219], v[216:217]
	v_pk_add_f32 v[220:221], v[220:221], v[250:251]
	ds_read_b128 v[248:251], v246 offset:3664
	s_waitcnt lgkmcnt(3)
	v_lshlrev_b32_e32 v216, 16, v252
	v_and_b32_e32 v217, 0xffff0000, v252
	v_lshlrev_b32_e32 v252, 16, v253
	v_and_b32_e32 v253, 0xffff0000, v253
	v_pk_add_f32 v[106:107], v[106:107], v[216:217]
	v_pk_add_f32 v[108:109], v[108:109], v[252:253]
	v_lshlrev_b32_e32 v216, 16, v254
	v_and_b32_e32 v217, 0xffff0000, v254
	v_lshlrev_b32_e32 v254, 16, v255
	v_and_b32_e32 v255, 0xffff0000, v255
	v_pk_add_f32 v[218:219], v[218:219], v[216:217]
	v_pk_add_f32 v[220:221], v[220:221], v[254:255]
	ds_read_b128 v[252:255], v246 offset:3392
	v_fma_f32 v106, v159, v106, -v98
	v_fma_f32 v107, v159, v107, -v99
	v_fma_f32 v108, v159, v108, -v100
	v_fma_f32 v109, v159, v109, -v101
	v_fma_f32 v218, v159, v218, -v102
	v_fma_f32 v219, v159, v219, -v103
	v_fma_f32 v220, v159, v220, -v104
	v_fma_f32 v221, v159, v221, -v105
	v_cvt_pk_bf16_f32 v106, v106, v107
	v_cvt_pk_bf16_f32 v107, v108, v109
	v_cvt_pk_bf16_f32 v108, v218, v219
	v_cvt_pk_bf16_f32 v109, v220, v221
	s_and_saveexec_b64 s[28:29], s[6:7]
	s_cbranch_execz .Lpu1_3
	global_store_dwordx4 v[192:193], v[98:101], off offset:192
	global_store_dwordx4 v[192:193], v[102:105], off offset:208
.Lpu1_3:
	s_or_b64 exec, exec, s[28:29]
	s_waitcnt vmcnt(8)
	v_mfma_f32_32x32x16_bf16 v[2:17], v[106:109], v[70:73], v[2:17]
	v_mfma_f32_32x32x16_bf16 v[18:33], v[106:109], v[74:77], v[18:33]
	v_mfma_f32_32x32x16_bf16 v[34:49], v[106:109], v[78:81], v[34:49]
	v_mfma_f32_32x32x16_bf16 v[50:65], v[106:109], v[66:69], v[50:65]
	global_load_dwordx4 v[70:73], v[112:113], off offset:3072
	global_load_dwordx4 v[74:77], v[114:115], off offset:3072
	global_load_dwordx4 v[78:81], v[116:117], off offset:3072
	global_load_dwordx4 v[66:69], v[118:119], off offset:3072
	s_waitcnt lgkmcnt(3)
	v_lshlrev_b32_e32 v98, 16, v238
	v_and_b32_e32 v99, 0xffff0000, v238
	v_lshlrev_b32_e32 v100, 16, v239
	v_and_b32_e32 v101, 0xffff0000, v239
	v_lshlrev_b32_e32 v102, 16, v240
	v_and_b32_e32 v103, 0xffff0000, v240
	v_lshlrev_b32_e32 v104, 16, v241
	v_and_b32_e32 v105, 0xffff0000, v241
	ds_read_b128 v[238:241], v246 offset:3120
	s_waitcnt lgkmcnt(3)
	v_lshlrev_b32_e32 v216, 16, v242
	v_and_b32_e32 v217, 0xffff0000, v242
	v_lshlrev_b32_e32 v242, 16, v243
	v_and_b32_e32 v243, 0xffff0000, v243
	v_pk_add_f32 v[106:107], v[98:99], v[216:217]
	v_pk_add_f32 v[108:109], v[100:101], v[242:243]
	v_lshlrev_b32_e32 v216, 16, v244
	v_and_b32_e32 v217, 0xffff0000, v244
	v_lshlrev_b32_e32 v244, 16, v245
	v_and_b32_e32 v245, 0xffff0000, v245
	v_pk_add_f32 v[218:219], v[102:103], v[216:217]
	v_pk_add_f32 v[220:221], v[104:105], v[244:245]
	ds_read_b128 v[242:245], v246 offset:2848
	s_waitcnt lgkmcnt(3)
	v_lshlrev_b32_e32 v216, 16, v248
	v_and_b32_e32 v217, 0xffff0000, v248
	v_lshlrev_b32_e32 v248, 16, v249
	v_and_b32_e32 v249, 0xffff0000, v249
	v_pk_add_f32 v[106:107], v[106:107], v[216:217]
	v_pk_add_f32 v[108:109], v[108:109], v[248:249]
	v_lshlrev_b32_e32 v216, 16, v250
	v_and_b32_e32 v217, 0xffff0000, v250
	v_lshlrev_b32_e32 v250, 16, v251
	v_and_b32_e32 v251, 0xffff0000, v251
	v_pk_add_f32 v[218:219], v[218:219], v[216:217]
	v_pk_add_f32 v[220:221], v[220:221], v[250:251]
	ds_read_b128 v[248:251], v246 offset:2576
	s_waitcnt lgkmcnt(3)
	v_lshlrev_b32_e32 v216, 16, v252
	v_and_b32_e32 v217, 0xffff0000, v252
	v_lshlrev_b32_e32 v252, 16, v253
	v_and_b32_e32 v253, 0xffff0000, v253
	v_pk_add_f32 v[106:107], v[106:107], v[216:217]
	v_pk_add_f32 v[108:109], v[108:109], v[252:253]
	v_lshlrev_b32_e32 v216, 16, v254
	v_and_b32_e32 v217, 0xffff0000, v254
	v_lshlrev_b32_e32 v254, 16, v255
	v_and_b32_e32 v255, 0xffff0000, v255
	v_pk_add_f32 v[218:219], v[218:219], v[216:217]
	v_pk_add_f32 v[220:221], v[220:221], v[254:255]
	ds_read_b128 v[252:255], v246 offset:2304
	s_waitcnt lgkmcnt(3)
	v_lshlrev_b32_e32 v216, 16, v238
	v_and_b32_e32 v217, 0xffff0000, v238
	v_lshlrev_b32_e32 v238, 16, v239
	v_and_b32_e32 v239, 0xffff0000, v239
	v_pk_add_f32 v[106:107], v[106:107], v[216:217]
	v_pk_add_f32 v[108:109], v[108:109], v[238:239]
	v_lshlrev_b32_e32 v216, 16, v240
	v_and_b32_e32 v217, 0xffff0000, v240
	v_lshlrev_b32_e32 v240, 16, v241
	v_and_b32_e32 v241, 0xffff0000, v241
	v_pk_add_f32 v[218:219], v[218:219], v[216:217]
	v_pk_add_f32 v[220:221], v[220:221], v[240:241]
	ds_read_b128 v[238:241], v246 offset:4240
	s_waitcnt lgkmcnt(3)
	v_lshlrev_b32_e32 v216, 16, v242
	v_and_b32_e32 v217, 0xffff0000, v242
	v_lshlrev_b32_e32 v242, 16, v243
	v_and_b32_e32 v243, 0xffff0000, v243
	v_pk_add_f32 v[106:107], v[106:107], v[216:217]
	v_pk_add_f32 v[108:109], v[108:109], v[242:243]
	v_lshlrev_b32_e32 v216, 16, v244
	v_and_b32_e32 v217, 0xffff0000, v244
	v_lshlrev_b32_e32 v244, 16, v245
	v_and_b32_e32 v245, 0xffff0000, v245
	v_pk_add_f32 v[218:219], v[218:219], v[216:217]
	v_pk_add_f32 v[220:221], v[220:221], v[244:245]
	ds_read_b128 v[242:245], v246 offset:3968
	s_waitcnt lgkmcnt(3)
	v_lshlrev_b32_e32 v216, 16, v248
	v_and_b32_e32 v217, 0xffff0000, v248
	v_lshlrev_b32_e32 v248, 16, v249
	v_and_b32_e32 v249, 0xffff0000, v249
	v_pk_add_f32 v[106:107], v[106:107], v[216:217]
	v_pk_add_f32 v[108:109], v[108:109], v[248:249]
	v_lshlrev_b32_e32 v216, 16, v250
	v_and_b32_e32 v217, 0xffff0000, v250
	v_lshlrev_b32_e32 v250, 16, v251
	v_and_b32_e32 v251, 0xffff0000, v251
	v_pk_add_f32 v[218:219], v[218:219], v[216:217]
	v_pk_add_f32 v[220:221], v[220:221], v[250:251]
	ds_read_b128 v[248:251], v246 offset:3696
	s_waitcnt lgkmcnt(3)
	v_lshlrev_b32_e32 v216, 16, v252
	v_and_b32_e32 v217, 0xffff0000, v252
	v_lshlrev_b32_e32 v252, 16, v253
	v_and_b32_e32 v253, 0xffff0000, v253
	v_pk_add_f32 v[106:107], v[106:107], v[216:217]
	v_pk_add_f32 v[108:109], v[108:109], v[252:253]
	v_lshlrev_b32_e32 v216, 16, v254
	v_and_b32_e32 v217, 0xffff0000, v254
	v_lshlrev_b32_e32 v254, 16, v255
	v_and_b32_e32 v255, 0xffff0000, v255
	v_pk_add_f32 v[218:219], v[218:219], v[216:217]
	v_pk_add_f32 v[220:221], v[220:221], v[254:255]
	ds_read_b128 v[252:255], v246 offset:3424
	v_fma_f32 v106, v159, v106, -v98
	v_fma_f32 v107, v159, v107, -v99
	v_fma_f32 v108, v159, v108, -v100
	v_fma_f32 v109, v159, v109, -v101
	v_fma_f32 v218, v159, v218, -v102
	v_fma_f32 v219, v159, v219, -v103
	v_fma_f32 v220, v159, v220, -v104
	v_fma_f32 v221, v159, v221, -v105
	v_cvt_pk_bf16_f32 v106, v106, v107
	v_cvt_pk_bf16_f32 v107, v108, v109
	v_cvt_pk_bf16_f32 v108, v218, v219
	v_cvt_pk_bf16_f32 v109, v220, v221
	s_and_saveexec_b64 s[28:29], s[6:7]
	s_cbranch_execz .Lpu1_4
	global_store_dwordx4 v[192:193], v[98:101], off offset:256
	global_store_dwordx4 v[192:193], v[102:105], off offset:272
.Lpu1_4:
	s_or_b64 exec, exec, s[28:29]
	s_waitcnt vmcnt(8)
	v_mfma_f32_32x32x16_bf16 v[2:17], v[106:109], v[82:85], v[2:17]
	v_mfma_f32_32x32x16_bf16 v[18:33], v[106:109], v[86:89], v[18:33]
	v_mfma_f32_32x32x16_bf16 v[34:49], v[106:109], v[90:93], v[34:49]
	v_mfma_f32_32x32x16_bf16 v[50:65], v[106:109], v[94:97], v[50:65]
	global_load_dwordx4 v[82:85], v[112:113], off offset:3584
	global_load_dwordx4 v[86:89], v[114:115], off offset:3584
	global_load_dwordx4 v[90:93], v[116:117], off offset:3584
	global_load_dwordx4 v[94:97], v[118:119], off offset:3584
	s_waitcnt lgkmcnt(3)
	v_lshlrev_b32_e32 v98, 16, v238
	v_and_b32_e32 v99, 0xffff0000, v238
	v_lshlrev_b32_e32 v100, 16, v239
	v_and_b32_e32 v101, 0xffff0000, v239
	v_lshlrev_b32_e32 v102, 16, v240
	v_and_b32_e32 v103, 0xffff0000, v240
	v_lshlrev_b32_e32 v104, 16, v241
	v_and_b32_e32 v105, 0xffff0000, v241
	ds_read_b128 v[238:241], v246 offset:3152
	s_waitcnt lgkmcnt(3)
	v_lshlrev_b32_e32 v216, 16, v242
	v_and_b32_e32 v217, 0xffff0000, v242
	v_lshlrev_b32_e32 v242, 16, v243
	v_and_b32_e32 v243, 0xffff0000, v243
	v_pk_add_f32 v[106:107], v[98:99], v[216:217]
	v_pk_add_f32 v[108:109], v[100:101], v[242:243]
	v_lshlrev_b32_e32 v216, 16, v244
	v_and_b32_e32 v217, 0xffff0000, v244
	v_lshlrev_b32_e32 v244, 16, v245
	v_and_b32_e32 v245, 0xffff0000, v245
	v_pk_add_f32 v[218:219], v[102:103], v[216:217]
	v_pk_add_f32 v[220:221], v[104:105], v[244:245]
	ds_read_b128 v[242:245], v246 offset:2880
	s_waitcnt lgkmcnt(3)
	v_lshlrev_b32_e32 v216, 16, v248
	v_and_b32_e32 v217, 0xffff0000, v248
	v_lshlrev_b32_e32 v248, 16, v249
	v_and_b32_e32 v249, 0xffff0000, v249
	v_pk_add_f32 v[106:107], v[106:107], v[216:217]
	v_pk_add_f32 v[108:109], v[108:109], v[248:249]
	v_lshlrev_b32_e32 v216, 16, v250
	v_and_b32_e32 v217, 0xffff0000, v250
	v_lshlrev_b32_e32 v250, 16, v251
	v_and_b32_e32 v251, 0xffff0000, v251
	v_pk_add_f32 v[218:219], v[218:219], v[216:217]
	v_pk_add_f32 v[220:221], v[220:221], v[250:251]
	ds_read_b128 v[248:251], v246 offset:2608
	s_waitcnt lgkmcnt(3)
	v_lshlrev_b32_e32 v216, 16, v252
	v_and_b32_e32 v217, 0xffff0000, v252
	v_lshlrev_b32_e32 v252, 16, v253
	v_and_b32_e32 v253, 0xffff0000, v253
	v_pk_add_f32 v[106:107], v[106:107], v[216:217]
	v_pk_add_f32 v[108:109], v[108:109], v[252:253]
	v_lshlrev_b32_e32 v216, 16, v254
	v_and_b32_e32 v217, 0xffff0000, v254
	v_lshlrev_b32_e32 v254, 16, v255
	v_and_b32_e32 v255, 0xffff0000, v255
	v_pk_add_f32 v[218:219], v[218:219], v[216:217]
	v_pk_add_f32 v[220:221], v[220:221], v[254:255]
	ds_read_b128 v[252:255], v246 offset:2336
	s_waitcnt lgkmcnt(3)
	v_lshlrev_b32_e32 v216, 16, v238
	v_and_b32_e32 v217, 0xffff0000, v238
	v_lshlrev_b32_e32 v238, 16, v239
	v_and_b32_e32 v239, 0xffff0000, v239
	v_pk_add_f32 v[106:107], v[106:107], v[216:217]
	v_pk_add_f32 v[108:109], v[108:109], v[238:239]
	v_lshlrev_b32_e32 v216, 16, v240
	v_and_b32_e32 v217, 0xffff0000, v240
	v_lshlrev_b32_e32 v240, 16, v241
	v_and_b32_e32 v241, 0xffff0000, v241
	v_pk_add_f32 v[218:219], v[218:219], v[216:217]
	v_pk_add_f32 v[220:221], v[220:221], v[240:241]
	ds_read_b128 v[238:241], v246 offset:4272
	s_waitcnt lgkmcnt(3)
	v_lshlrev_b32_e32 v216, 16, v242
	v_and_b32_e32 v217, 0xffff0000, v242
	v_lshlrev_b32_e32 v242, 16, v243
	v_and_b32_e32 v243, 0xffff0000, v243
	v_pk_add_f32 v[106:107], v[106:107], v[216:217]
	v_pk_add_f32 v[108:109], v[108:109], v[242:243]
	v_lshlrev_b32_e32 v216, 16, v244
	v_and_b32_e32 v217, 0xffff0000, v244
	v_lshlrev_b32_e32 v244, 16, v245
	v_and_b32_e32 v245, 0xffff0000, v245
	v_pk_add_f32 v[218:219], v[218:219], v[216:217]
	v_pk_add_f32 v[220:221], v[220:221], v[244:245]
	ds_read_b128 v[242:245], v246 offset:4000
	s_waitcnt lgkmcnt(3)
	v_lshlrev_b32_e32 v216, 16, v248
	v_and_b32_e32 v217, 0xffff0000, v248
	v_lshlrev_b32_e32 v248, 16, v249
	v_and_b32_e32 v249, 0xffff0000, v249
	v_pk_add_f32 v[106:107], v[106:107], v[216:217]
	v_pk_add_f32 v[108:109], v[108:109], v[248:249]
	v_lshlrev_b32_e32 v216, 16, v250
	v_and_b32_e32 v217, 0xffff0000, v250
	v_lshlrev_b32_e32 v250, 16, v251
	v_and_b32_e32 v251, 0xffff0000, v251
	v_pk_add_f32 v[218:219], v[218:219], v[216:217]
	v_pk_add_f32 v[220:221], v[220:221], v[250:251]
	ds_read_b128 v[248:251], v246 offset:3728
	s_waitcnt lgkmcnt(3)
	v_lshlrev_b32_e32 v216, 16, v252
	v_and_b32_e32 v217, 0xffff0000, v252
	v_lshlrev_b32_e32 v252, 16, v253
	v_and_b32_e32 v253, 0xffff0000, v253
	v_pk_add_f32 v[106:107], v[106:107], v[216:217]
	v_pk_add_f32 v[108:109], v[108:109], v[252:253]
	v_lshlrev_b32_e32 v216, 16, v254
	v_and_b32_e32 v217, 0xffff0000, v254
	v_lshlrev_b32_e32 v254, 16, v255
	v_and_b32_e32 v255, 0xffff0000, v255
	v_pk_add_f32 v[218:219], v[218:219], v[216:217]
	v_pk_add_f32 v[220:221], v[220:221], v[254:255]
	ds_read_b128 v[252:255], v246 offset:3456
	v_fma_f32 v106, v159, v106, -v98
	v_fma_f32 v107, v159, v107, -v99
	v_fma_f32 v108, v159, v108, -v100
	v_fma_f32 v109, v159, v109, -v101
	v_fma_f32 v218, v159, v218, -v102
	v_fma_f32 v219, v159, v219, -v103
	v_fma_f32 v220, v159, v220, -v104
	v_fma_f32 v221, v159, v221, -v105
	v_cvt_pk_bf16_f32 v106, v106, v107
	v_cvt_pk_bf16_f32 v107, v108, v109
	v_cvt_pk_bf16_f32 v108, v218, v219
	v_cvt_pk_bf16_f32 v109, v220, v221
	s_and_saveexec_b64 s[28:29], s[6:7]
	s_cbranch_execz .Lpu1_5
	global_store_dwordx4 v[192:193], v[98:101], off offset:320
	global_store_dwordx4 v[192:193], v[102:105], off offset:336
.Lpu1_5:
	s_or_b64 exec, exec, s[28:29]
	s_waitcnt vmcnt(8)
	v_mfma_f32_32x32x16_bf16 v[2:17], v[106:109], v[222:225], v[2:17]
	v_mfma_f32_32x32x16_bf16 v[18:33], v[106:109], v[226:229], v[18:33]
	v_mfma_f32_32x32x16_bf16 v[34:49], v[106:109], v[230:233], v[34:49]
	v_mfma_f32_32x32x16_bf16 v[50:65], v[106:109], v[234:237], v[50:65]
	s_waitcnt lgkmcnt(3)
	v_lshlrev_b32_e32 v98, 16, v238
	v_and_b32_e32 v99, 0xffff0000, v238
	v_lshlrev_b32_e32 v100, 16, v239
	v_and_b32_e32 v101, 0xffff0000, v239
	v_lshlrev_b32_e32 v102, 16, v240
	v_and_b32_e32 v103, 0xffff0000, v240
	v_lshlrev_b32_e32 v104, 16, v241
	v_and_b32_e32 v105, 0xffff0000, v241
	ds_read_b128 v[238:241], v246 offset:3184
	s_waitcnt lgkmcnt(3)
	v_lshlrev_b32_e32 v216, 16, v242
	v_and_b32_e32 v217, 0xffff0000, v242
	v_lshlrev_b32_e32 v242, 16, v243
	v_and_b32_e32 v243, 0xffff0000, v243
	v_pk_add_f32 v[106:107], v[98:99], v[216:217]
	v_pk_add_f32 v[108:109], v[100:101], v[242:243]
	v_lshlrev_b32_e32 v216, 16, v244
	v_and_b32_e32 v217, 0xffff0000, v244
	v_lshlrev_b32_e32 v244, 16, v245
	v_and_b32_e32 v245, 0xffff0000, v245
	v_pk_add_f32 v[218:219], v[102:103], v[216:217]
	v_pk_add_f32 v[220:221], v[104:105], v[244:245]
	ds_read_b128 v[242:245], v246 offset:2912
	s_waitcnt lgkmcnt(3)
	v_lshlrev_b32_e32 v216, 16, v248
	v_and_b32_e32 v217, 0xffff0000, v248
	v_lshlrev_b32_e32 v248, 16, v249
	v_and_b32_e32 v249, 0xffff0000, v249
	v_pk_add_f32 v[106:107], v[106:107], v[216:217]
	v_pk_add_f32 v[108:109], v[108:109], v[248:249]
	v_lshlrev_b32_e32 v216, 16, v250
	v_and_b32_e32 v217, 0xffff0000, v250
	v_lshlrev_b32_e32 v250, 16, v251
	v_and_b32_e32 v251, 0xffff0000, v251
	v_pk_add_f32 v[218:219], v[218:219], v[216:217]
	v_pk_add_f32 v[220:221], v[220:221], v[250:251]
	ds_read_b128 v[248:251], v246 offset:2640
	s_waitcnt lgkmcnt(3)
	v_lshlrev_b32_e32 v216, 16, v252
	v_and_b32_e32 v217, 0xffff0000, v252
	v_lshlrev_b32_e32 v252, 16, v253
	v_and_b32_e32 v253, 0xffff0000, v253
	v_pk_add_f32 v[106:107], v[106:107], v[216:217]
	v_pk_add_f32 v[108:109], v[108:109], v[252:253]
	v_lshlrev_b32_e32 v216, 16, v254
	v_and_b32_e32 v217, 0xffff0000, v254
	v_lshlrev_b32_e32 v254, 16, v255
	v_and_b32_e32 v255, 0xffff0000, v255
	v_pk_add_f32 v[218:219], v[218:219], v[216:217]
	v_pk_add_f32 v[220:221], v[220:221], v[254:255]
	ds_read_b128 v[252:255], v246 offset:2368
	s_waitcnt lgkmcnt(3)
	v_lshlrev_b32_e32 v216, 16, v238
	v_and_b32_e32 v217, 0xffff0000, v238
	v_lshlrev_b32_e32 v238, 16, v239
	v_and_b32_e32 v239, 0xffff0000, v239
	v_pk_add_f32 v[106:107], v[106:107], v[216:217]
	v_pk_add_f32 v[108:109], v[108:109], v[238:239]
	v_lshlrev_b32_e32 v216, 16, v240
	v_and_b32_e32 v217, 0xffff0000, v240
	v_lshlrev_b32_e32 v240, 16, v241
	v_and_b32_e32 v241, 0xffff0000, v241
	v_pk_add_f32 v[218:219], v[218:219], v[216:217]
	v_pk_add_f32 v[220:221], v[220:221], v[240:241]
	ds_read_b128 v[238:241], v246 offset:4304
	s_waitcnt lgkmcnt(3)
	v_lshlrev_b32_e32 v216, 16, v242
	v_and_b32_e32 v217, 0xffff0000, v242
	v_lshlrev_b32_e32 v242, 16, v243
	v_and_b32_e32 v243, 0xffff0000, v243
	v_pk_add_f32 v[106:107], v[106:107], v[216:217]
	v_pk_add_f32 v[108:109], v[108:109], v[242:243]
	v_lshlrev_b32_e32 v216, 16, v244
	v_and_b32_e32 v217, 0xffff0000, v244
	v_lshlrev_b32_e32 v244, 16, v245
	v_and_b32_e32 v245, 0xffff0000, v245
	v_pk_add_f32 v[218:219], v[218:219], v[216:217]
	v_pk_add_f32 v[220:221], v[220:221], v[244:245]
	ds_read_b128 v[242:245], v246 offset:4032
	s_waitcnt lgkmcnt(3)
	v_lshlrev_b32_e32 v216, 16, v248
	v_and_b32_e32 v217, 0xffff0000, v248
	v_lshlrev_b32_e32 v248, 16, v249
	v_and_b32_e32 v249, 0xffff0000, v249
	v_pk_add_f32 v[106:107], v[106:107], v[216:217]
	v_pk_add_f32 v[108:109], v[108:109], v[248:249]
	v_lshlrev_b32_e32 v216, 16, v250
	v_and_b32_e32 v217, 0xffff0000, v250
	v_lshlrev_b32_e32 v250, 16, v251
	v_and_b32_e32 v251, 0xffff0000, v251
	v_pk_add_f32 v[218:219], v[218:219], v[216:217]
	v_pk_add_f32 v[220:221], v[220:221], v[250:251]
	ds_read_b128 v[248:251], v246 offset:3760
	s_waitcnt lgkmcnt(3)
	v_lshlrev_b32_e32 v216, 16, v252
	v_and_b32_e32 v217, 0xffff0000, v252
	v_lshlrev_b32_e32 v252, 16, v253
	v_and_b32_e32 v253, 0xffff0000, v253
	v_pk_add_f32 v[106:107], v[106:107], v[216:217]
	v_pk_add_f32 v[108:109], v[108:109], v[252:253]
	v_lshlrev_b32_e32 v216, 16, v254
	v_and_b32_e32 v217, 0xffff0000, v254
	v_lshlrev_b32_e32 v254, 16, v255
	v_and_b32_e32 v255, 0xffff0000, v255
	v_pk_add_f32 v[218:219], v[218:219], v[216:217]
	v_pk_add_f32 v[220:221], v[220:221], v[254:255]
	ds_read_b128 v[252:255], v246 offset:3488
	v_fma_f32 v106, v159, v106, -v98
	v_fma_f32 v107, v159, v107, -v99
	v_fma_f32 v108, v159, v108, -v100
	v_fma_f32 v109, v159, v109, -v101
	v_fma_f32 v218, v159, v218, -v102
	v_fma_f32 v219, v159, v219, -v103
	v_fma_f32 v220, v159, v220, -v104
	v_fma_f32 v221, v159, v221, -v105
	v_cvt_pk_bf16_f32 v106, v106, v107
	v_cvt_pk_bf16_f32 v107, v108, v109
	v_cvt_pk_bf16_f32 v108, v218, v219
	v_cvt_pk_bf16_f32 v109, v220, v221
	s_and_saveexec_b64 s[28:29], s[6:7]
	s_cbranch_execz .Lpu1_6
	global_store_dwordx4 v[192:193], v[98:101], off offset:384
	global_store_dwordx4 v[192:193], v[102:105], off offset:400
.Lpu1_6:
	s_or_b64 exec, exec, s[28:29]
	s_waitcnt vmcnt(4)
	v_mfma_f32_32x32x16_bf16 v[2:17], v[106:109], v[70:73], v[2:17]
	v_mfma_f32_32x32x16_bf16 v[18:33], v[106:109], v[74:77], v[18:33]
	v_mfma_f32_32x32x16_bf16 v[34:49], v[106:109], v[78:81], v[34:49]
	v_mfma_f32_32x32x16_bf16 v[50:65], v[106:109], v[66:69], v[50:65]
	s_waitcnt lgkmcnt(3)
	v_lshlrev_b32_e32 v98, 16, v238
	v_and_b32_e32 v99, 0xffff0000, v238
	v_lshlrev_b32_e32 v100, 16, v239
	v_and_b32_e32 v101, 0xffff0000, v239
	v_lshlrev_b32_e32 v102, 16, v240
	v_and_b32_e32 v103, 0xffff0000, v240
	v_lshlrev_b32_e32 v104, 16, v241
	v_and_b32_e32 v105, 0xffff0000, v241
	ds_read_b128 v[238:241], v246 offset:3216
	s_waitcnt lgkmcnt(3)
	v_lshlrev_b32_e32 v216, 16, v242
	v_and_b32_e32 v217, 0xffff0000, v242
	v_lshlrev_b32_e32 v242, 16, v243
	v_and_b32_e32 v243, 0xffff0000, v243
	v_pk_add_f32 v[106:107], v[98:99], v[216:217]
	v_pk_add_f32 v[108:109], v[100:101], v[242:243]
	v_lshlrev_b32_e32 v216, 16, v244
	v_and_b32_e32 v217, 0xffff0000, v244
	v_lshlrev_b32_e32 v244, 16, v245
	v_and_b32_e32 v245, 0xffff0000, v245
	v_pk_add_f32 v[218:219], v[102:103], v[216:217]
	v_pk_add_f32 v[220:221], v[104:105], v[244:245]
	ds_read_b128 v[242:245], v246 offset:2944
	s_waitcnt lgkmcnt(3)
	v_lshlrev_b32_e32 v216, 16, v248
	v_and_b32_e32 v217, 0xffff0000, v248
	v_lshlrev_b32_e32 v248, 16, v249
	v_and_b32_e32 v249, 0xffff0000, v249
	v_pk_add_f32 v[106:107], v[106:107], v[216:217]
	v_pk_add_f32 v[108:109], v[108:109], v[248:249]
	v_lshlrev_b32_e32 v216, 16, v250
	v_and_b32_e32 v217, 0xffff0000, v250
	v_lshlrev_b32_e32 v250, 16, v251
	v_and_b32_e32 v251, 0xffff0000, v251
	v_pk_add_f32 v[218:219], v[218:219], v[216:217]
	v_pk_add_f32 v[220:221], v[220:221], v[250:251]
	ds_read_b128 v[248:251], v246 offset:2672
	s_waitcnt lgkmcnt(3)
	v_lshlrev_b32_e32 v216, 16, v252
	v_and_b32_e32 v217, 0xffff0000, v252
	v_lshlrev_b32_e32 v252, 16, v253
	v_and_b32_e32 v253, 0xffff0000, v253
	v_pk_add_f32 v[106:107], v[106:107], v[216:217]
	v_pk_add_f32 v[108:109], v[108:109], v[252:253]
	v_lshlrev_b32_e32 v216, 16, v254
	v_and_b32_e32 v217, 0xffff0000, v254
	v_lshlrev_b32_e32 v254, 16, v255
	v_and_b32_e32 v255, 0xffff0000, v255
	v_pk_add_f32 v[218:219], v[218:219], v[216:217]
	v_pk_add_f32 v[220:221], v[220:221], v[254:255]
	ds_read_b128 v[252:255], v246 offset:2400
	s_waitcnt lgkmcnt(3)
	v_lshlrev_b32_e32 v216, 16, v238
	v_and_b32_e32 v217, 0xffff0000, v238
	v_lshlrev_b32_e32 v238, 16, v239
	v_and_b32_e32 v239, 0xffff0000, v239
	v_pk_add_f32 v[106:107], v[106:107], v[216:217]
	v_pk_add_f32 v[108:109], v[108:109], v[238:239]
	v_lshlrev_b32_e32 v216, 16, v240
	v_and_b32_e32 v217, 0xffff0000, v240
	v_lshlrev_b32_e32 v240, 16, v241
	v_and_b32_e32 v241, 0xffff0000, v241
	v_pk_add_f32 v[218:219], v[218:219], v[216:217]
	v_pk_add_f32 v[220:221], v[220:221], v[240:241]
	s_waitcnt lgkmcnt(2)
	v_lshlrev_b32_e32 v216, 16, v242
	v_and_b32_e32 v217, 0xffff0000, v242
	v_lshlrev_b32_e32 v242, 16, v243
	v_and_b32_e32 v243, 0xffff0000, v243
	v_pk_add_f32 v[106:107], v[106:107], v[216:217]
	v_pk_add_f32 v[108:109], v[108:109], v[242:243]
	v_lshlrev_b32_e32 v216, 16, v244
	v_and_b32_e32 v217, 0xffff0000, v244
	v_lshlrev_b32_e32 v244, 16, v245
	v_and_b32_e32 v245, 0xffff0000, v245
	v_pk_add_f32 v[218:219], v[218:219], v[216:217]
	v_pk_add_f32 v[220:221], v[220:221], v[244:245]
	s_waitcnt lgkmcnt(1)
	v_lshlrev_b32_e32 v216, 16, v248
	v_and_b32_e32 v217, 0xffff0000, v248
	v_lshlrev_b32_e32 v248, 16, v249
	v_and_b32_e32 v249, 0xffff0000, v249
	v_pk_add_f32 v[106:107], v[106:107], v[216:217]
	v_pk_add_f32 v[108:109], v[108:109], v[248:249]
	v_lshlrev_b32_e32 v216, 16, v250
	v_and_b32_e32 v217, 0xffff0000, v250
	v_lshlrev_b32_e32 v250, 16, v251
	v_and_b32_e32 v251, 0xffff0000, v251
	v_pk_add_f32 v[218:219], v[218:219], v[216:217]
	v_pk_add_f32 v[220:221], v[220:221], v[250:251]
	s_waitcnt lgkmcnt(0)
	v_lshlrev_b32_e32 v216, 16, v252
	v_and_b32_e32 v217, 0xffff0000, v252
	v_lshlrev_b32_e32 v252, 16, v253
	v_and_b32_e32 v253, 0xffff0000, v253
	v_pk_add_f32 v[106:107], v[106:107], v[216:217]
	v_pk_add_f32 v[108:109], v[108:109], v[252:253]
	v_lshlrev_b32_e32 v216, 16, v254
	v_and_b32_e32 v217, 0xffff0000, v254
	v_lshlrev_b32_e32 v254, 16, v255
	v_and_b32_e32 v255, 0xffff0000, v255
	v_pk_add_f32 v[218:219], v[218:219], v[216:217]
	v_pk_add_f32 v[220:221], v[220:221], v[254:255]
	v_fma_f32 v106, v159, v106, -v98
	v_fma_f32 v107, v159, v107, -v99
	v_fma_f32 v108, v159, v108, -v100
	v_fma_f32 v109, v159, v109, -v101
	v_fma_f32 v218, v159, v218, -v102
	v_fma_f32 v219, v159, v219, -v103
	v_fma_f32 v220, v159, v220, -v104
	v_fma_f32 v221, v159, v221, -v105
	v_cvt_pk_bf16_f32 v106, v106, v107
	v_cvt_pk_bf16_f32 v107, v108, v109
	v_cvt_pk_bf16_f32 v108, v218, v219
	v_cvt_pk_bf16_f32 v109, v220, v221
	s_and_saveexec_b64 s[28:29], s[6:7]
	s_cbranch_execz .Lpu1_7
	global_store_dwordx4 v[192:193], v[98:101], off offset:448
	global_store_dwordx4 v[192:193], v[102:105], off offset:464

.LBB0_379:
	s_or_b64 exec, exec, s[6:7]
	s_waitcnt lgkmcnt(0)
	global_load_dwordx4 v[82:85], v[122:123], off offset:512
	global_load_dwordx4 v[86:89], v[124:125], off offset:512
	global_load_dwordx4 v[90:93], v[126:127], off offset:512
	global_load_dwordx4 v[94:97], v[128:129], off offset:512
	global_load_dwordx4 v[222:225], v[122:123], off offset:1024
	global_load_dwordx4 v[226:229], v[124:125], off offset:1024
	global_load_dwordx4 v[230:233], v[126:127], off offset:1024
	global_load_dwordx4 v[234:237], v[128:129], off offset:1024
	v_lshl_add_u32 v246, v197, 1, v214
	ds_read_b128 v[238:241], v246 offset:4080
	ds_read_b128 v[242:245], v246 offset:3808
	ds_read_b128 v[248:251], v246 offset:3536
	ds_read_b128 v[252:255], v246 offset:3264
	v_or_b32_e32 v2, s28, v1
	v_min_u32_e32 v3, 3, v2
	v_add_u32_e32 v3, 1, v3
	v_cvt_f32_ubyte0_e32 v3, v3
	v_div_scale_f32 v4, s[6:7], v3, v3, 1.0
	v_rcp_f32_e32 v5, v4
	s_ashr_i32 s8, s30, 6
	s_mul_i32 s10, s8, 15
	v_cmp_lt_u32_e64 s[6:7], s41, v2
	v_fma_f32 v6, -v4, v5, 1.0
	v_fmac_f32_e32 v5, v6, v5
	v_div_scale_f32 v6, vcc, 1.0, v3, 1.0
	v_mul_f32_e32 v7, v6, v5
	v_fma_f32 v8, -v4, v7, v6
	v_fmac_f32_e32 v7, v8, v5
	v_fma_f32 v4, -v4, v7, v6
	v_div_fmas_f32 v4, v4, v5, v7
	v_div_fixup_f32 v159, v4, v3, 1.0
	s_ashr_i32 s11, s10, 31
	v_add_u32_e32 v2, 0xfffff80f, v2
	v_mov_b32_e32 v3, v155
	v_lshl_add_u64 v[2:3], v[2:3], 0, s[10:11]
	v_lshlrev_b64 v[2:3], 11, v[2:3]
	v_lshl_add_u64 v[2:3], s[70:71], 0, v[2:3]
	v_mov_b32_e32 v163, v155
	v_lshl_add_u64 v[2:3], v[2:3], 0, v[162:163]
	v_lshl_add_u64 v[190:191], v[2:3], 0, s[24:25]
	v_mov_b64_e32 v[2:3], 0
	v_mov_b64_e32 v[4:5], 0
	v_mov_b64_e32 v[6:7], 0
	v_mov_b64_e32 v[8:9], 0
	v_mov_b64_e32 v[10:11], 0
	v_mov_b64_e32 v[12:13], 0
	v_mov_b64_e32 v[14:15], 0
	v_mov_b64_e32 v[16:17], 0
	v_mov_b64_e32 v[18:19], 0
	v_mov_b64_e32 v[20:21], 0
	v_mov_b64_e32 v[22:23], 0
	v_mov_b64_e32 v[24:25], 0
	v_mov_b64_e32 v[26:27], 0
	v_mov_b64_e32 v[28:29], 0
	v_mov_b64_e32 v[30:31], 0
	v_mov_b64_e32 v[32:33], 0
	v_mov_b64_e32 v[34:35], 0
	v_mov_b64_e32 v[36:37], 0
	v_mov_b64_e32 v[38:39], 0
	v_mov_b64_e32 v[40:41], 0
	v_mov_b64_e32 v[42:43], 0
	v_mov_b64_e32 v[44:45], 0
	v_mov_b64_e32 v[46:47], 0
	v_mov_b64_e32 v[48:49], 0
	v_mov_b64_e32 v[50:51], 0
	v_mov_b64_e32 v[52:53], 0
	v_mov_b64_e32 v[54:55], 0
	v_mov_b64_e32 v[56:57], 0
	v_mov_b64_e32 v[58:59], 0
	v_mov_b64_e32 v[60:61], 0
	v_mov_b64_e32 v[62:63], 0
	v_mov_b64_e32 v[64:65], 0
	s_mov_b32 s49, 0
	s_mov_b64 s[10:11], 0
	s_waitcnt lgkmcnt(3)
	v_lshlrev_b32_e32 v98, 16, v238
	v_and_b32_e32 v99, 0xffff0000, v238
	v_lshlrev_b32_e32 v100, 16, v239
	v_and_b32_e32 v101, 0xffff0000, v239
	v_lshlrev_b32_e32 v102, 16, v240
	v_and_b32_e32 v103, 0xffff0000, v240
	v_lshlrev_b32_e32 v104, 16, v241
	v_and_b32_e32 v105, 0xffff0000, v241
	ds_read_b128 v[238:241], v246 offset:4112
	s_waitcnt lgkmcnt(3)
	v_lshlrev_b32_e32 v216, 16, v242
	v_and_b32_e32 v217, 0xffff0000, v242
	v_lshlrev_b32_e32 v242, 16, v243
	v_and_b32_e32 v243, 0xffff0000, v243
	v_pk_add_f32 v[106:107], v[98:99], v[216:217]
	v_pk_add_f32 v[108:109], v[100:101], v[242:243]
	v_lshlrev_b32_e32 v216, 16, v244
	v_and_b32_e32 v217, 0xffff0000, v244
	v_lshlrev_b32_e32 v244, 16, v245
	v_and_b32_e32 v245, 0xffff0000, v245
	v_pk_add_f32 v[218:219], v[102:103], v[216:217]
	v_pk_add_f32 v[220:221], v[104:105], v[244:245]
	ds_read_b128 v[242:245], v246 offset:3840
	s_waitcnt lgkmcnt(3)
	v_lshlrev_b32_e32 v216, 16, v248
	v_and_b32_e32 v217, 0xffff0000, v248
	v_lshlrev_b32_e32 v248, 16, v249
	v_and_b32_e32 v249, 0xffff0000, v249
	v_pk_add_f32 v[106:107], v[106:107], v[216:217]
	v_pk_add_f32 v[108:109], v[108:109], v[248:249]
	v_lshlrev_b32_e32 v216, 16, v250
	v_and_b32_e32 v217, 0xffff0000, v250
	v_lshlrev_b32_e32 v250, 16, v251
	v_and_b32_e32 v251, 0xffff0000, v251
	v_pk_add_f32 v[218:219], v[218:219], v[216:217]
	v_pk_add_f32 v[220:221], v[220:221], v[250:251]
	ds_read_b128 v[248:251], v246 offset:3568
	s_waitcnt lgkmcnt(3)
	v_lshlrev_b32_e32 v216, 16, v252
	v_and_b32_e32 v217, 0xffff0000, v252
	v_lshlrev_b32_e32 v252, 16, v253
	v_and_b32_e32 v253, 0xffff0000, v253
	v_pk_add_f32 v[106:107], v[106:107], v[216:217]
	v_pk_add_f32 v[108:109], v[108:109], v[252:253]
	v_lshlrev_b32_e32 v216, 16, v254
	v_and_b32_e32 v217, 0xffff0000, v254
	v_lshlrev_b32_e32 v254, 16, v255
	v_and_b32_e32 v255, 0xffff0000, v255
	v_pk_add_f32 v[218:219], v[218:219], v[216:217]
	v_pk_add_f32 v[220:221], v[220:221], v[254:255]
	ds_read_b128 v[252:255], v246 offset:3296
	v_fma_f32 v106, v159, v106, -v98
	v_fma_f32 v107, v159, v107, -v99
	v_fma_f32 v108, v159, v108, -v100
	v_fma_f32 v109, v159, v109, -v101
	v_fma_f32 v218, v159, v218, -v102
	v_fma_f32 v219, v159, v219, -v103
	v_fma_f32 v220, v159, v220, -v104
	v_fma_f32 v221, v159, v221, -v105
	v_cvt_pk_bf16_f32 v106, v106, v107
	v_cvt_pk_bf16_f32 v107, v108, v109
	v_cvt_pk_bf16_f32 v108, v218, v219
	v_cvt_pk_bf16_f32 v109, v220, v221
	s_and_saveexec_b64 s[28:29], s[6:7]
	s_cbranch_execz .Lpu2_0
	global_store_dwordx4 v[190:191], v[98:101], off offset:0
	global_store_dwordx4 v[190:191], v[102:105], off offset:16
.Lpu2_0:
	s_or_b64 exec, exec, s[28:29]
	s_waitcnt vmcnt(8)
	v_mfma_f32_32x32x16_bf16 v[2:17], v[106:109], v[70:73], v[2:17]
	v_mfma_f32_32x32x16_bf16 v[18:33], v[106:109], v[74:77], v[18:33]
	v_mfma_f32_32x32x16_bf16 v[34:49], v[106:109], v[78:81], v[34:49]
	v_mfma_f32_32x32x16_bf16 v[50:65], v[106:109], v[66:69], v[50:65]
	global_load_dwordx4 v[70:73], v[122:123], off offset:1536
	global_load_dwordx4 v[74:77], v[124:125], off offset:1536
	global_load_dwordx4 v[78:81], v[126:127], off offset:1536
	global_load_dwordx4 v[66:69], v[128:129], off offset:1536
	s_waitcnt lgkmcnt(3)
	v_lshlrev_b32_e32 v98, 16, v238
	v_and_b32_e32 v99, 0xffff0000, v238
	v_lshlrev_b32_e32 v100, 16, v239
	v_and_b32_e32 v101, 0xffff0000, v239
	v_lshlrev_b32_e32 v102, 16, v240
	v_and_b32_e32 v103, 0xffff0000, v240
	v_lshlrev_b32_e32 v104, 16, v241
	v_and_b32_e32 v105, 0xffff0000, v241
	ds_read_b128 v[238:241], v246 offset:4144
	s_waitcnt lgkmcnt(3)
	v_lshlrev_b32_e32 v216, 16, v242
	v_and_b32_e32 v217, 0xffff0000, v242
	v_lshlrev_b32_e32 v242, 16, v243
	v_and_b32_e32 v243, 0xffff0000, v243
	v_pk_add_f32 v[106:107], v[98:99], v[216:217]
	v_pk_add_f32 v[108:109], v[100:101], v[242:243]
	v_lshlrev_b32_e32 v216, 16, v244
	v_and_b32_e32 v217, 0xffff0000, v244
	v_lshlrev_b32_e32 v244, 16, v245
	v_and_b32_e32 v245, 0xffff0000, v245
	v_pk_add_f32 v[218:219], v[102:103], v[216:217]
	v_pk_add_f32 v[220:221], v[104:105], v[244:245]
	ds_read_b128 v[242:245], v246 offset:3872
	s_waitcnt lgkmcnt(3)
	v_lshlrev_b32_e32 v216, 16, v248
	v_and_b32_e32 v217, 0xffff0000, v248
	v_lshlrev_b32_e32 v248, 16, v249
	v_and_b32_e32 v249, 0xffff0000, v249
	v_pk_add_f32 v[106:107], v[106:107], v[216:217]
	v_pk_add_f32 v[108:109], v[108:109], v[248:249]
	v_lshlrev_b32_e32 v216, 16, v250
	v_and_b32_e32 v217, 0xffff0000, v250
	v_lshlrev_b32_e32 v250, 16, v251
	v_and_b32_e32 v251, 0xffff0000, v251
	v_pk_add_f32 v[218:219], v[218:219], v[216:217]
	v_pk_add_f32 v[220:221], v[220:221], v[250:251]
	ds_read_b128 v[248:251], v246 offset:3600
	s_waitcnt lgkmcnt(3)
	v_lshlrev_b32_e32 v216, 16, v252
	v_and_b32_e32 v217, 0xffff0000, v252
	v_lshlrev_b32_e32 v252, 16, v253
	v_and_b32_e32 v253, 0xffff0000, v253
	v_pk_add_f32 v[106:107], v[106:107], v[216:217]
	v_pk_add_f32 v[108:109], v[108:109], v[252:253]
	v_lshlrev_b32_e32 v216, 16, v254
	v_and_b32_e32 v217, 0xffff0000, v254
	v_lshlrev_b32_e32 v254, 16, v255
	v_and_b32_e32 v255, 0xffff0000, v255
	v_pk_add_f32 v[218:219], v[218:219], v[216:217]
	v_pk_add_f32 v[220:221], v[220:221], v[254:255]
	ds_read_b128 v[252:255], v246 offset:3328
	v_fma_f32 v106, v159, v106, -v98
	v_fma_f32 v107, v159, v107, -v99
	v_fma_f32 v108, v159, v108, -v100
	v_fma_f32 v109, v159, v109, -v101
	v_fma_f32 v218, v159, v218, -v102
	v_fma_f32 v219, v159, v219, -v103
	v_fma_f32 v220, v159, v220, -v104
	v_fma_f32 v221, v159, v221, -v105
	v_cvt_pk_bf16_f32 v106, v106, v107
	v_cvt_pk_bf16_f32 v107, v108, v109
	v_cvt_pk_bf16_f32 v108, v218, v219
	v_cvt_pk_bf16_f32 v109, v220, v221
	s_and_saveexec_b64 s[28:29], s[6:7]
	s_cbranch_execz .Lpu2_1
	global_store_dwordx4 v[190:191], v[98:101], off offset:64
	global_store_dwordx4 v[190:191], v[102:105], off offset:80
.Lpu2_1:
	s_or_b64 exec, exec, s[28:29]
	s_waitcnt vmcnt(8)
	v_mfma_f32_32x32x16_bf16 v[2:17], v[106:109], v[82:85], v[2:17]
	v_mfma_f32_32x32x16_bf16 v[18:33], v[106:109], v[86:89], v[18:33]
	v_mfma_f32_32x32x16_bf16 v[34:49], v[106:109], v[90:93], v[34:49]
	v_mfma_f32_32x32x16_bf16 v[50:65], v[106:109], v[94:97], v[50:65]
	global_load_dwordx4 v[82:85], v[122:123], off offset:2048
	global_load_dwordx4 v[86:89], v[124:125], off offset:2048
	global_load_dwordx4 v[90:93], v[126:127], off offset:2048
	global_load_dwordx4 v[94:97], v[128:129], off offset:2048
	s_waitcnt lgkmcnt(3)
	v_lshlrev_b32_e32 v98, 16, v238
	v_and_b32_e32 v99, 0xffff0000, v238
	v_lshlrev_b32_e32 v100, 16, v239
	v_and_b32_e32 v101, 0xffff0000, v239
	v_lshlrev_b32_e32 v102, 16, v240
	v_and_b32_e32 v103, 0xffff0000, v240
	v_lshlrev_b32_e32 v104, 16, v241
	v_and_b32_e32 v105, 0xffff0000, v241
	ds_read_b128 v[238:241], v246 offset:4176
	s_waitcnt lgkmcnt(3)
	v_lshlrev_b32_e32 v216, 16, v242
	v_and_b32_e32 v217, 0xffff0000, v242
	v_lshlrev_b32_e32 v242, 16, v243
	v_and_b32_e32 v243, 0xffff0000, v243
	v_pk_add_f32 v[106:107], v[98:99], v[216:217]
	v_pk_add_f32 v[108:109], v[100:101], v[242:243]
	v_lshlrev_b32_e32 v216, 16, v244
	v_and_b32_e32 v217, 0xffff0000, v244
	v_lshlrev_b32_e32 v244, 16, v245
	v_and_b32_e32 v245, 0xffff0000, v245
	v_pk_add_f32 v[218:219], v[102:103], v[216:217]
	v_pk_add_f32 v[220:221], v[104:105], v[244:245]
	ds_read_b128 v[242:245], v246 offset:3904
	s_waitcnt lgkmcnt(3)
	v_lshlrev_b32_e32 v216, 16, v248
	v_and_b32_e32 v217, 0xffff0000, v248
	v_lshlrev_b32_e32 v248, 16, v249
	v_and_b32_e32 v249, 0xffff0000, v249
	v_pk_add_f32 v[106:107], v[106:107], v[216:217]
	v_pk_add_f32 v[108:109], v[108:109], v[248:249]
	v_lshlrev_b32_e32 v216, 16, v250
	v_and_b32_e32 v217, 0xffff0000, v250
	v_lshlrev_b32_e32 v250, 16, v251
	v_and_b32_e32 v251, 0xffff0000, v251
	v_pk_add_f32 v[218:219], v[218:219], v[216:217]
	v_pk_add_f32 v[220:221], v[220:221], v[250:251]
	ds_read_b128 v[248:251], v246 offset:3632
	s_waitcnt lgkmcnt(3)
	v_lshlrev_b32_e32 v216, 16, v252
	v_and_b32_e32 v217, 0xffff0000, v252
	v_lshlrev_b32_e32 v252, 16, v253
	v_and_b32_e32 v253, 0xffff0000, v253
	v_pk_add_f32 v[106:107], v[106:107], v[216:217]
	v_pk_add_f32 v[108:109], v[108:109], v[252:253]
	v_lshlrev_b32_e32 v216, 16, v254
	v_and_b32_e32 v217, 0xffff0000, v254
	v_lshlrev_b32_e32 v254, 16, v255
	v_and_b32_e32 v255, 0xffff0000, v255
	v_pk_add_f32 v[218:219], v[218:219], v[216:217]
	v_pk_add_f32 v[220:221], v[220:221], v[254:255]
	ds_read_b128 v[252:255], v246 offset:3360
	v_fma_f32 v106, v159, v106, -v98
	v_fma_f32 v107, v159, v107, -v99
	v_fma_f32 v108, v159, v108, -v100
	v_fma_f32 v109, v159, v109, -v101
	v_fma_f32 v218, v159, v218, -v102
	v_fma_f32 v219, v159, v219, -v103
	v_fma_f32 v220, v159, v220, -v104
	v_fma_f32 v221, v159, v221, -v105
	v_cvt_pk_bf16_f32 v106, v106, v107
	v_cvt_pk_bf16_f32 v107, v108, v109
	v_cvt_pk_bf16_f32 v108, v218, v219
	v_cvt_pk_bf16_f32 v109, v220, v221
	s_and_saveexec_b64 s[28:29], s[6:7]
	s_cbranch_execz .Lpu2_2
	global_store_dwordx4 v[190:191], v[98:101], off offset:128
	global_store_dwordx4 v[190:191], v[102:105], off offset:144
.Lpu2_2:
	s_or_b64 exec, exec, s[28:29]
	s_waitcnt vmcnt(8)
	v_mfma_f32_32x32x16_bf16 v[2:17], v[106:109], v[222:225], v[2:17]
	v_mfma_f32_32x32x16_bf16 v[18:33], v[106:109], v[226:229], v[18:33]
	v_mfma_f32_32x32x16_bf16 v[34:49], v[106:109], v[230:233], v[34:49]
	v_mfma_f32_32x32x16_bf16 v[50:65], v[106:109], v[234:237], v[50:65]
	global_load_dwordx4 v[222:225], v[122:123], off offset:2560
	global_load_dwordx4 v[226:229], v[124:125], off offset:2560
	global_load_dwordx4 v[230:233], v[126:127], off offset:2560
	global_load_dwordx4 v[234:237], v[128:129], off offset:2560
	s_waitcnt lgkmcnt(3)
	v_lshlrev_b32_e32 v98, 16, v238
	v_and_b32_e32 v99, 0xffff0000, v238
	v_lshlrev_b32_e32 v100, 16, v239
	v_and_b32_e32 v101, 0xffff0000, v239
	v_lshlrev_b32_e32 v102, 16, v240
	v_and_b32_e32 v103, 0xffff0000, v240
	v_lshlrev_b32_e32 v104, 16, v241
	v_and_b32_e32 v105, 0xffff0000, v241
	ds_read_b128 v[238:241], v246 offset:4208
	s_waitcnt lgkmcnt(3)
	v_lshlrev_b32_e32 v216, 16, v242
	v_and_b32_e32 v217, 0xffff0000, v242
	v_lshlrev_b32_e32 v242, 16, v243
	v_and_b32_e32 v243, 0xffff0000, v243
	v_pk_add_f32 v[106:107], v[98:99], v[216:217]
	v_pk_add_f32 v[108:109], v[100:101], v[242:243]
	v_lshlrev_b32_e32 v216, 16, v244
	v_and_b32_e32 v217, 0xffff0000, v244
	v_lshlrev_b32_e32 v244, 16, v245
	v_and_b32_e32 v245, 0xffff0000, v245
	v_pk_add_f32 v[218:219], v[102:103], v[216:217]
	v_pk_add_f32 v[220:221], v[104:105], v[244:245]
	ds_read_b128 v[242:245], v246 offset:3936
	s_waitcnt lgkmcnt(3)
	v_lshlrev_b32_e32 v216, 16, v248
	v_and_b32_e32 v217, 0xffff0000, v248
	v_lshlrev_b32_e32 v248, 16, v249
	v_and_b32_e32 v249, 0xffff0000, v249
	v_pk_add_f32 v[106:107], v[106:107], v[216:217]
	v_pk_add_f32 v[108:109], v[108:109], v[248:249]
	v_lshlrev_b32_e32 v216, 16, v250
	v_and_b32_e32 v217, 0xffff0000, v250
	v_lshlrev_b32_e32 v250, 16, v251
	v_and_b32_e32 v251, 0xffff0000, v251
	v_pk_add_f32 v[218:219], v[218:219], v[216:217]
	v_pk_add_f32 v[220:221], v[220:221], v[250:251]
	ds_read_b128 v[248:251], v246 offset:3664
	s_waitcnt lgkmcnt(3)
	v_lshlrev_b32_e32 v216, 16, v252
	v_and_b32_e32 v217, 0xffff0000, v252
	v_lshlrev_b32_e32 v252, 16, v253
	v_and_b32_e32 v253, 0xffff0000, v253
	v_pk_add_f32 v[106:107], v[106:107], v[216:217]
	v_pk_add_f32 v[108:109], v[108:109], v[252:253]
	v_lshlrev_b32_e32 v216, 16, v254
	v_and_b32_e32 v217, 0xffff0000, v254
	v_lshlrev_b32_e32 v254, 16, v255
	v_and_b32_e32 v255, 0xffff0000, v255
	v_pk_add_f32 v[218:219], v[218:219], v[216:217]
	v_pk_add_f32 v[220:221], v[220:221], v[254:255]
	ds_read_b128 v[252:255], v246 offset:3392
	v_fma_f32 v106, v159, v106, -v98
	v_fma_f32 v107, v159, v107, -v99
	v_fma_f32 v108, v159, v108, -v100
	v_fma_f32 v109, v159, v109, -v101
	v_fma_f32 v218, v159, v218, -v102
	v_fma_f32 v219, v159, v219, -v103
	v_fma_f32 v220, v159, v220, -v104
	v_fma_f32 v221, v159, v221, -v105
	v_cvt_pk_bf16_f32 v106, v106, v107
	v_cvt_pk_bf16_f32 v107, v108, v109
	v_cvt_pk_bf16_f32 v108, v218, v219
	v_cvt_pk_bf16_f32 v109, v220, v221
	s_and_saveexec_b64 s[28:29], s[6:7]
	s_cbranch_execz .Lpu2_3
	global_store_dwordx4 v[190:191], v[98:101], off offset:192
	global_store_dwordx4 v[190:191], v[102:105], off offset:208
.Lpu2_3:
	s_or_b64 exec, exec, s[28:29]
	s_waitcnt vmcnt(8)
	v_mfma_f32_32x32x16_bf16 v[2:17], v[106:109], v[70:73], v[2:17]
	v_mfma_f32_32x32x16_bf16 v[18:33], v[106:109], v[74:77], v[18:33]
	v_mfma_f32_32x32x16_bf16 v[34:49], v[106:109], v[78:81], v[34:49]
	v_mfma_f32_32x32x16_bf16 v[50:65], v[106:109], v[66:69], v[50:65]
	global_load_dwordx4 v[70:73], v[122:123], off offset:3072
	global_load_dwordx4 v[74:77], v[124:125], off offset:3072
	global_load_dwordx4 v[78:81], v[126:127], off offset:3072
	global_load_dwordx4 v[66:69], v[128:129], off offset:3072
	s_waitcnt lgkmcnt(3)
	v_lshlrev_b32_e32 v98, 16, v238
	v_and_b32_e32 v99, 0xffff0000, v238
	v_lshlrev_b32_e32 v100, 16, v239
	v_and_b32_e32 v101, 0xffff0000, v239
	v_lshlrev_b32_e32 v102, 16, v240
	v_and_b32_e32 v103, 0xffff0000, v240
	v_lshlrev_b32_e32 v104, 16, v241
	v_and_b32_e32 v105, 0xffff0000, v241
	ds_read_b128 v[238:241], v246 offset:4240
	s_waitcnt lgkmcnt(3)
	v_lshlrev_b32_e32 v216, 16, v242
	v_and_b32_e32 v217, 0xffff0000, v242
	v_lshlrev_b32_e32 v242, 16, v243
	v_and_b32_e32 v243, 0xffff0000, v243
	v_pk_add_f32 v[106:107], v[98:99], v[216:217]
	v_pk_add_f32 v[108:109], v[100:101], v[242:243]
	v_lshlrev_b32_e32 v216, 16, v244
	v_and_b32_e32 v217, 0xffff0000, v244
	v_lshlrev_b32_e32 v244, 16, v245
	v_and_b32_e32 v245, 0xffff0000, v245
	v_pk_add_f32 v[218:219], v[102:103], v[216:217]
	v_pk_add_f32 v[220:221], v[104:105], v[244:245]
	ds_read_b128 v[242:245], v246 offset:3968
	s_waitcnt lgkmcnt(3)
	v_lshlrev_b32_e32 v216, 16, v248
	v_and_b32_e32 v217, 0xffff0000, v248
	v_lshlrev_b32_e32 v248, 16, v249
	v_and_b32_e32 v249, 0xffff0000, v249
	v_pk_add_f32 v[106:107], v[106:107], v[216:217]
	v_pk_add_f32 v[108:109], v[108:109], v[248:249]
	v_lshlrev_b32_e32 v216, 16, v250
	v_and_b32_e32 v217, 0xffff0000, v250
	v_lshlrev_b32_e32 v250, 16, v251
	v_and_b32_e32 v251, 0xffff0000, v251
	v_pk_add_f32 v[218:219], v[218:219], v[216:217]
	v_pk_add_f32 v[220:221], v[220:221], v[250:251]
	ds_read_b128 v[248:251], v246 offset:3696
	s_waitcnt lgkmcnt(3)
	v_lshlrev_b32_e32 v216, 16, v252
	v_and_b32_e32 v217, 0xffff0000, v252
	v_lshlrev_b32_e32 v252, 16, v253
	v_and_b32_e32 v253, 0xffff0000, v253
	v_pk_add_f32 v[106:107], v[106:107], v[216:217]
	v_pk_add_f32 v[108:109], v[108:109], v[252:253]
	v_lshlrev_b32_e32 v216, 16, v254
	v_and_b32_e32 v217, 0xffff0000, v254
	v_lshlrev_b32_e32 v254, 16, v255
	v_and_b32_e32 v255, 0xffff0000, v255
	v_pk_add_f32 v[218:219], v[218:219], v[216:217]
	v_pk_add_f32 v[220:221], v[220:221], v[254:255]
	ds_read_b128 v[252:255], v246 offset:3424
	v_fma_f32 v106, v159, v106, -v98
	v_fma_f32 v107, v159, v107, -v99
	v_fma_f32 v108, v159, v108, -v100
	v_fma_f32 v109, v159, v109, -v101
	v_fma_f32 v218, v159, v218, -v102
	v_fma_f32 v219, v159, v219, -v103
	v_fma_f32 v220, v159, v220, -v104
	v_fma_f32 v221, v159, v221, -v105
	v_cvt_pk_bf16_f32 v106, v106, v107
	v_cvt_pk_bf16_f32 v107, v108, v109
	v_cvt_pk_bf16_f32 v108, v218, v219
	v_cvt_pk_bf16_f32 v109, v220, v221
	s_and_saveexec_b64 s[28:29], s[6:7]
	s_cbranch_execz .Lpu2_4
	global_store_dwordx4 v[190:191], v[98:101], off offset:256
	global_store_dwordx4 v[190:191], v[102:105], off offset:272
.Lpu2_4:
	s_or_b64 exec, exec, s[28:29]
	s_waitcnt vmcnt(8)
	v_mfma_f32_32x32x16_bf16 v[2:17], v[106:109], v[82:85], v[2:17]
	v_mfma_f32_32x32x16_bf16 v[18:33], v[106:109], v[86:89], v[18:33]
	v_mfma_f32_32x32x16_bf16 v[34:49], v[106:109], v[90:93], v[34:49]
	v_mfma_f32_32x32x16_bf16 v[50:65], v[106:109], v[94:97], v[50:65]
	global_load_dwordx4 v[82:85], v[122:123], off offset:3584
	global_load_dwordx4 v[86:89], v[124:125], off offset:3584
	global_load_dwordx4 v[90:93], v[126:127], off offset:3584
	global_load_dwordx4 v[94:97], v[128:129], off offset:3584
	s_waitcnt lgkmcnt(3)
	v_lshlrev_b32_e32 v98, 16, v238
	v_and_b32_e32 v99, 0xffff0000, v238
	v_lshlrev_b32_e32 v100, 16, v239
	v_and_b32_e32 v101, 0xffff0000, v239
	v_lshlrev_b32_e32 v102, 16, v240
	v_and_b32_e32 v103, 0xffff0000, v240
	v_lshlrev_b32_e32 v104, 16, v241
	v_and_b32_e32 v105, 0xffff0000, v241
	ds_read_b128 v[238:241], v246 offset:4272
	s_waitcnt lgkmcnt(3)
	v_lshlrev_b32_e32 v216, 16, v242
	v_and_b32_e32 v217, 0xffff0000, v242
	v_lshlrev_b32_e32 v242, 16, v243
	v_and_b32_e32 v243, 0xffff0000, v243
	v_pk_add_f32 v[106:107], v[98:99], v[216:217]
	v_pk_add_f32 v[108:109], v[100:101], v[242:243]
	v_lshlrev_b32_e32 v216, 16, v244
	v_and_b32_e32 v217, 0xffff0000, v244
	v_lshlrev_b32_e32 v244, 16, v245
	v_and_b32_e32 v245, 0xffff0000, v245
	v_pk_add_f32 v[218:219], v[102:103], v[216:217]
	v_pk_add_f32 v[220:221], v[104:105], v[244:245]
	ds_read_b128 v[242:245], v246 offset:4000
	s_waitcnt lgkmcnt(3)
	v_lshlrev_b32_e32 v216, 16, v248
	v_and_b32_e32 v217, 0xffff0000, v248
	v_lshlrev_b32_e32 v248, 16, v249
	v_and_b32_e32 v249, 0xffff0000, v249
	v_pk_add_f32 v[106:107], v[106:107], v[216:217]
	v_pk_add_f32 v[108:109], v[108:109], v[248:249]
	v_lshlrev_b32_e32 v216, 16, v250
	v_and_b32_e32 v217, 0xffff0000, v250
	v_lshlrev_b32_e32 v250, 16, v251
	v_and_b32_e32 v251, 0xffff0000, v251
	v_pk_add_f32 v[218:219], v[218:219], v[216:217]
	v_pk_add_f32 v[220:221], v[220:221], v[250:251]
	ds_read_b128 v[248:251], v246 offset:3728
	s_waitcnt lgkmcnt(3)
	v_lshlrev_b32_e32 v216, 16, v252
	v_and_b32_e32 v217, 0xffff0000, v252
	v_lshlrev_b32_e32 v252, 16, v253
	v_and_b32_e32 v253, 0xffff0000, v253
	v_pk_add_f32 v[106:107], v[106:107], v[216:217]
	v_pk_add_f32 v[108:109], v[108:109], v[252:253]
	v_lshlrev_b32_e32 v216, 16, v254
	v_and_b32_e32 v217, 0xffff0000, v254
	v_lshlrev_b32_e32 v254, 16, v255
	v_and_b32_e32 v255, 0xffff0000, v255
	v_pk_add_f32 v[218:219], v[218:219], v[216:217]
	v_pk_add_f32 v[220:221], v[220:221], v[254:255]
	ds_read_b128 v[252:255], v246 offset:3456
	v_fma_f32 v106, v159, v106, -v98
	v_fma_f32 v107, v159, v107, -v99
	v_fma_f32 v108, v159, v108, -v100
	v_fma_f32 v109, v159, v109, -v101
	v_fma_f32 v218, v159, v218, -v102
	v_fma_f32 v219, v159, v219, -v103
	v_fma_f32 v220, v159, v220, -v104
	v_fma_f32 v221, v159, v221, -v105
	v_cvt_pk_bf16_f32 v106, v106, v107
	v_cvt_pk_bf16_f32 v107, v108, v109
	v_cvt_pk_bf16_f32 v108, v218, v219
	v_cvt_pk_bf16_f32 v109, v220, v221
	s_and_saveexec_b64 s[28:29], s[6:7]
	s_cbranch_execz .Lpu2_5
	global_store_dwordx4 v[190:191], v[98:101], off offset:320
	global_store_dwordx4 v[190:191], v[102:105], off offset:336
.Lpu2_5:
	s_or_b64 exec, exec, s[28:29]
	s_waitcnt vmcnt(8)
	v_mfma_f32_32x32x16_bf16 v[2:17], v[106:109], v[222:225], v[2:17]
	v_mfma_f32_32x32x16_bf16 v[18:33], v[106:109], v[226:229], v[18:33]
	v_mfma_f32_32x32x16_bf16 v[34:49], v[106:109], v[230:233], v[34:49]
	v_mfma_f32_32x32x16_bf16 v[50:65], v[106:109], v[234:237], v[50:65]
	s_waitcnt lgkmcnt(3)
	v_lshlrev_b32_e32 v98, 16, v238
	v_and_b32_e32 v99, 0xffff0000, v238
	v_lshlrev_b32_e32 v100, 16, v239
	v_and_b32_e32 v101, 0xffff0000, v239
	v_lshlrev_b32_e32 v102, 16, v240
	v_and_b32_e32 v103, 0xffff0000, v240
	v_lshlrev_b32_e32 v104, 16, v241
	v_and_b32_e32 v105, 0xffff0000, v241
	ds_read_b128 v[238:241], v246 offset:4304
	s_waitcnt lgkmcnt(3)
	v_lshlrev_b32_e32 v216, 16, v242
	v_and_b32_e32 v217, 0xffff0000, v242
	v_lshlrev_b32_e32 v242, 16, v243
	v_and_b32_e32 v243, 0xffff0000, v243
	v_pk_add_f32 v[106:107], v[98:99], v[216:217]
	v_pk_add_f32 v[108:109], v[100:101], v[242:243]
	v_lshlrev_b32_e32 v216, 16, v244
	v_and_b32_e32 v217, 0xffff0000, v244
	v_lshlrev_b32_e32 v244, 16, v245
	v_and_b32_e32 v245, 0xffff0000, v245
	v_pk_add_f32 v[218:219], v[102:103], v[216:217]
	v_pk_add_f32 v[220:221], v[104:105], v[244:245]
	ds_read_b128 v[242:245], v246 offset:4032
	s_waitcnt lgkmcnt(3)
	v_lshlrev_b32_e32 v216, 16, v248
	v_and_b32_e32 v217, 0xffff0000, v248
	v_lshlrev_b32_e32 v248, 16, v249
	v_and_b32_e32 v249, 0xffff0000, v249
	v_pk_add_f32 v[106:107], v[106:107], v[216:217]
	v_pk_add_f32 v[108:109], v[108:109], v[248:249]
	v_lshlrev_b32_e32 v216, 16, v250
	v_and_b32_e32 v217, 0xffff0000, v250
	v_lshlrev_b32_e32 v250, 16, v251
	v_and_b32_e32 v251, 0xffff0000, v251
	v_pk_add_f32 v[218:219], v[218:219], v[216:217]
	v_pk_add_f32 v[220:221], v[220:221], v[250:251]
	ds_read_b128 v[248:251], v246 offset:3760
	s_waitcnt lgkmcnt(3)
	v_lshlrev_b32_e32 v216, 16, v252
	v_and_b32_e32 v217, 0xffff0000, v252
	v_lshlrev_b32_e32 v252, 16, v253
	v_and_b32_e32 v253, 0xffff0000, v253
	v_pk_add_f32 v[106:107], v[106:107], v[216:217]
	v_pk_add_f32 v[108:109], v[108:109], v[252:253]
	v_lshlrev_b32_e32 v216, 16, v254
	v_and_b32_e32 v217, 0xffff0000, v254
	v_lshlrev_b32_e32 v254, 16, v255
	v_and_b32_e32 v255, 0xffff0000, v255
	v_pk_add_f32 v[218:219], v[218:219], v[216:217]
	v_pk_add_f32 v[220:221], v[220:221], v[254:255]
	ds_read_b128 v[252:255], v246 offset:3488
	v_fma_f32 v106, v159, v106, -v98
	v_fma_f32 v107, v159, v107, -v99
	v_fma_f32 v108, v159, v108, -v100
	v_fma_f32 v109, v159, v109, -v101
	v_fma_f32 v218, v159, v218, -v102
	v_fma_f32 v219, v159, v219, -v103
	v_fma_f32 v220, v159, v220, -v104
	v_fma_f32 v221, v159, v221, -v105
	v_cvt_pk_bf16_f32 v106, v106, v107
	v_cvt_pk_bf16_f32 v107, v108, v109
	v_cvt_pk_bf16_f32 v108, v218, v219
	v_cvt_pk_bf16_f32 v109, v220, v221
	s_and_saveexec_b64 s[28:29], s[6:7]
	s_cbranch_execz .Lpu2_6
	global_store_dwordx4 v[190:191], v[98:101], off offset:384
	global_store_dwordx4 v[190:191], v[102:105], off offset:400

.LBB0_403:
	s_or_b64 exec, exec, s[2:3]
	s_waitcnt lgkmcnt(0)
	global_load_dwordx4 v[82:85], v[110:111], off offset:512
	global_load_dwordx4 v[86:89], v[134:135], off offset:512
	global_load_dwordx4 v[90:93], v[136:137], off offset:512
	global_load_dwordx4 v[94:97], v[138:139], off offset:512
	global_load_dwordx4 v[222:225], v[110:111], off offset:1024
	global_load_dwordx4 v[226:229], v[134:135], off offset:1024
	global_load_dwordx4 v[230:233], v[136:137], off offset:1024
	global_load_dwordx4 v[234:237], v[138:139], off offset:1024
	v_lshl_add_u32 v246, v197, 1, v214
	ds_read_b128 v[238:241], v246 offset:4080
	ds_read_b128 v[242:245], v246 offset:3808
	ds_read_b128 v[248:251], v246 offset:4112
	ds_read_b128 v[252:255], v246 offset:3840
	s_ashr_i32 s2, s30, 6
	v_or_b32_e32 v2, s28, v1
	s_mul_i32 s2, s2, 15
	v_cmp_eq_u32_e32 vcc, 0, v2
	v_cmp_lt_u32_e64 s[6:7], s41, v2
	s_ashr_i32 s3, s2, 31
	v_add_u32_e32 v2, 0xfffff80f, v2
	v_mov_b32_e32 v3, v155
	v_lshl_add_u64 v[2:3], v[2:3], 0, s[2:3]
	v_lshlrev_b64 v[2:3], 11, v[2:3]
	v_lshl_add_u64 v[184:185], v[140:141], 0, v[2:3]
	v_mov_b64_e32 v[2:3], 0
	v_mov_b64_e32 v[4:5], 0
	v_mov_b64_e32 v[6:7], 0
	v_mov_b64_e32 v[8:9], 0
	v_mov_b64_e32 v[10:11], 0
	v_mov_b64_e32 v[12:13], 0
	v_mov_b64_e32 v[14:15], 0
	v_mov_b64_e32 v[16:17], 0
	v_mov_b64_e32 v[18:19], 0
	v_mov_b64_e32 v[20:21], 0
	v_mov_b64_e32 v[22:23], 0
	v_mov_b64_e32 v[24:25], 0
	v_mov_b64_e32 v[26:27], 0
	v_mov_b64_e32 v[28:29], 0
	v_mov_b64_e32 v[30:31], 0
	v_mov_b64_e32 v[32:33], 0
	v_mov_b64_e32 v[34:35], 0
	v_mov_b64_e32 v[36:37], 0
	v_mov_b64_e32 v[38:39], 0
	v_mov_b64_e32 v[40:41], 0
	v_mov_b64_e32 v[42:43], 0
	v_mov_b64_e32 v[44:45], 0
	v_mov_b64_e32 v[46:47], 0
	v_mov_b64_e32 v[48:49], 0
	v_mov_b64_e32 v[50:51], 0
	v_mov_b64_e32 v[52:53], 0
	v_mov_b64_e32 v[54:55], 0
	v_mov_b64_e32 v[56:57], 0
	v_mov_b64_e32 v[58:59], 0
	v_mov_b64_e32 v[60:61], 0
	v_mov_b64_e32 v[62:63], 0
	v_mov_b64_e32 v[64:65], 0
	s_mov_b32 s28, 0
	v_cndmask_b32_e64 v159, 0.5, 1.0, vcc
	s_mov_b64 s[2:3], 0
	s_waitcnt lgkmcnt(3)
	v_lshlrev_b32_e32 v98, 16, v238
	v_and_b32_e32 v99, 0xffff0000, v238
	v_lshlrev_b32_e32 v100, 16, v239
	v_and_b32_e32 v101, 0xffff0000, v239
	v_lshlrev_b32_e32 v102, 16, v240
	v_and_b32_e32 v103, 0xffff0000, v240
	v_lshlrev_b32_e32 v104, 16, v241
	v_and_b32_e32 v105, 0xffff0000, v241
	ds_read_b128 v[238:241], v246 offset:4144
	s_waitcnt lgkmcnt(3)
	v_lshlrev_b32_e32 v216, 16, v242
	v_and_b32_e32 v217, 0xffff0000, v242
	v_lshlrev_b32_e32 v242, 16, v243
	v_and_b32_e32 v243, 0xffff0000, v243
	v_pk_add_f32 v[106:107], v[98:99], v[216:217]
	v_pk_add_f32 v[108:109], v[100:101], v[242:243]
	v_lshlrev_b32_e32 v216, 16, v244
	v_and_b32_e32 v217, 0xffff0000, v244
	v_lshlrev_b32_e32 v244, 16, v245
	v_and_b32_e32 v245, 0xffff0000, v245
	v_pk_add_f32 v[218:219], v[102:103], v[216:217]
	v_pk_add_f32 v[220:221], v[104:105], v[244:245]
	ds_read_b128 v[242:245], v246 offset:3872
	v_fma_f32 v106, v159, v106, -v98
	v_fma_f32 v107, v159, v107, -v99
	v_fma_f32 v108, v159, v108, -v100
	v_fma_f32 v109, v159, v109, -v101
	v_fma_f32 v218, v159, v218, -v102
	v_fma_f32 v219, v159, v219, -v103
	v_fma_f32 v220, v159, v220, -v104
	v_fma_f32 v221, v159, v221, -v105
	v_cvt_pk_bf16_f32 v106, v106, v107
	v_cvt_pk_bf16_f32 v107, v108, v109
	v_cvt_pk_bf16_f32 v108, v218, v219
	v_cvt_pk_bf16_f32 v109, v220, v221
	s_and_saveexec_b64 s[10:11], s[6:7]
	s_cbranch_execz .Lpu3_0
	global_store_dwordx4 v[184:185], v[98:101], off offset:0
	global_store_dwordx4 v[184:185], v[102:105], off offset:16
.Lpu3_0:
	s_or_b64 exec, exec, s[10:11]
	s_waitcnt vmcnt(8)
	v_mfma_f32_32x32x16_bf16 v[2:17], v[106:109], v[70:73], v[2:17]
	v_mfma_f32_32x32x16_bf16 v[18:33], v[106:109], v[74:77], v[18:33]
	v_mfma_f32_32x32x16_bf16 v[34:49], v[106:109], v[78:81], v[34:49]
	v_mfma_f32_32x32x16_bf16 v[50:65], v[106:109], v[66:69], v[50:65]
	global_load_dwordx4 v[70:73], v[110:111], off offset:1536
	global_load_dwordx4 v[74:77], v[134:135], off offset:1536
	global_load_dwordx4 v[78:81], v[136:137], off offset:1536
	global_load_dwordx4 v[66:69], v[138:139], off offset:1536
	s_waitcnt lgkmcnt(3)
	v_lshlrev_b32_e32 v98, 16, v248
	v_and_b32_e32 v99, 0xffff0000, v248
	v_lshlrev_b32_e32 v100, 16, v249
	v_and_b32_e32 v101, 0xffff0000, v249
	v_lshlrev_b32_e32 v102, 16, v250
	v_and_b32_e32 v103, 0xffff0000, v250
	v_lshlrev_b32_e32 v104, 16, v251
	v_and_b32_e32 v105, 0xffff0000, v251
	ds_read_b128 v[248:251], v246 offset:4176
	s_waitcnt lgkmcnt(3)
	v_lshlrev_b32_e32 v216, 16, v252
	v_and_b32_e32 v217, 0xffff0000, v252
	v_lshlrev_b32_e32 v252, 16, v253
	v_and_b32_e32 v253, 0xffff0000, v253
	v_pk_add_f32 v[106:107], v[98:99], v[216:217]
	v_pk_add_f32 v[108:109], v[100:101], v[252:253]
	v_lshlrev_b32_e32 v216, 16, v254
	v_and_b32_e32 v217, 0xffff0000, v254
	v_lshlrev_b32_e32 v254, 16, v255
	v_and_b32_e32 v255, 0xffff0000, v255
	v_pk_add_f32 v[218:219], v[102:103], v[216:217]
	v_pk_add_f32 v[220:221], v[104:105], v[254:255]
	ds_read_b128 v[252:255], v246 offset:3904
	v_fma_f32 v106, v159, v106, -v98
	v_fma_f32 v107, v159, v107, -v99
	v_fma_f32 v108, v159, v108, -v100
	v_fma_f32 v109, v159, v109, -v101
	v_fma_f32 v218, v159, v218, -v102
	v_fma_f32 v219, v159, v219, -v103
	v_fma_f32 v220, v159, v220, -v104
	v_fma_f32 v221, v159, v221, -v105
	v_cvt_pk_bf16_f32 v106, v106, v107
	v_cvt_pk_bf16_f32 v107, v108, v109
	v_cvt_pk_bf16_f32 v108, v218, v219
	v_cvt_pk_bf16_f32 v109, v220, v221
	s_and_saveexec_b64 s[10:11], s[6:7]
	s_cbranch_execz .Lpu3_1
	global_store_dwordx4 v[184:185], v[98:101], off offset:64
	global_store_dwordx4 v[184:185], v[102:105], off offset:80
.Lpu3_1:
	s_or_b64 exec, exec, s[10:11]
	s_waitcnt vmcnt(8)
	v_mfma_f32_32x32x16_bf16 v[2:17], v[106:109], v[82:85], v[2:17]
	v_mfma_f32_32x32x16_bf16 v[18:33], v[106:109], v[86:89], v[18:33]
	v_mfma_f32_32x32x16_bf16 v[34:49], v[106:109], v[90:93], v[34:49]
	v_mfma_f32_32x32x16_bf16 v[50:65], v[106:109], v[94:97], v[50:65]
	global_load_dwordx4 v[82:85], v[110:111], off offset:2048
	global_load_dwordx4 v[86:89], v[134:135], off offset:2048
	global_load_dwordx4 v[90:93], v[136:137], off offset:2048
	global_load_dwordx4 v[94:97], v[138:139], off offset:2048
	s_waitcnt lgkmcnt(3)
	v_lshlrev_b32_e32 v98, 16, v238
	v_and_b32_e32 v99, 0xffff0000, v238
	v_lshlrev_b32_e32 v100, 16, v239
	v_and_b32_e32 v101, 0xffff0000, v239
	v_lshlrev_b32_e32 v102, 16, v240
	v_and_b32_e32 v103, 0xffff0000, v240
	v_lshlrev_b32_e32 v104, 16, v241
	v_and_b32_e32 v105, 0xffff0000, v241
	ds_read_b128 v[238:241], v246 offset:4208
	s_waitcnt lgkmcnt(3)
	v_lshlrev_b32_e32 v216, 16, v242
	v_and_b32_e32 v217, 0xffff0000, v242
	v_lshlrev_b32_e32 v242, 16, v243
	v_and_b32_e32 v243, 0xffff0000, v243
	v_pk_add_f32 v[106:107], v[98:99], v[216:217]
	v_pk_add_f32 v[108:109], v[100:101], v[242:243]
	v_lshlrev_b32_e32 v216, 16, v244
	v_and_b32_e32 v217, 0xffff0000, v244
	v_lshlrev_b32_e32 v244, 16, v245
	v_and_b32_e32 v245, 0xffff0000, v245
	v_pk_add_f32 v[218:219], v[102:103], v[216:217]
	v_pk_add_f32 v[220:221], v[104:105], v[244:245]
	ds_read_b128 v[242:245], v246 offset:3936
	v_fma_f32 v106, v159, v106, -v98
	v_fma_f32 v107, v159, v107, -v99
	v_fma_f32 v108, v159, v108, -v100
	v_fma_f32 v109, v159, v109, -v101
	v_fma_f32 v218, v159, v218, -v102
	v_fma_f32 v219, v159, v219, -v103
	v_fma_f32 v220, v159, v220, -v104
	v_fma_f32 v221, v159, v221, -v105
	v_cvt_pk_bf16_f32 v106, v106, v107
	v_cvt_pk_bf16_f32 v107, v108, v109
	v_cvt_pk_bf16_f32 v108, v218, v219
	v_cvt_pk_bf16_f32 v109, v220, v221
	s_and_saveexec_b64 s[10:11], s[6:7]
	s_cbranch_execz .Lpu3_2
	global_store_dwordx4 v[184:185], v[98:101], off offset:128
	global_store_dwordx4 v[184:185], v[102:105], off offset:144
.Lpu3_2:
	s_or_b64 exec, exec, s[10:11]
	s_waitcnt vmcnt(8)
	v_mfma_f32_32x32x16_bf16 v[2:17], v[106:109], v[222:225], v[2:17]
	v_mfma_f32_32x32x16_bf16 v[18:33], v[106:109], v[226:229], v[18:33]
	v_mfma_f32_32x32x16_bf16 v[34:49], v[106:109], v[230:233], v[34:49]
	v_mfma_f32_32x32x16_bf16 v[50:65], v[106:109], v[234:237], v[50:65]
	global_load_dwordx4 v[222:225], v[110:111], off offset:2560
	global_load_dwordx4 v[226:229], v[134:135], off offset:2560
	global_load_dwordx4 v[230:233], v[136:137], off offset:2560
	global_load_dwordx4 v[234:237], v[138:139], off offset:2560
	s_waitcnt lgkmcnt(3)
	v_lshlrev_b32_e32 v98, 16, v248
	v_and_b32_e32 v99, 0xffff0000, v248
	v_lshlrev_b32_e32 v100, 16, v249
	v_and_b32_e32 v101, 0xffff0000, v249
	v_lshlrev_b32_e32 v102, 16, v250
	v_and_b32_e32 v103, 0xffff0000, v250
	v_lshlrev_b32_e32 v104, 16, v251
	v_and_b32_e32 v105, 0xffff0000, v251
	ds_read_b128 v[248:251], v246 offset:4240
	s_waitcnt lgkmcnt(3)
	v_lshlrev_b32_e32 v216, 16, v252
	v_and_b32_e32 v217, 0xffff0000, v252
	v_lshlrev_b32_e32 v252, 16, v253
	v_and_b32_e32 v253, 0xffff0000, v253
	v_pk_add_f32 v[106:107], v[98:99], v[216:217]
	v_pk_add_f32 v[108:109], v[100:101], v[252:253]
	v_lshlrev_b32_e32 v216, 16, v254
	v_and_b32_e32 v217, 0xffff0000, v254
	v_lshlrev_b32_e32 v254, 16, v255
	v_and_b32_e32 v255, 0xffff0000, v255
	v_pk_add_f32 v[218:219], v[102:103], v[216:217]
	v_pk_add_f32 v[220:221], v[104:105], v[254:255]
	ds_read_b128 v[252:255], v246 offset:3968
	v_fma_f32 v106, v159, v106, -v98
	v_fma_f32 v107, v159, v107, -v99
	v_fma_f32 v108, v159, v108, -v100
	v_fma_f32 v109, v159, v109, -v101
	v_fma_f32 v218, v159, v218, -v102
	v_fma_f32 v219, v159, v219, -v103
	v_fma_f32 v220, v159, v220, -v104
	v_fma_f32 v221, v159, v221, -v105
	v_cvt_pk_bf16_f32 v106, v106, v107
	v_cvt_pk_bf16_f32 v107, v108, v109
	v_cvt_pk_bf16_f32 v108, v218, v219
	v_cvt_pk_bf16_f32 v109, v220, v221
	s_and_saveexec_b64 s[10:11], s[6:7]
	s_cbranch_execz .Lpu3_3
	global_store_dwordx4 v[184:185], v[98:101], off offset:192
	global_store_dwordx4 v[184:185], v[102:105], off offset:208
.Lpu3_3:
	s_or_b64 exec, exec, s[10:11]
	s_waitcnt vmcnt(8)
	v_mfma_f32_32x32x16_bf16 v[2:17], v[106:109], v[70:73], v[2:17]
	v_mfma_f32_32x32x16_bf16 v[18:33], v[106:109], v[74:77], v[18:33]
	v_mfma_f32_32x32x16_bf16 v[34:49], v[106:109], v[78:81], v[34:49]
	v_mfma_f32_32x32x16_bf16 v[50:65], v[106:109], v[66:69], v[50:65]
	global_load_dwordx4 v[70:73], v[110:111], off offset:3072
	global_load_dwordx4 v[74:77], v[134:135], off offset:3072
	global_load_dwordx4 v[78:81], v[136:137], off offset:3072
	global_load_dwordx4 v[66:69], v[138:139], off offset:3072
	s_waitcnt lgkmcnt(3)
	v_lshlrev_b32_e32 v98, 16, v238
	v_and_b32_e32 v99, 0xffff0000, v238
	v_lshlrev_b32_e32 v100, 16, v239
	v_and_b32_e32 v101, 0xffff0000, v239
	v_lshlrev_b32_e32 v102, 16, v240
	v_and_b32_e32 v103, 0xffff0000, v240
	v_lshlrev_b32_e32 v104, 16, v241
	v_and_b32_e32 v105, 0xffff0000, v241
	ds_read_b128 v[238:241], v246 offset:4272
	s_waitcnt lgkmcnt(3)
	v_lshlrev_b32_e32 v216, 16, v242
	v_and_b32_e32 v217, 0xffff0000, v242
	v_lshlrev_b32_e32 v242, 16, v243
	v_and_b32_e32 v243, 0xffff0000, v243
	v_pk_add_f32 v[106:107], v[98:99], v[216:217]
	v_pk_add_f32 v[108:109], v[100:101], v[242:243]
	v_lshlrev_b32_e32 v216, 16, v244
	v_and_b32_e32 v217, 0xffff0000, v244
	v_lshlrev_b32_e32 v244, 16, v245
	v_and_b32_e32 v245, 0xffff0000, v245
	v_pk_add_f32 v[218:219], v[102:103], v[216:217]
	v_pk_add_f32 v[220:221], v[104:105], v[244:245]
	ds_read_b128 v[242:245], v246 offset:4000
	v_fma_f32 v106, v159, v106, -v98
	v_fma_f32 v107, v159, v107, -v99
	v_fma_f32 v108, v159, v108, -v100
	v_fma_f32 v109, v159, v109, -v101
	v_fma_f32 v218, v159, v218, -v102
	v_fma_f32 v219, v159, v219, -v103
	v_fma_f32 v220, v159, v220, -v104
	v_fma_f32 v221, v159, v221, -v105
	v_cvt_pk_bf16_f32 v106, v106, v107
	v_cvt_pk_bf16_f32 v107, v108, v109
	v_cvt_pk_bf16_f32 v108, v218, v219
	v_cvt_pk_bf16_f32 v109, v220, v221
	s_and_saveexec_b64 s[10:11], s[6:7]
	s_cbranch_execz .Lpu3_4
	global_store_dwordx4 v[184:185], v[98:101], off offset:256
	global_store_dwordx4 v[184:185], v[102:105], off offset:272
.Lpu3_4:
	s_or_b64 exec, exec, s[10:11]
	s_waitcnt vmcnt(8)
	v_mfma_f32_32x32x16_bf16 v[2:17], v[106:109], v[82:85], v[2:17]
	v_mfma_f32_32x32x16_bf16 v[18:33], v[106:109], v[86:89], v[18:33]
	v_mfma_f32_32x32x16_bf16 v[34:49], v[106:109], v[90:93], v[34:49]
	v_mfma_f32_32x32x16_bf16 v[50:65], v[106:109], v[94:97], v[50:65]
	global_load_dwordx4 v[82:85], v[110:111], off offset:3584
	global_load_dwordx4 v[86:89], v[134:135], off offset:3584
	global_load_dwordx4 v[90:93], v[136:137], off offset:3584
	global_load_dwordx4 v[94:97], v[138:139], off offset:3584
	s_waitcnt lgkmcnt(3)
	v_lshlrev_b32_e32 v98, 16, v248
	v_and_b32_e32 v99, 0xffff0000, v248
	v_lshlrev_b32_e32 v100, 16, v249
	v_and_b32_e32 v101, 0xffff0000, v249
	v_lshlrev_b32_e32 v102, 16, v250
	v_and_b32_e32 v103, 0xffff0000, v250
	v_lshlrev_b32_e32 v104, 16, v251
	v_and_b32_e32 v105, 0xffff0000, v251
	ds_read_b128 v[248:251], v246 offset:4304
	s_waitcnt lgkmcnt(3)
	v_lshlrev_b32_e32 v216, 16, v252
	v_and_b32_e32 v217, 0xffff0000, v252
	v_lshlrev_b32_e32 v252, 16, v253
	v_and_b32_e32 v253, 0xffff0000, v253
	v_pk_add_f32 v[106:107], v[98:99], v[216:217]
	v_pk_add_f32 v[108:109], v[100:101], v[252:253]
	v_lshlrev_b32_e32 v216, 16, v254
	v_and_b32_e32 v217, 0xffff0000, v254
	v_lshlrev_b32_e32 v254, 16, v255
	v_and_b32_e32 v255, 0xffff0000, v255
	v_pk_add_f32 v[218:219], v[102:103], v[216:217]
	v_pk_add_f32 v[220:221], v[104:105], v[254:255]
	ds_read_b128 v[252:255], v246 offset:4032
	v_fma_f32 v106, v159, v106, -v98
	v_fma_f32 v107, v159, v107, -v99
	v_fma_f32 v108, v159, v108, -v100
	v_fma_f32 v109, v159, v109, -v101
	v_fma_f32 v218, v159, v218, -v102
	v_fma_f32 v219, v159, v219, -v103
	v_fma_f32 v220, v159, v220, -v104
	v_fma_f32 v221, v159, v221, -v105
	v_cvt_pk_bf16_f32 v106, v106, v107
	v_cvt_pk_bf16_f32 v107, v108, v109
	v_cvt_pk_bf16_f32 v108, v218, v219
	v_cvt_pk_bf16_f32 v109, v220, v221
	s_and_saveexec_b64 s[10:11], s[6:7]
	s_cbranch_execz .Lpu3_5
	global_store_dwordx4 v[184:185], v[98:101], off offset:320
	global_store_dwordx4 v[184:185], v[102:105], off offset:336
